# static s_setprio 1 for waves 4-7 at kernel entry, all per-segment setprio flips deleted
# speedup vs baseline: 1.0033x; 1.0029x over previous
; #define LAS __attribute__((address_space(3)))
; __device__ __forceinline__ unsigned xb_add(unsigned* p, unsigned v) { return __hip_atomic_fetch_add(p, v, __ATOMIC_RELAXED, __HIP_MEMORY_SCOPE_AGENT); }
; __device__ __forceinline__ unsigned xb_xcc_id() { return (unsigned)__builtin_amdgcn_s_getreg((3 << 11) | 20) & 0xFu; }
; __device__ __forceinline__ XcdBarrier xcd_barrier_post(unsigned* bar, volatile LAS unsigned* st) {
;     XcdBarrier b; b.bar = bar; b.x = xb_xcc_id(); b.st = st;
;     if (threadIdx.x == 0) (void)xb_add(&bar[XB_XCNT(b.x)], 1u);
;     return b;
; __global__ void __launch_bounds__(NTHR, 2) mega_fwd(Params p) {
;     extern __shared__ __attribute__((aligned(16))) unsigned char lds_raw[];
;     LAS unsigned char* lds = (LAS unsigned char*)lds_raw;
;     const int G = gridDim.x, bid = blockIdx.x;
;     unsigned char* ws = p.ws;
;     bf16_t* W13 = (bf16_t*)(ws + WS_W13); bf16_t* W2 = (bf16_t*)(ws + WS_W2); bf16_t* WA = (bf16_t*)(ws + WS_WA); bf16_t* WB = (bf16_t*)(ws + WS_WB);
;     bf16_t* POOLW = (bf16_t*)(ws + WS_POOLW); float* ROPE = (float*)(ws + WS_ROPE); bf16_t* XN = (bf16_t*)(ws + WS_XN); bf16_t* BIG = (bf16_t*)(ws + WS_BIG);
;     bf16_t* OG = (bf16_t*)(ws + WS_OG); bf16_t* POOLED = (bf16_t*)(ws + WS_OG); float* LSE = (float*)(ws + WS_LSE);
;     float* H = p.out;
;     const int lo = p.ph_lo, hi = p.ph_hi;
;     volatile LAS unsigned* bst = (volatile LAS unsigned*)(lds + ATT_LDS);
;     if (threadIdx.x < 4) bst[threadIdx.x] = 0u;
;     __syncthreads();
;     XcdBarrier xbar; xbar.bar = (unsigned*)(ws + WS_BAR); xbar.x = 0; xbar.st = bst;
;     if (hi - lo > 1) xbar = xcd_barrier_post((unsigned*)(ws + WS_BAR), bst);
_Z8mega_fwd6Params:
	v_readfirstlane_b32 s99, v0
	s_nop 3
	s_and_b32 s99, s99, 0x3ff
	s_lshr_b32 s99, s99, 6
	s_cmp_ge_u32 s99, 4
	s_cbranch_scc0 .Lprio_done
	s_setprio 1
.Lprio_done:
	s_load_dword s78, s[0:1], 0xc8
	s_load_dwordx4 s[80:83], s[0:1], 0x70
	s_load_dwordx2 s[84:85], s[0:1], 0xc0
	s_mov_b32 s79, s2
	s_add_u32 s2, s0, 0xc8
	v_writelane_b32 v252, s0, 0
	s_addc_u32 s3, s1, 0
	v_and_b32_e32 v224, 0x3ff, v0
	v_writelane_b32 v252, s1, 1
	v_writelane_b32 v252, s2, 2
	v_cmp_gt_u32_e32 vcc, 4, v224
	s_nop 0
	v_writelane_b32 v252, s3, 3
	s_and_saveexec_b64 s[0:1], vcc
	v_lshl_add_u32 v1, v224, 2, 0
	v_add_u32_e32 v1, 0x22000, v1
	v_mov_b32_e32 v2, 0
	ds_write_b32 v1, v2
	s_or_b64 exec, exec, s[0:1]
	s_waitcnt lgkmcnt(0)
	s_add_u32 s0, s82, 0x2a9f0000
	s_addc_u32 s1, s83, 0
	v_writelane_b32 v252, s0, 4
	v_cmp_eq_u32_e32 vcc, 0, v224
	s_nop 0
	v_writelane_b32 v252, s1, 5
	s_sub_i32 s0, s85, s84
	s_mov_b32 s1, 0
	s_cmp_lt_i32 s0, 2
	s_barrier
	v_writelane_b32 v252, s1, 6
	s_cbranch_scc1 .LBB0_7
	s_getreg_b32 s0, hwreg(HW_REG_XCC_ID, 0, 4)
	s_and_b32 s0, s0, 15
	v_writelane_b32 v252, s0, 6
	s_and_saveexec_b64 s[0:1], vcc
	s_cbranch_execz .LBB0_6
	s_mov_b64 s[2:3], exec
	v_mbcnt_lo_u32_b32 v1, s2, 0
	v_mbcnt_hi_u32_b32 v1, s3, v1
	v_cmp_eq_u32_e32 vcc, 0, v1
	s_and_b64 s[4:5], exec, vcc
	s_mov_b64 exec, s[4:5]
	s_cbranch_execz .LBB0_6
	v_readlane_b32 s4, v252, 6
	s_bcnt1_i32_b64 s2, s[2:3]
	s_lshl_b32 s4, s4, 8
	v_mov_b32_e32 v2, s2
	v_readlane_b32 s2, v252, 4
	v_mov_b32_e32 v1, s4
	v_readlane_b32 s3, v252, 5
	s_nop 4
	global_atomic_add v1, v2, s[2:3] offset:1024

; #define PG8_STAGE(bufoff, gbase, voff) do { _Pragma("unroll") for (int _i = 0; _i < 2; ++_i) \
;         __builtin_amdgcn_global_load_lds((const unsigned*)((const char*)(gbase) + (voff)[_i]), (LAS unsigned*)(lds + (bufoff) + ldsw + _i * 8192), 16, 0, 0); } while (0)
; #define PG8_LDA(dst, b, h) do { _Pragma("unroll") for (int m = 0; m < 4; ++m) _Pragma("unroll") for (int k = 0; k < 2; ++k) dst[m][k] = *(const LAS bf16x8*)(lds + PG8_SA(b, h) + aoff + m * 2048 + k * 1024); } while (0)
; #define PG8_LDB(dst, b, h) do { _Pragma("unroll") for (int n = 0; n < 2; ++n) _Pragma("unroll") for (int k = 0; k < 2; ++k) dst[n][k] = *(const LAS bf16x8*)(lds + PG8_SB(b, h) + boff + n * 2048 + k * 1024); } while (0)
; #define PG8_MMA(ai, bj, At, Bt) do { __builtin_amdgcn_s_setprio(1); _Pragma("unroll") for (int m = 0; m < 4; ++m) _Pragma("unroll") for (int n = 0; n < 2; ++n) _Pragma("unroll") for (int k = 0; k < 2; ++k) \
;         acc[ai][bj][m][n] = __builtin_amdgcn_mfma_f32_16x16x32_bf16(Bt[n][k], At[m][k], acc[ai][bj][m][n], 0, 0, 0); __builtin_amdgcn_s_setprio(0); } while (0)
; #define PG8_WAIT_V(n) asm volatile("s_waitcnt vmcnt(" #n ")" ::: "memory")
; #define PG8_WAIT_L(n) asm volatile("s_waitcnt lgkmcnt(" #n ")" ::: "memory")
; #define PG8_BAR __builtin_amdgcn_s_barrier()
; #define PG8_SCHED __builtin_amdgcn_sched_barrier(0)
; template <class Epi>
; __device__ __forceinline__ void gemm_phase(LAS unsigned char* lds, const Gemm g, const StaticOrder S, const Epi E) {
;     ...
;             const char* a1 = cA + (long)(t + 1) * ksc;
;             const char* a2 = last ? nA : cA + (long)(t + 2) * ksc; const char* b2 = last ? nB : cB + (long)(t + 2) * ksc;
;             const long ks3 = last ? ksn : ksc;
;             const char* a3 = a2 + ks3; const char* b3 = b2 + ks3;
;             PG8_LDB(B0, 0, 0); PG8_LDB(B1, 0, 1); PG8_SCHED; PG8_LDA(At, 0, 0); PG8_STAGE(PG8_SA(1, 1), a1 + hstepA, voffA);
;             PG8_WAIT_V(8); PG8_WAIT_L(0); PG8_BAR; PG8_MMA(0, 0, At, B0); PG8_MMA(0, 1, At, B1); PG8_BAR; PG8_SCHED;
;             PG8_LDA(At, 0, 1); PG8_STAGE(PG8_SB(0, 0), b2, voffB); PG8_STAGE(PG8_SB(0, 1), b2 + hstepB, voffB); PG8_STAGE(PG8_SA(0, 0), a2, voffA);
;             PG8_WAIT_V(8); PG8_WAIT_L(0); PG8_BAR; PG8_MMA(1, 0, At, B0); PG8_MMA(1, 1, At, B1); PG8_BAR; PG8_SCHED;
.LBB0_121:
	ds_read_b128 v[148:151], v254
	ds_read_b128 v[152:155], v254 offset:1024
	ds_read_b128 v[156:159], v254 offset:2048
	ds_read_b128 v[160:163], v254 offset:3072
	ds_read_b128 v[164:167], v254 offset:16384
	ds_read_b128 v[168:171], v254 offset:17408
	ds_read_b128 v[172:175], v254 offset:18432
	ds_read_b128 v[176:179], v254 offset:19456
	s_or_b32 s13, s62, 1
	s_mul_i32 s46, s27, s13
	s_mul_hi_u32 s47, s26, s13
	s_add_i32 s47, s47, s46
	s_mul_i32 s13, s26, s13
	s_add_u32 s13, s24, s13
	s_addc_u32 s63, s25, s47
	s_add_u32 s46, s44, s42
	s_addc_u32 s47, s45, s43
	s_add_u32 s64, s13, 0x80000
	s_addc_u32 s65, s63, 0
	s_add_i32 m0, s21, 0xc000
	ds_read_b128 v[180:183], v145
	ds_read_b128 v[184:187], v145 offset:1024
	ds_read_b128 v[188:191], v145 offset:2048
	ds_read_b128 v[192:195], v145 offset:3072
	ds_read_b128 v[196:199], v145 offset:4096
	ds_read_b128 v[200:203], v145 offset:5120
	ds_read_b128 v[204:207], v145 offset:6144
	ds_read_b128 v[208:211], v145 offset:7168
	global_load_lds_dwordx4 v134, s[64:65]
	s_add_i32 m0, s21, 0xe000
	s_nop 0
	global_load_lds_dwordx4 v130, s[64:65]
	s_waitcnt vmcnt(8)
	s_waitcnt lgkmcnt(0)
	s_barrier
	s_waitcnt lgkmcnt(0)
	v_mfma_f32_16x16x32_bf16 v[116:119], v[148:151], v[180:183], v[116:119]
	v_mfma_f32_16x16x32_bf16 v[112:115], v[156:159], v[180:183], v[112:115]
	v_mfma_f32_16x16x32_bf16 v[108:111], v[148:151], v[188:191], v[108:111]
	v_mfma_f32_16x16x32_bf16 v[104:107], v[156:159], v[188:191], v[104:107]
	v_mfma_f32_16x16x32_bf16 v[92:95], v[148:151], v[196:199], v[92:95]
	v_mfma_f32_16x16x32_bf16 v[88:91], v[156:159], v[196:199], v[88:91]
	v_mfma_f32_16x16x32_bf16 v[76:79], v[148:151], v[204:207], v[76:79]
	v_mfma_f32_16x16x32_bf16 v[72:75], v[156:159], v[204:207], v[72:75]
	v_mfma_f32_16x16x32_bf16 v[116:119], v[152:155], v[184:187], v[116:119]
	v_mfma_f32_16x16x32_bf16 v[112:115], v[160:163], v[184:187], v[112:115]
	v_mfma_f32_16x16x32_bf16 v[108:111], v[152:155], v[192:195], v[108:111]
	v_mfma_f32_16x16x32_bf16 v[104:107], v[160:163], v[192:195], v[104:107]
	v_mfma_f32_16x16x32_bf16 v[92:95], v[152:155], v[200:203], v[92:95]
	v_mfma_f32_16x16x32_bf16 v[88:91], v[160:163], v[200:203], v[88:91]
	v_mfma_f32_16x16x32_bf16 v[76:79], v[152:155], v[208:211], v[76:79]
	v_mfma_f32_16x16x32_bf16 v[72:75], v[160:163], v[208:211], v[72:75]
	v_mfma_f32_16x16x32_bf16 v[124:127], v[164:167], v[180:183], v[124:127]
	v_mfma_f32_16x16x32_bf16 v[120:123], v[172:175], v[180:183], v[120:123]
	v_mfma_f32_16x16x32_bf16 v[100:103], v[164:167], v[188:191], v[100:103]
	v_mfma_f32_16x16x32_bf16 v[96:99], v[172:175], v[188:191], v[96:99]
	v_mfma_f32_16x16x32_bf16 v[84:87], v[164:167], v[196:199], v[84:87]
	v_mfma_f32_16x16x32_bf16 v[80:83], v[172:175], v[196:199], v[80:83]
	v_mfma_f32_16x16x32_bf16 v[68:71], v[164:167], v[204:207], v[68:71]
	v_mfma_f32_16x16x32_bf16 v[64:67], v[172:175], v[204:207], v[64:67]
	v_mfma_f32_16x16x32_bf16 v[124:127], v[168:171], v[184:187], v[124:127]
	v_mfma_f32_16x16x32_bf16 v[120:123], v[176:179], v[184:187], v[120:123]
	v_mfma_f32_16x16x32_bf16 v[100:103], v[168:171], v[192:195], v[100:103]
	v_mfma_f32_16x16x32_bf16 v[96:99], v[176:179], v[192:195], v[96:99]
	v_mfma_f32_16x16x32_bf16 v[84:87], v[168:171], v[200:203], v[84:87]
	v_mfma_f32_16x16x32_bf16 v[80:83], v[176:179], v[200:203], v[80:83]
	v_mfma_f32_16x16x32_bf16 v[68:71], v[168:171], v[208:211], v[68:71]
	v_mfma_f32_16x16x32_bf16 v[64:67], v[176:179], v[208:211], v[64:67]
	s_barrier
	s_add_i32 s13, s57, s33
	s_mov_b32 m0, s13
	ds_read_b128 v[180:183], v145 offset:16384
	ds_read_b128 v[184:187], v145 offset:17408
	ds_read_b128 v[188:191], v145 offset:18432
	ds_read_b128 v[192:195], v145 offset:19456
	ds_read_b128 v[196:199], v145 offset:20480
	ds_read_b128 v[200:203], v145 offset:21504
	ds_read_b128 v[204:207], v145 offset:22528
	ds_read_b128 v[208:211], v145 offset:23552
	global_load_lds_dwordx4 v132, s[40:41]
	s_add_i32 m0, s13, 0x2000
	s_add_u32 s64, s40, 0x80000
	s_addc_u32 s65, s41, 0
	s_add_i32 s13, s58, s33
	global_load_lds_dwordx4 v128, s[40:41]
	s_mov_b32 m0, s13
	s_nop 0
	global_load_lds_dwordx4 v132, s[64:65]
	s_add_i32 m0, s13, 0x2000
	s_nop 0
	global_load_lds_dwordx4 v128, s[64:65]
	s_mov_b32 m0, s21
	s_nop 0
	global_load_lds_dwordx4 v134, s[44:45]
	s_mov_b32 m0, s50
	s_nop 0
	global_load_lds_dwordx4 v130, s[44:45]
	s_waitcnt vmcnt(8)
	s_waitcnt lgkmcnt(0)
	s_barrier
	s_waitcnt lgkmcnt(0)
	v_mfma_f32_16x16x32_bf16 v[60:63], v[148:151], v[180:183], v[60:63]
	v_mfma_f32_16x16x32_bf16 v[56:59], v[156:159], v[180:183], v[56:59]
	v_mfma_f32_16x16x32_bf16 v[44:47], v[148:151], v[188:191], v[44:47]
	v_mfma_f32_16x16x32_bf16 v[40:43], v[156:159], v[188:191], v[40:43]
	v_mfma_f32_16x16x32_bf16 v[28:31], v[148:151], v[196:199], v[28:31]
	v_mfma_f32_16x16x32_bf16 v[24:27], v[156:159], v[196:199], v[24:27]
	v_mfma_f32_16x16x32_bf16 v[12:15], v[148:151], v[204:207], v[12:15]
	v_mfma_f32_16x16x32_bf16 v[8:11], v[156:159], v[204:207], v[8:11]
	v_mfma_f32_16x16x32_bf16 v[60:63], v[152:155], v[184:187], v[60:63]
	v_mfma_f32_16x16x32_bf16 v[56:59], v[160:163], v[184:187], v[56:59]
	v_mfma_f32_16x16x32_bf16 v[44:47], v[152:155], v[192:195], v[44:47]
	v_mfma_f32_16x16x32_bf16 v[40:43], v[160:163], v[192:195], v[40:43]
	v_mfma_f32_16x16x32_bf16 v[28:31], v[152:155], v[200:203], v[28:31]
	v_mfma_f32_16x16x32_bf16 v[24:27], v[160:163], v[200:203], v[24:27]
	v_mfma_f32_16x16x32_bf16 v[12:15], v[152:155], v[208:211], v[12:15]
	v_mfma_f32_16x16x32_bf16 v[8:11], v[160:163], v[208:211], v[8:11]
	v_mfma_f32_16x16x32_bf16 v[52:55], v[164:167], v[180:183], v[52:55]
	v_mfma_f32_16x16x32_bf16 v[48:51], v[172:175], v[180:183], v[48:51]
	v_mfma_f32_16x16x32_bf16 v[36:39], v[164:167], v[188:191], v[36:39]
	v_mfma_f32_16x16x32_bf16 v[32:35], v[172:175], v[188:191], v[32:35]
	v_mfma_f32_16x16x32_bf16 v[20:23], v[164:167], v[196:199], v[20:23]
	v_mfma_f32_16x16x32_bf16 v[16:19], v[172:175], v[196:199], v[16:19]
	v_mfma_f32_16x16x32_bf16 v[4:7], v[164:167], v[204:207], v[4:7]
	v_mfma_f32_16x16x32_bf16 v[0:3], v[172:175], v[204:207], v[0:3]
	v_mfma_f32_16x16x32_bf16 v[52:55], v[168:171], v[184:187], v[52:55]
	v_mfma_f32_16x16x32_bf16 v[48:51], v[176:179], v[184:187], v[48:51]
	v_mfma_f32_16x16x32_bf16 v[36:39], v[168:171], v[192:195], v[36:39]
	v_mfma_f32_16x16x32_bf16 v[32:35], v[176:179], v[192:195], v[32:35]
	v_mfma_f32_16x16x32_bf16 v[20:23], v[168:171], v[200:203], v[20:23]
	v_mfma_f32_16x16x32_bf16 v[16:19], v[176:179], v[200:203], v[16:19]
	v_mfma_f32_16x16x32_bf16 v[4:7], v[168:171], v[208:211], v[4:7]
	v_mfma_f32_16x16x32_bf16 v[0:3], v[176:179], v[208:211], v[0:3]
	s_barrier
; #define PG8_STAGE(bufoff, gbase, voff) do { _Pragma("unroll") for (int _i = 0; _i < 2; ++_i) \
;         __builtin_amdgcn_global_load_lds((const unsigned*)((const char*)(gbase) + (voff)[_i]), (LAS unsigned*)(lds + (bufoff) + ldsw + _i * 8192), 16, 0, 0); } while (0)
; #define PG8_LDA(dst, b, h) do { _Pragma("unroll") for (int m = 0; m < 4; ++m) _Pragma("unroll") for (int k = 0; k < 2; ++k) dst[m][k] = *(const LAS bf16x8*)(lds + PG8_SA(b, h) + aoff + m * 2048 + k * 1024); } while (0)
; #define PG8_LDB(dst, b, h) do { _Pragma("unroll") for (int n = 0; n < 2; ++n) _Pragma("unroll") for (int k = 0; k < 2; ++k) dst[n][k] = *(const LAS bf16x8*)(lds + PG8_SB(b, h) + boff + n * 2048 + k * 1024); } while (0)
; #define PG8_MMA(ai, bj, At, Bt) do { __builtin_amdgcn_s_setprio(1); _Pragma("unroll") for (int m = 0; m < 4; ++m) _Pragma("unroll") for (int n = 0; n < 2; ++n) _Pragma("unroll") for (int k = 0; k < 2; ++k) \
;         acc[ai][bj][m][n] = __builtin_amdgcn_mfma_f32_16x16x32_bf16(Bt[n][k], At[m][k], acc[ai][bj][m][n], 0, 0, 0); __builtin_amdgcn_s_setprio(0); } while (0)
; #define PG8_WAIT_V(n) asm volatile("s_waitcnt vmcnt(" #n ")" ::: "memory")
; #define PG8_WAIT_L(n) asm volatile("s_waitcnt lgkmcnt(" #n ")" ::: "memory")
; #define PG8_BAR __builtin_amdgcn_s_barrier()
; #define PG8_SCHED __builtin_amdgcn_sched_barrier(0)
; template <class Epi>
; __device__ __forceinline__ void gemm_phase(LAS unsigned char* lds, const Gemm g, const StaticOrder S, const Epi E) {
;     ...
;             PG8_LDB(B0, 1, 0); PG8_LDB(B1, 1, 1); PG8_SCHED; PG8_LDA(At, 1, 0); PG8_STAGE(PG8_SA(0, 1), a2 + hstepA, voffA);
;             PG8_WAIT_V(8); PG8_WAIT_L(0); PG8_BAR; PG8_MMA(0, 0, At, B0); PG8_MMA(0, 1, At, B1); PG8_BAR; PG8_SCHED;
;             PG8_LDA(At, 1, 1); PG8_STAGE(PG8_SB(1, 0), b3, voffB); PG8_STAGE(PG8_SB(1, 1), b3 + hstepB, voffB); PG8_STAGE(PG8_SA(1, 0), a3, voffA);
;             PG8_WAIT_V(8); PG8_WAIT_L(0); PG8_BAR; PG8_MMA(1, 0, At, B0); PG8_MMA(1, 1, At, B1); PG8_BAR; PG8_SCHED;
;         }
	s_add_i32 s13, 0, 0x18000
	s_add_i32 s63, 0, 0x1c000
	ds_read_b128 v[148:151], v254 offset:32768
	ds_read_b128 v[152:155], v254 offset:33792
	ds_read_b128 v[156:159], v254 offset:34816
	ds_read_b128 v[160:163], v254 offset:35840
	ds_read_b128 v[164:167], v254 offset:49152
	ds_read_b128 v[168:171], v254 offset:50176
	ds_read_b128 v[172:175], v254 offset:51200
	ds_read_b128 v[176:179], v254 offset:52224
	s_add_u32 s44, s44, 0x80000
	s_addc_u32 s45, s45, 0
	s_mov_b32 m0, s51
	ds_read_b128 v[180:183], v145 offset:32768
	ds_read_b128 v[184:187], v145 offset:33792
	ds_read_b128 v[188:191], v145 offset:34816
	ds_read_b128 v[192:195], v145 offset:35840
	ds_read_b128 v[196:199], v145 offset:36864
	ds_read_b128 v[200:203], v145 offset:37888
	ds_read_b128 v[204:207], v145 offset:38912
	ds_read_b128 v[208:211], v145 offset:39936
	global_load_lds_dwordx4 v134, s[44:45]
	s_mov_b32 m0, s52
	s_nop 0
	global_load_lds_dwordx4 v130, s[44:45]
	s_waitcnt vmcnt(8)
	s_waitcnt lgkmcnt(0)
	s_barrier
	s_waitcnt lgkmcnt(0)
	v_mfma_f32_16x16x32_bf16 v[116:119], v[148:151], v[180:183], v[116:119]
	v_mfma_f32_16x16x32_bf16 v[112:115], v[156:159], v[180:183], v[112:115]
	v_mfma_f32_16x16x32_bf16 v[108:111], v[148:151], v[188:191], v[108:111]
	v_mfma_f32_16x16x32_bf16 v[104:107], v[156:159], v[188:191], v[104:107]
	v_mfma_f32_16x16x32_bf16 v[92:95], v[148:151], v[196:199], v[92:95]
	v_mfma_f32_16x16x32_bf16 v[88:91], v[156:159], v[196:199], v[88:91]
	v_mfma_f32_16x16x32_bf16 v[76:79], v[148:151], v[204:207], v[76:79]
	v_mfma_f32_16x16x32_bf16 v[72:75], v[156:159], v[204:207], v[72:75]
	v_mfma_f32_16x16x32_bf16 v[116:119], v[152:155], v[184:187], v[116:119]
	v_mfma_f32_16x16x32_bf16 v[112:115], v[160:163], v[184:187], v[112:115]
	v_mfma_f32_16x16x32_bf16 v[108:111], v[152:155], v[192:195], v[108:111]
	v_mfma_f32_16x16x32_bf16 v[104:107], v[160:163], v[192:195], v[104:107]
	v_mfma_f32_16x16x32_bf16 v[92:95], v[152:155], v[200:203], v[92:95]
	v_mfma_f32_16x16x32_bf16 v[88:91], v[160:163], v[200:203], v[88:91]
	v_mfma_f32_16x16x32_bf16 v[76:79], v[152:155], v[208:211], v[76:79]
	v_mfma_f32_16x16x32_bf16 v[72:75], v[160:163], v[208:211], v[72:75]
	v_mfma_f32_16x16x32_bf16 v[124:127], v[164:167], v[180:183], v[124:127]
	v_mfma_f32_16x16x32_bf16 v[120:123], v[172:175], v[180:183], v[120:123]
	v_mfma_f32_16x16x32_bf16 v[100:103], v[164:167], v[188:191], v[100:103]
	v_mfma_f32_16x16x32_bf16 v[96:99], v[172:175], v[188:191], v[96:99]
	v_mfma_f32_16x16x32_bf16 v[84:87], v[164:167], v[196:199], v[84:87]
	v_mfma_f32_16x16x32_bf16 v[80:83], v[172:175], v[196:199], v[80:83]
	v_mfma_f32_16x16x32_bf16 v[68:71], v[164:167], v[204:207], v[68:71]
	v_mfma_f32_16x16x32_bf16 v[64:67], v[172:175], v[204:207], v[64:67]
	v_mfma_f32_16x16x32_bf16 v[124:127], v[168:171], v[184:187], v[124:127]
	v_mfma_f32_16x16x32_bf16 v[120:123], v[176:179], v[184:187], v[120:123]
	v_mfma_f32_16x16x32_bf16 v[100:103], v[168:171], v[192:195], v[100:103]
	v_mfma_f32_16x16x32_bf16 v[96:99], v[176:179], v[192:195], v[96:99]
	v_mfma_f32_16x16x32_bf16 v[84:87], v[168:171], v[200:203], v[84:87]
	v_mfma_f32_16x16x32_bf16 v[80:83], v[176:179], v[200:203], v[80:83]
	v_mfma_f32_16x16x32_bf16 v[68:71], v[168:171], v[208:211], v[68:71]
	v_mfma_f32_16x16x32_bf16 v[64:67], v[176:179], v[208:211], v[64:67]
	s_barrier
	s_add_u32 s40, s40, s42
	s_addc_u32 s41, s41, s43
	s_add_i32 s13, s13, s33
	s_mov_b32 m0, s13
	ds_read_b128 v[180:183], v145 offset:49152
	ds_read_b128 v[184:187], v145 offset:50176
	ds_read_b128 v[188:191], v145 offset:51200
	ds_read_b128 v[192:195], v145 offset:52224
	ds_read_b128 v[196:199], v145 offset:53248
	ds_read_b128 v[200:203], v145 offset:54272
	ds_read_b128 v[204:207], v145 offset:55296
	ds_read_b128 v[208:211], v145 offset:56320
	global_load_lds_dwordx4 v132, s[40:41]
	s_add_i32 m0, s13, 0x2000
	s_nop 0
	global_load_lds_dwordx4 v128, s[40:41]
	s_add_u32 s40, s40, 0x80000
	s_addc_u32 s41, s41, 0
	s_add_i32 s13, s63, s33
	s_mov_b32 m0, s13
	s_nop 0
	global_load_lds_dwordx4 v132, s[40:41]
	s_add_i32 m0, s13, 0x2000
	s_nop 0
	global_load_lds_dwordx4 v128, s[40:41]
	s_mov_b32 m0, s53
	s_nop 0
	global_load_lds_dwordx4 v134, s[46:47]
	s_mov_b32 m0, s54
	s_nop 0
	global_load_lds_dwordx4 v130, s[46:47]
	s_waitcnt vmcnt(8)
	s_waitcnt lgkmcnt(0)
	s_barrier
	s_waitcnt lgkmcnt(0)
	v_mfma_f32_16x16x32_bf16 v[60:63], v[148:151], v[180:183], v[60:63]
	v_mfma_f32_16x16x32_bf16 v[56:59], v[156:159], v[180:183], v[56:59]
	v_mfma_f32_16x16x32_bf16 v[44:47], v[148:151], v[188:191], v[44:47]
	v_mfma_f32_16x16x32_bf16 v[40:43], v[156:159], v[188:191], v[40:43]
	v_mfma_f32_16x16x32_bf16 v[28:31], v[148:151], v[196:199], v[28:31]
	v_mfma_f32_16x16x32_bf16 v[24:27], v[156:159], v[196:199], v[24:27]
	v_mfma_f32_16x16x32_bf16 v[12:15], v[148:151], v[204:207], v[12:15]
	v_mfma_f32_16x16x32_bf16 v[8:11], v[156:159], v[204:207], v[8:11]
	v_mfma_f32_16x16x32_bf16 v[60:63], v[152:155], v[184:187], v[60:63]
	v_mfma_f32_16x16x32_bf16 v[56:59], v[160:163], v[184:187], v[56:59]
	v_mfma_f32_16x16x32_bf16 v[44:47], v[152:155], v[192:195], v[44:47]
	v_mfma_f32_16x16x32_bf16 v[40:43], v[160:163], v[192:195], v[40:43]
	v_mfma_f32_16x16x32_bf16 v[28:31], v[152:155], v[200:203], v[28:31]
	v_mfma_f32_16x16x32_bf16 v[24:27], v[160:163], v[200:203], v[24:27]
	v_mfma_f32_16x16x32_bf16 v[12:15], v[152:155], v[208:211], v[12:15]
	v_mfma_f32_16x16x32_bf16 v[8:11], v[160:163], v[208:211], v[8:11]
	v_mfma_f32_16x16x32_bf16 v[52:55], v[164:167], v[180:183], v[52:55]
	v_mfma_f32_16x16x32_bf16 v[48:51], v[172:175], v[180:183], v[48:51]
	v_mfma_f32_16x16x32_bf16 v[36:39], v[164:167], v[188:191], v[36:39]
	v_mfma_f32_16x16x32_bf16 v[32:35], v[172:175], v[188:191], v[32:35]
	v_mfma_f32_16x16x32_bf16 v[20:23], v[164:167], v[196:199], v[20:23]
	v_mfma_f32_16x16x32_bf16 v[16:19], v[172:175], v[196:199], v[16:19]
	v_mfma_f32_16x16x32_bf16 v[4:7], v[164:167], v[204:207], v[4:7]
	v_mfma_f32_16x16x32_bf16 v[0:3], v[172:175], v[204:207], v[0:3]
	v_mfma_f32_16x16x32_bf16 v[52:55], v[168:171], v[184:187], v[52:55]
	v_mfma_f32_16x16x32_bf16 v[48:51], v[176:179], v[184:187], v[48:51]
	v_mfma_f32_16x16x32_bf16 v[36:39], v[168:171], v[192:195], v[36:39]
	v_mfma_f32_16x16x32_bf16 v[32:35], v[176:179], v[192:195], v[32:35]
	v_mfma_f32_16x16x32_bf16 v[20:23], v[168:171], v[200:203], v[20:23]
	v_mfma_f32_16x16x32_bf16 v[16:19], v[176:179], v[200:203], v[16:19]
	v_mfma_f32_16x16x32_bf16 v[4:7], v[168:171], v[208:211], v[4:7]
	v_mfma_f32_16x16x32_bf16 v[0:3], v[176:179], v[208:211], v[0:3]
	s_barrier
	s_cmp_gt_u32 s62, 29
	s_mov_b32 s62, s11
	s_cbranch_scc1 .LBB0_126

; #define PG8_STAGE(bufoff, gbase, voff) do { _Pragma("unroll") for (int _i = 0; _i < 2; ++_i) \
;         __builtin_amdgcn_global_load_lds((const unsigned*)((const char*)(gbase) + (voff)[_i]), (LAS unsigned*)(lds + (bufoff) + ldsw + _i * 8192), 16, 0, 0); } while (0)
; #define PG8_LDA(dst, b, h) do { _Pragma("unroll") for (int m = 0; m < 4; ++m) _Pragma("unroll") for (int k = 0; k < 2; ++k) dst[m][k] = *(const LAS bf16x8*)(lds + PG8_SA(b, h) + aoff + m * 2048 + k * 1024); } while (0)
; #define PG8_LDB(dst, b, h) do { _Pragma("unroll") for (int n = 0; n < 2; ++n) _Pragma("unroll") for (int k = 0; k < 2; ++k) dst[n][k] = *(const LAS bf16x8*)(lds + PG8_SB(b, h) + boff + n * 2048 + k * 1024); } while (0)
; #define PG8_MMA(ai, bj, At, Bt) do { __builtin_amdgcn_s_setprio(1); _Pragma("unroll") for (int m = 0; m < 4; ++m) _Pragma("unroll") for (int n = 0; n < 2; ++n) _Pragma("unroll") for (int k = 0; k < 2; ++k) \
;         acc[ai][bj][m][n] = __builtin_amdgcn_mfma_f32_16x16x32_bf16(Bt[n][k], At[m][k], acc[ai][bj][m][n], 0, 0, 0); __builtin_amdgcn_s_setprio(0); } while (0)
; #define PG8_WAIT_V(n) asm volatile("s_waitcnt vmcnt(" #n ")" ::: "memory")
; #define PG8_WAIT_L(n) asm volatile("s_waitcnt lgkmcnt(" #n ")" ::: "memory")
; #define PG8_BAR __builtin_amdgcn_s_barrier()
; #define PG8_SCHED __builtin_amdgcn_sched_barrier(0)
; template <class Epi>
; __device__ __forceinline__ void gemm_phase(LAS unsigned char* lds, const Gemm g, const StaticOrder S, const Epi E) {
;     ...
;             const char* a1 = cA + (long)(t + 1) * ksc;
;             const char* a2 = last ? nA : cA + (long)(t + 2) * ksc; const char* b2 = last ? nB : cB + (long)(t + 2) * ksc;
;             const long ks3 = last ? ksn : ksc;
;             const char* a3 = a2 + ks3; const char* b3 = b2 + ks3;
;             PG8_LDB(B0, 0, 0); PG8_LDB(B1, 0, 1); PG8_SCHED; PG8_LDA(At, 0, 0); PG8_STAGE(PG8_SA(1, 1), a1 + hstepA, voffA);
;             PG8_WAIT_V(8); PG8_WAIT_L(0); PG8_BAR; PG8_MMA(0, 0, At, B0); PG8_MMA(0, 1, At, B1); PG8_BAR; PG8_SCHED;
;             PG8_LDA(At, 0, 1); PG8_STAGE(PG8_SB(0, 0), b2, voffB); PG8_STAGE(PG8_SB(0, 1), b2 + hstepB, voffB); PG8_STAGE(PG8_SA(0, 0), a2, voffA);
;             PG8_WAIT_V(8); PG8_WAIT_L(0); PG8_BAR; PG8_MMA(1, 0, At, B0); PG8_MMA(1, 1, At, B1); PG8_BAR; PG8_SCHED;
.LBB0_206:
	v_add_u32_e32 v152, s59, v164
	v_add_u32_e32 v176, s60, v164
	ds_read_b128 v[128:131], v152
	ds_read_b128 v[132:135], v152 offset:1024
	ds_read_b128 v[136:139], v152 offset:2048
	ds_read_b128 v[152:155], v152 offset:3072
	ds_read_b128 v[156:159], v176
	ds_read_b128 v[168:171], v176 offset:1024
	ds_read_b128 v[172:175], v176 offset:2048
	ds_read_b128 v[176:179], v176 offset:3072
	s_or_b32 s48, s70, 1
	s_mul_i32 s49, s35, s48
	s_mul_hi_u32 s72, s34, s48
	s_add_i32 s72, s72, s49
	s_mul_i32 s48, s34, s48
	s_add_u32 s73, s30, s48
	s_addc_u32 s74, s31, s72
	s_add_u32 s48, s46, s44
	s_addc_u32 s49, s47, s45
	s_add_u32 s72, s73, 0x160000
	s_addc_u32 s73, s74, 0
	s_add_i32 m0, s50, 0xc000
	ds_read_b128 v[180:183], v166
	ds_read_b128 v[184:187], v166 offset:1024
	ds_read_b128 v[188:191], v166 offset:2048
	ds_read_b128 v[192:195], v166 offset:3072
	ds_read_b128 v[196:199], v166 offset:4096
	ds_read_b128 v[200:203], v166 offset:5120
	ds_read_b128 v[204:207], v166 offset:6144
	ds_read_b128 v[208:211], v166 offset:7168
	global_load_lds_dwordx4 v140, s[72:73]
	s_add_i32 m0, s50, 0xe000
	s_nop 0
	global_load_lds_dwordx4 v144, s[72:73]
	s_waitcnt vmcnt(8)
	s_waitcnt lgkmcnt(0)
	s_barrier
	s_waitcnt lgkmcnt(0)
	v_mfma_f32_16x16x32_bf16 v[124:127], v[128:131], v[180:183], v[124:127]
	v_mfma_f32_16x16x32_bf16 v[120:123], v[136:139], v[180:183], v[120:123]
	v_mfma_f32_16x16x32_bf16 v[108:111], v[128:131], v[188:191], v[108:111]
	v_mfma_f32_16x16x32_bf16 v[104:107], v[136:139], v[188:191], v[104:107]
	v_mfma_f32_16x16x32_bf16 v[92:95], v[128:131], v[196:199], v[92:95]
	v_mfma_f32_16x16x32_bf16 v[88:91], v[136:139], v[196:199], v[88:91]
	v_mfma_f32_16x16x32_bf16 v[76:79], v[128:131], v[204:207], v[76:79]
	v_mfma_f32_16x16x32_bf16 v[72:75], v[136:139], v[204:207], v[72:75]
	v_mfma_f32_16x16x32_bf16 v[124:127], v[132:135], v[184:187], v[124:127]
	v_mfma_f32_16x16x32_bf16 v[120:123], v[152:155], v[184:187], v[120:123]
	v_mfma_f32_16x16x32_bf16 v[108:111], v[132:135], v[192:195], v[108:111]
	v_mfma_f32_16x16x32_bf16 v[104:107], v[152:155], v[192:195], v[104:107]
	v_mfma_f32_16x16x32_bf16 v[92:95], v[132:135], v[200:203], v[92:95]
	v_mfma_f32_16x16x32_bf16 v[88:91], v[152:155], v[200:203], v[88:91]
	v_mfma_f32_16x16x32_bf16 v[76:79], v[132:135], v[208:211], v[76:79]
	v_mfma_f32_16x16x32_bf16 v[72:75], v[152:155], v[208:211], v[72:75]
	v_mfma_f32_16x16x32_bf16 v[116:119], v[156:159], v[180:183], v[116:119]
	v_mfma_f32_16x16x32_bf16 v[112:115], v[172:175], v[180:183], v[112:115]
	v_mfma_f32_16x16x32_bf16 v[100:103], v[156:159], v[188:191], v[100:103]
	v_mfma_f32_16x16x32_bf16 v[96:99], v[172:175], v[188:191], v[96:99]
	v_mfma_f32_16x16x32_bf16 v[84:87], v[156:159], v[196:199], v[84:87]
	v_mfma_f32_16x16x32_bf16 v[80:83], v[172:175], v[196:199], v[80:83]
	v_mfma_f32_16x16x32_bf16 v[68:71], v[156:159], v[204:207], v[68:71]
	v_mfma_f32_16x16x32_bf16 v[64:67], v[172:175], v[204:207], v[64:67]
	v_mfma_f32_16x16x32_bf16 v[116:119], v[168:171], v[184:187], v[116:119]
	v_mfma_f32_16x16x32_bf16 v[112:115], v[176:179], v[184:187], v[112:115]
	v_mfma_f32_16x16x32_bf16 v[100:103], v[168:171], v[192:195], v[100:103]
	v_mfma_f32_16x16x32_bf16 v[96:99], v[176:179], v[192:195], v[96:99]
	v_mfma_f32_16x16x32_bf16 v[84:87], v[168:171], v[200:203], v[84:87]
	v_mfma_f32_16x16x32_bf16 v[80:83], v[176:179], v[200:203], v[80:83]
	v_mfma_f32_16x16x32_bf16 v[68:71], v[168:171], v[208:211], v[68:71]
	v_mfma_f32_16x16x32_bf16 v[64:67], v[176:179], v[208:211], v[64:67]
	s_barrier
	s_add_i32 s72, s59, s33
	s_mov_b32 m0, s72
	ds_read_b128 v[180:183], v166 offset:16384
	ds_read_b128 v[184:187], v166 offset:17408
	ds_read_b128 v[188:191], v166 offset:18432
	ds_read_b128 v[192:195], v166 offset:19456
	ds_read_b128 v[196:199], v166 offset:20480
	ds_read_b128 v[200:203], v166 offset:21504
	ds_read_b128 v[204:207], v166 offset:22528
	ds_read_b128 v[208:211], v166 offset:23552
	global_load_lds_dwordx4 v142, s[42:43]
	s_add_i32 m0, s72, 0x2000
	s_add_u32 s72, s42, 0x160000
	s_addc_u32 s73, s43, 0
	s_add_i32 s74, s60, s33
	global_load_lds_dwordx4 v146, s[42:43]
	s_mov_b32 m0, s74
	s_nop 0
	global_load_lds_dwordx4 v142, s[72:73]
	s_add_i32 m0, s74, 0x2000
	s_nop 0
	global_load_lds_dwordx4 v146, s[72:73]
	s_mov_b32 m0, s50
	s_nop 0
	global_load_lds_dwordx4 v140, s[46:47]
	s_mov_b32 m0, s51
	s_nop 0
	global_load_lds_dwordx4 v144, s[46:47]
	s_waitcnt vmcnt(8)
	s_waitcnt lgkmcnt(0)
	s_barrier
	s_waitcnt lgkmcnt(0)
	v_mfma_f32_16x16x32_bf16 v[60:63], v[128:131], v[180:183], v[60:63]
	v_mfma_f32_16x16x32_bf16 v[56:59], v[136:139], v[180:183], v[56:59]
	v_mfma_f32_16x16x32_bf16 v[44:47], v[128:131], v[188:191], v[44:47]
	v_mfma_f32_16x16x32_bf16 v[40:43], v[136:139], v[188:191], v[40:43]
	v_mfma_f32_16x16x32_bf16 v[28:31], v[128:131], v[196:199], v[28:31]
	v_mfma_f32_16x16x32_bf16 v[24:27], v[136:139], v[196:199], v[24:27]
	v_mfma_f32_16x16x32_bf16 v[12:15], v[128:131], v[204:207], v[12:15]
	v_mfma_f32_16x16x32_bf16 v[8:11], v[136:139], v[204:207], v[8:11]
	v_mfma_f32_16x16x32_bf16 v[60:63], v[132:135], v[184:187], v[60:63]
	v_mfma_f32_16x16x32_bf16 v[56:59], v[152:155], v[184:187], v[56:59]
	v_mfma_f32_16x16x32_bf16 v[44:47], v[132:135], v[192:195], v[44:47]
	v_mfma_f32_16x16x32_bf16 v[40:43], v[152:155], v[192:195], v[40:43]
	v_mfma_f32_16x16x32_bf16 v[28:31], v[132:135], v[200:203], v[28:31]
	v_mfma_f32_16x16x32_bf16 v[24:27], v[152:155], v[200:203], v[24:27]
	v_mfma_f32_16x16x32_bf16 v[12:15], v[132:135], v[208:211], v[12:15]
	v_mfma_f32_16x16x32_bf16 v[8:11], v[152:155], v[208:211], v[8:11]
	v_mfma_f32_16x16x32_bf16 v[52:55], v[156:159], v[180:183], v[52:55]
	v_mfma_f32_16x16x32_bf16 v[48:51], v[172:175], v[180:183], v[48:51]
	v_mfma_f32_16x16x32_bf16 v[36:39], v[156:159], v[188:191], v[36:39]
	v_mfma_f32_16x16x32_bf16 v[32:35], v[172:175], v[188:191], v[32:35]
	v_mfma_f32_16x16x32_bf16 v[20:23], v[156:159], v[196:199], v[20:23]
	v_mfma_f32_16x16x32_bf16 v[16:19], v[172:175], v[196:199], v[16:19]
	v_mfma_f32_16x16x32_bf16 v[4:7], v[156:159], v[204:207], v[4:7]
	v_mfma_f32_16x16x32_bf16 v[0:3], v[172:175], v[204:207], v[0:3]
	v_mfma_f32_16x16x32_bf16 v[52:55], v[168:171], v[184:187], v[52:55]
	v_mfma_f32_16x16x32_bf16 v[48:51], v[176:179], v[184:187], v[48:51]
	v_mfma_f32_16x16x32_bf16 v[36:39], v[168:171], v[192:195], v[36:39]
	v_mfma_f32_16x16x32_bf16 v[32:35], v[176:179], v[192:195], v[32:35]
	v_mfma_f32_16x16x32_bf16 v[20:23], v[168:171], v[200:203], v[20:23]
	v_mfma_f32_16x16x32_bf16 v[16:19], v[176:179], v[200:203], v[16:19]
	v_mfma_f32_16x16x32_bf16 v[4:7], v[168:171], v[208:211], v[4:7]
	v_mfma_f32_16x16x32_bf16 v[0:3], v[176:179], v[208:211], v[0:3]
	s_barrier
; #define PG8_STAGE(bufoff, gbase, voff) do { _Pragma("unroll") for (int _i = 0; _i < 2; ++_i) \
;         __builtin_amdgcn_global_load_lds((const unsigned*)((const char*)(gbase) + (voff)[_i]), (LAS unsigned*)(lds + (bufoff) + ldsw + _i * 8192), 16, 0, 0); } while (0)
; #define PG8_LDA(dst, b, h) do { _Pragma("unroll") for (int m = 0; m < 4; ++m) _Pragma("unroll") for (int k = 0; k < 2; ++k) dst[m][k] = *(const LAS bf16x8*)(lds + PG8_SA(b, h) + aoff + m * 2048 + k * 1024); } while (0)
; #define PG8_LDB(dst, b, h) do { _Pragma("unroll") for (int n = 0; n < 2; ++n) _Pragma("unroll") for (int k = 0; k < 2; ++k) dst[n][k] = *(const LAS bf16x8*)(lds + PG8_SB(b, h) + boff + n * 2048 + k * 1024); } while (0)
; #define PG8_MMA(ai, bj, At, Bt) do { __builtin_amdgcn_s_setprio(1); _Pragma("unroll") for (int m = 0; m < 4; ++m) _Pragma("unroll") for (int n = 0; n < 2; ++n) _Pragma("unroll") for (int k = 0; k < 2; ++k) \
;         acc[ai][bj][m][n] = __builtin_amdgcn_mfma_f32_16x16x32_bf16(Bt[n][k], At[m][k], acc[ai][bj][m][n], 0, 0, 0); __builtin_amdgcn_s_setprio(0); } while (0)
; #define PG8_WAIT_V(n) asm volatile("s_waitcnt vmcnt(" #n ")" ::: "memory")
; #define PG8_WAIT_L(n) asm volatile("s_waitcnt lgkmcnt(" #n ")" ::: "memory")
; #define PG8_BAR __builtin_amdgcn_s_barrier()
; #define PG8_SCHED __builtin_amdgcn_sched_barrier(0)
; template <class Epi>
; __device__ __forceinline__ void gemm_phase(LAS unsigned char* lds, const Gemm g, const StaticOrder S, const Epi E) {
;     ...
;             PG8_LDB(B0, 1, 0); PG8_LDB(B1, 1, 1); PG8_SCHED; PG8_LDA(At, 1, 0); PG8_STAGE(PG8_SA(0, 1), a2 + hstepA, voffA);
;             PG8_WAIT_V(8); PG8_WAIT_L(0); PG8_BAR; PG8_MMA(0, 0, At, B0); PG8_MMA(0, 1, At, B1); PG8_BAR; PG8_SCHED;
;             PG8_LDA(At, 1, 1); PG8_STAGE(PG8_SB(1, 0), b3, voffB); PG8_STAGE(PG8_SB(1, 1), b3 + hstepB, voffB); PG8_STAGE(PG8_SA(1, 0), a3, voffA);
;             PG8_WAIT_V(8); PG8_WAIT_L(0); PG8_BAR; PG8_MMA(1, 0, At, B0); PG8_MMA(1, 1, At, B1); PG8_BAR; PG8_SCHED;
;         }
	s_add_i32 s72, 0, 0x18000
	s_add_i32 s73, 0, 0x1c000
	v_add_u32_e32 v152, s72, v164
	v_add_u32_e32 v176, s73, v164
	ds_read_b128 v[128:131], v152
	ds_read_b128 v[132:135], v152 offset:1024
	ds_read_b128 v[136:139], v152 offset:2048
	ds_read_b128 v[152:155], v152 offset:3072
	ds_read_b128 v[156:159], v176
	ds_read_b128 v[168:171], v176 offset:1024
	ds_read_b128 v[172:175], v176 offset:2048
	ds_read_b128 v[176:179], v176 offset:3072
	s_add_u32 s46, s46, 0x160000
	s_addc_u32 s47, s47, 0
	s_mov_b32 m0, s52
	ds_read_b128 v[180:183], v166 offset:32768
	ds_read_b128 v[184:187], v166 offset:33792
	ds_read_b128 v[188:191], v166 offset:34816
	ds_read_b128 v[192:195], v166 offset:35840
	ds_read_b128 v[196:199], v166 offset:36864
	ds_read_b128 v[200:203], v166 offset:37888
	ds_read_b128 v[204:207], v166 offset:38912
	ds_read_b128 v[208:211], v166 offset:39936
	global_load_lds_dwordx4 v140, s[46:47]
	s_mov_b32 m0, s53
	s_nop 0
	global_load_lds_dwordx4 v144, s[46:47]
	s_waitcnt vmcnt(8)
	s_waitcnt lgkmcnt(0)
	s_barrier
	s_waitcnt lgkmcnt(0)
	v_mfma_f32_16x16x32_bf16 v[124:127], v[128:131], v[180:183], v[124:127]
	v_mfma_f32_16x16x32_bf16 v[120:123], v[136:139], v[180:183], v[120:123]
	v_mfma_f32_16x16x32_bf16 v[108:111], v[128:131], v[188:191], v[108:111]
	v_mfma_f32_16x16x32_bf16 v[104:107], v[136:139], v[188:191], v[104:107]
	v_mfma_f32_16x16x32_bf16 v[92:95], v[128:131], v[196:199], v[92:95]
	v_mfma_f32_16x16x32_bf16 v[88:91], v[136:139], v[196:199], v[88:91]
	v_mfma_f32_16x16x32_bf16 v[76:79], v[128:131], v[204:207], v[76:79]
	v_mfma_f32_16x16x32_bf16 v[72:75], v[136:139], v[204:207], v[72:75]
	v_mfma_f32_16x16x32_bf16 v[124:127], v[132:135], v[184:187], v[124:127]
	v_mfma_f32_16x16x32_bf16 v[120:123], v[152:155], v[184:187], v[120:123]
	v_mfma_f32_16x16x32_bf16 v[108:111], v[132:135], v[192:195], v[108:111]
	v_mfma_f32_16x16x32_bf16 v[104:107], v[152:155], v[192:195], v[104:107]
	v_mfma_f32_16x16x32_bf16 v[92:95], v[132:135], v[200:203], v[92:95]
	v_mfma_f32_16x16x32_bf16 v[88:91], v[152:155], v[200:203], v[88:91]
	v_mfma_f32_16x16x32_bf16 v[76:79], v[132:135], v[208:211], v[76:79]
	v_mfma_f32_16x16x32_bf16 v[72:75], v[152:155], v[208:211], v[72:75]
	v_mfma_f32_16x16x32_bf16 v[116:119], v[156:159], v[180:183], v[116:119]
	v_mfma_f32_16x16x32_bf16 v[112:115], v[172:175], v[180:183], v[112:115]
	v_mfma_f32_16x16x32_bf16 v[100:103], v[156:159], v[188:191], v[100:103]
	v_mfma_f32_16x16x32_bf16 v[96:99], v[172:175], v[188:191], v[96:99]
	v_mfma_f32_16x16x32_bf16 v[84:87], v[156:159], v[196:199], v[84:87]
	v_mfma_f32_16x16x32_bf16 v[80:83], v[172:175], v[196:199], v[80:83]
	v_mfma_f32_16x16x32_bf16 v[68:71], v[156:159], v[204:207], v[68:71]
	v_mfma_f32_16x16x32_bf16 v[64:67], v[172:175], v[204:207], v[64:67]
	v_mfma_f32_16x16x32_bf16 v[116:119], v[168:171], v[184:187], v[116:119]
	v_mfma_f32_16x16x32_bf16 v[112:115], v[176:179], v[184:187], v[112:115]
	v_mfma_f32_16x16x32_bf16 v[100:103], v[168:171], v[192:195], v[100:103]
	v_mfma_f32_16x16x32_bf16 v[96:99], v[176:179], v[192:195], v[96:99]
	v_mfma_f32_16x16x32_bf16 v[84:87], v[168:171], v[200:203], v[84:87]
	v_mfma_f32_16x16x32_bf16 v[80:83], v[176:179], v[200:203], v[80:83]
	v_mfma_f32_16x16x32_bf16 v[68:71], v[168:171], v[208:211], v[68:71]
	v_mfma_f32_16x16x32_bf16 v[64:67], v[176:179], v[208:211], v[64:67]
	s_barrier
	s_add_u32 s42, s42, s44
	s_addc_u32 s43, s43, s45
	s_add_i32 s44, s72, s33
	s_mov_b32 m0, s44
	ds_read_b128 v[180:183], v166 offset:49152
	ds_read_b128 v[184:187], v166 offset:50176
	ds_read_b128 v[188:191], v166 offset:51200
	ds_read_b128 v[192:195], v166 offset:52224
	ds_read_b128 v[196:199], v166 offset:53248
	ds_read_b128 v[200:203], v166 offset:54272
	ds_read_b128 v[204:207], v166 offset:55296
	ds_read_b128 v[208:211], v166 offset:56320
	global_load_lds_dwordx4 v142, s[42:43]
	s_add_i32 m0, s44, 0x2000
	s_nop 0
	global_load_lds_dwordx4 v146, s[42:43]
	s_add_u32 s42, s42, 0x160000
	s_addc_u32 s43, s43, 0
	s_add_i32 s44, s73, s33
	s_mov_b32 m0, s44
	s_nop 0
	global_load_lds_dwordx4 v142, s[42:43]
	s_add_i32 m0, s44, 0x2000
	s_nop 0
	global_load_lds_dwordx4 v146, s[42:43]
	s_mov_b32 m0, s55
	s_nop 0
	global_load_lds_dwordx4 v140, s[48:49]
	s_mov_b32 m0, s56
	s_nop 0
	global_load_lds_dwordx4 v144, s[48:49]
	s_waitcnt vmcnt(8)
	s_waitcnt lgkmcnt(0)
	s_barrier
	s_waitcnt lgkmcnt(0)
	v_mfma_f32_16x16x32_bf16 v[60:63], v[128:131], v[180:183], v[60:63]
	v_mfma_f32_16x16x32_bf16 v[56:59], v[136:139], v[180:183], v[56:59]
	v_mfma_f32_16x16x32_bf16 v[44:47], v[128:131], v[188:191], v[44:47]
	v_mfma_f32_16x16x32_bf16 v[40:43], v[136:139], v[188:191], v[40:43]
	v_mfma_f32_16x16x32_bf16 v[28:31], v[128:131], v[196:199], v[28:31]
	v_mfma_f32_16x16x32_bf16 v[24:27], v[136:139], v[196:199], v[24:27]
	v_mfma_f32_16x16x32_bf16 v[12:15], v[128:131], v[204:207], v[12:15]
	v_mfma_f32_16x16x32_bf16 v[8:11], v[136:139], v[204:207], v[8:11]
	v_mfma_f32_16x16x32_bf16 v[60:63], v[132:135], v[184:187], v[60:63]
	v_mfma_f32_16x16x32_bf16 v[56:59], v[152:155], v[184:187], v[56:59]
	v_mfma_f32_16x16x32_bf16 v[44:47], v[132:135], v[192:195], v[44:47]
	v_mfma_f32_16x16x32_bf16 v[40:43], v[152:155], v[192:195], v[40:43]
	v_mfma_f32_16x16x32_bf16 v[28:31], v[132:135], v[200:203], v[28:31]
	v_mfma_f32_16x16x32_bf16 v[24:27], v[152:155], v[200:203], v[24:27]
	v_mfma_f32_16x16x32_bf16 v[12:15], v[132:135], v[208:211], v[12:15]
	v_mfma_f32_16x16x32_bf16 v[8:11], v[152:155], v[208:211], v[8:11]
	v_mfma_f32_16x16x32_bf16 v[52:55], v[156:159], v[180:183], v[52:55]
	v_mfma_f32_16x16x32_bf16 v[48:51], v[172:175], v[180:183], v[48:51]
	v_mfma_f32_16x16x32_bf16 v[36:39], v[156:159], v[188:191], v[36:39]
	v_mfma_f32_16x16x32_bf16 v[32:35], v[172:175], v[188:191], v[32:35]
	v_mfma_f32_16x16x32_bf16 v[20:23], v[156:159], v[196:199], v[20:23]
	v_mfma_f32_16x16x32_bf16 v[16:19], v[172:175], v[196:199], v[16:19]
	v_mfma_f32_16x16x32_bf16 v[4:7], v[156:159], v[204:207], v[4:7]
	v_mfma_f32_16x16x32_bf16 v[0:3], v[172:175], v[204:207], v[0:3]
	v_mfma_f32_16x16x32_bf16 v[52:55], v[168:171], v[184:187], v[52:55]
	v_mfma_f32_16x16x32_bf16 v[48:51], v[176:179], v[184:187], v[48:51]
	v_mfma_f32_16x16x32_bf16 v[36:39], v[168:171], v[192:195], v[36:39]
	v_mfma_f32_16x16x32_bf16 v[32:35], v[176:179], v[192:195], v[32:35]
	v_mfma_f32_16x16x32_bf16 v[20:23], v[168:171], v[200:203], v[20:23]
	v_mfma_f32_16x16x32_bf16 v[16:19], v[176:179], v[200:203], v[16:19]
	v_mfma_f32_16x16x32_bf16 v[4:7], v[168:171], v[208:211], v[4:7]
	v_mfma_f32_16x16x32_bf16 v[0:3], v[176:179], v[208:211], v[0:3]
	s_barrier
	s_cmpk_gt_u32 s70, 0x55
	s_mov_b32 s70, s71
	s_cbranch_scc1 .LBB0_211

; #define PG8_STAGE(bufoff, gbase, voff) do { _Pragma("unroll") for (int _i = 0; _i < 2; ++_i) \
;         __builtin_amdgcn_global_load_lds((const unsigned*)((const char*)(gbase) + (voff)[_i]), (LAS unsigned*)(lds + (bufoff) + ldsw + _i * 8192), 16, 0, 0); } while (0)
; #define PG8_LDA(dst, b, h) do { _Pragma("unroll") for (int m = 0; m < 4; ++m) _Pragma("unroll") for (int k = 0; k < 2; ++k) dst[m][k] = *(const LAS bf16x8*)(lds + PG8_SA(b, h) + aoff + m * 2048 + k * 1024); } while (0)
; #define PG8_LDB(dst, b, h) do { _Pragma("unroll") for (int n = 0; n < 2; ++n) _Pragma("unroll") for (int k = 0; k < 2; ++k) dst[n][k] = *(const LAS bf16x8*)(lds + PG8_SB(b, h) + boff + n * 2048 + k * 1024); } while (0)
; #define PG8_MMA(ai, bj, At, Bt) do { __builtin_amdgcn_s_setprio(1); _Pragma("unroll") for (int m = 0; m < 4; ++m) _Pragma("unroll") for (int n = 0; n < 2; ++n) _Pragma("unroll") for (int k = 0; k < 2; ++k) \
;         acc[ai][bj][m][n] = __builtin_amdgcn_mfma_f32_16x16x32_bf16(Bt[n][k], At[m][k], acc[ai][bj][m][n], 0, 0, 0); __builtin_amdgcn_s_setprio(0); } while (0)
; #define PG8_WAIT_V(n) asm volatile("s_waitcnt vmcnt(" #n ")" ::: "memory")
; #define PG8_WAIT_L(n) asm volatile("s_waitcnt lgkmcnt(" #n ")" ::: "memory")
; #define PG8_BAR __builtin_amdgcn_s_barrier()
; #define PG8_SCHED __builtin_amdgcn_sched_barrier(0)
; template <class Epi>
; __device__ __forceinline__ void gemm_phase(LAS unsigned char* lds, const Gemm g, const StaticOrder S, const Epi E) {
;     ...
;             const char* a1 = cA + (long)(t + 1) * ksc;
;             const char* a2 = last ? nA : cA + (long)(t + 2) * ksc; const char* b2 = last ? nB : cB + (long)(t + 2) * ksc;
;             const long ks3 = last ? ksn : ksc;
;             const char* a3 = a2 + ks3; const char* b3 = b2 + ks3;
;             PG8_LDB(B0, 0, 0); PG8_LDB(B1, 0, 1); PG8_SCHED; PG8_LDA(At, 0, 0); PG8_STAGE(PG8_SA(1, 1), a1 + hstepA, voffA);
;             PG8_WAIT_V(8); PG8_WAIT_L(0); PG8_BAR; PG8_MMA(0, 0, At, B0); PG8_MMA(0, 1, At, B1); PG8_BAR; PG8_SCHED;
;             PG8_LDA(At, 0, 1); PG8_STAGE(PG8_SB(0, 0), b2, voffB); PG8_STAGE(PG8_SB(0, 1), b2 + hstepB, voffB); PG8_STAGE(PG8_SA(0, 0), a2, voffA);
;             PG8_WAIT_V(8); PG8_WAIT_L(0); PG8_BAR; PG8_MMA(1, 0, At, B0); PG8_MMA(1, 1, At, B1); PG8_BAR; PG8_SCHED;
.LBB0_310:
	ds_read_b128 v[148:151], v254
	ds_read_b128 v[152:155], v254 offset:1024
	ds_read_b128 v[156:159], v254 offset:2048
	ds_read_b128 v[160:163], v254 offset:3072
	ds_read_b128 v[164:167], v254 offset:16384
	ds_read_b128 v[168:171], v254 offset:17408
	ds_read_b128 v[172:175], v254 offset:18432
	ds_read_b128 v[176:179], v254 offset:19456
	s_or_b32 s52, s70, 1
	s_mul_i32 s53, s45, s52
	s_mul_hi_u32 s72, s44, s52
	s_add_i32 s73, s72, s53
	s_mul_i32 s72, s44, s52
	s_add_u32 s52, s50, s48
	s_addc_u32 s53, s51, s49
	s_add_u32 s72, s21, s72
	s_addc_u32 s73, s23, s73
	s_add_i32 m0, s31, 0xc000
	ds_read_b128 v[180:183], v145
	ds_read_b128 v[184:187], v145 offset:1024
	ds_read_b128 v[188:191], v145 offset:2048
	ds_read_b128 v[192:195], v145 offset:3072
	ds_read_b128 v[196:199], v145 offset:4096
	ds_read_b128 v[200:203], v145 offset:5120
	ds_read_b128 v[204:207], v145 offset:6144
	ds_read_b128 v[208:211], v145 offset:7168
	global_load_lds_dwordx4 v128, s[72:73]
	s_add_i32 m0, s31, 0xe000
	s_nop 0
	global_load_lds_dwordx4 v132, s[72:73]
	s_waitcnt vmcnt(8)
	s_waitcnt lgkmcnt(0)
	s_barrier
	s_waitcnt lgkmcnt(0)
	v_mfma_f32_16x16x32_bf16 v[124:127], v[148:151], v[180:183], v[124:127]
	v_mfma_f32_16x16x32_bf16 v[120:123], v[156:159], v[180:183], v[120:123]
	v_mfma_f32_16x16x32_bf16 v[116:119], v[148:151], v[188:191], v[116:119]
	v_mfma_f32_16x16x32_bf16 v[112:115], v[156:159], v[188:191], v[112:115]
	v_mfma_f32_16x16x32_bf16 v[108:111], v[148:151], v[196:199], v[108:111]
	v_mfma_f32_16x16x32_bf16 v[100:103], v[156:159], v[196:199], v[100:103]
	v_mfma_f32_16x16x32_bf16 v[76:79], v[148:151], v[204:207], v[76:79]
	v_mfma_f32_16x16x32_bf16 v[72:75], v[156:159], v[204:207], v[72:75]
	v_mfma_f32_16x16x32_bf16 v[124:127], v[152:155], v[184:187], v[124:127]
	v_mfma_f32_16x16x32_bf16 v[120:123], v[160:163], v[184:187], v[120:123]
	v_mfma_f32_16x16x32_bf16 v[116:119], v[152:155], v[192:195], v[116:119]
	v_mfma_f32_16x16x32_bf16 v[112:115], v[160:163], v[192:195], v[112:115]
	v_mfma_f32_16x16x32_bf16 v[108:111], v[152:155], v[200:203], v[108:111]
	v_mfma_f32_16x16x32_bf16 v[100:103], v[160:163], v[200:203], v[100:103]
	v_mfma_f32_16x16x32_bf16 v[76:79], v[152:155], v[208:211], v[76:79]
	v_mfma_f32_16x16x32_bf16 v[72:75], v[160:163], v[208:211], v[72:75]
	v_mfma_f32_16x16x32_bf16 v[104:107], v[164:167], v[180:183], v[104:107]
	v_mfma_f32_16x16x32_bf16 v[96:99], v[172:175], v[180:183], v[96:99]
	v_mfma_f32_16x16x32_bf16 v[92:95], v[164:167], v[188:191], v[92:95]
	v_mfma_f32_16x16x32_bf16 v[88:91], v[172:175], v[188:191], v[88:91]
	v_mfma_f32_16x16x32_bf16 v[84:87], v[164:167], v[196:199], v[84:87]
	v_mfma_f32_16x16x32_bf16 v[80:83], v[172:175], v[196:199], v[80:83]
	v_mfma_f32_16x16x32_bf16 v[68:71], v[164:167], v[204:207], v[68:71]
	v_mfma_f32_16x16x32_bf16 v[64:67], v[172:175], v[204:207], v[64:67]
	v_mfma_f32_16x16x32_bf16 v[104:107], v[168:171], v[184:187], v[104:107]
	v_mfma_f32_16x16x32_bf16 v[96:99], v[176:179], v[184:187], v[96:99]
	v_mfma_f32_16x16x32_bf16 v[92:95], v[168:171], v[192:195], v[92:95]
	v_mfma_f32_16x16x32_bf16 v[88:91], v[176:179], v[192:195], v[88:91]
	v_mfma_f32_16x16x32_bf16 v[84:87], v[168:171], v[200:203], v[84:87]
	v_mfma_f32_16x16x32_bf16 v[80:83], v[176:179], v[200:203], v[80:83]
	v_mfma_f32_16x16x32_bf16 v[68:71], v[168:171], v[208:211], v[68:71]
	v_mfma_f32_16x16x32_bf16 v[64:67], v[176:179], v[208:211], v[64:67]
	s_barrier
	s_add_i32 s72, s62, s54
	s_mov_b32 m0, s72
	ds_read_b128 v[180:183], v145 offset:16384
	ds_read_b128 v[184:187], v145 offset:17408
	ds_read_b128 v[188:191], v145 offset:18432
	ds_read_b128 v[192:195], v145 offset:19456
	ds_read_b128 v[196:199], v145 offset:20480
	ds_read_b128 v[200:203], v145 offset:21504
	ds_read_b128 v[204:207], v145 offset:22528
	ds_read_b128 v[208:211], v145 offset:23552
	global_load_lds_dwordx4 v130, s[46:47]
	s_add_i32 m0, s72, 0x2000
	s_add_u32 s72, s46, 0x80000
	s_addc_u32 s73, s47, 0
	s_add_i32 s74, s63, s54
	global_load_lds_dwordx4 v134, s[46:47]
	s_mov_b32 m0, s74
	s_nop 0
	global_load_lds_dwordx4 v130, s[72:73]
	s_add_i32 m0, s74, 0x2000
	s_nop 0
	global_load_lds_dwordx4 v134, s[72:73]
	s_mov_b32 m0, s31
	s_nop 0
	global_load_lds_dwordx4 v128, s[50:51]
	s_mov_b32 m0, s55
	s_nop 0
	global_load_lds_dwordx4 v132, s[50:51]
	s_waitcnt vmcnt(8)
	s_waitcnt lgkmcnt(0)
	s_barrier
	s_waitcnt lgkmcnt(0)
	v_mfma_f32_16x16x32_bf16 v[60:63], v[148:151], v[180:183], v[60:63]
	v_mfma_f32_16x16x32_bf16 v[56:59], v[156:159], v[180:183], v[56:59]
	v_mfma_f32_16x16x32_bf16 v[48:51], v[148:151], v[188:191], v[48:51]
	v_mfma_f32_16x16x32_bf16 v[40:43], v[156:159], v[188:191], v[40:43]
	v_mfma_f32_16x16x32_bf16 v[32:35], v[148:151], v[196:199], v[32:35]
	v_mfma_f32_16x16x32_bf16 v[24:27], v[156:159], v[196:199], v[24:27]
	v_mfma_f32_16x16x32_bf16 v[16:19], v[148:151], v[204:207], v[16:19]
	v_mfma_f32_16x16x32_bf16 v[8:11], v[156:159], v[204:207], v[8:11]
	v_mfma_f32_16x16x32_bf16 v[60:63], v[152:155], v[184:187], v[60:63]
	v_mfma_f32_16x16x32_bf16 v[56:59], v[160:163], v[184:187], v[56:59]
	v_mfma_f32_16x16x32_bf16 v[48:51], v[152:155], v[192:195], v[48:51]
	v_mfma_f32_16x16x32_bf16 v[40:43], v[160:163], v[192:195], v[40:43]
	v_mfma_f32_16x16x32_bf16 v[32:35], v[152:155], v[200:203], v[32:35]
	v_mfma_f32_16x16x32_bf16 v[24:27], v[160:163], v[200:203], v[24:27]
	v_mfma_f32_16x16x32_bf16 v[16:19], v[152:155], v[208:211], v[16:19]
	v_mfma_f32_16x16x32_bf16 v[8:11], v[160:163], v[208:211], v[8:11]
	v_mfma_f32_16x16x32_bf16 v[52:55], v[164:167], v[180:183], v[52:55]
	v_mfma_f32_16x16x32_bf16 v[44:47], v[172:175], v[180:183], v[44:47]
	v_mfma_f32_16x16x32_bf16 v[36:39], v[164:167], v[188:191], v[36:39]
	v_mfma_f32_16x16x32_bf16 v[28:31], v[172:175], v[188:191], v[28:31]
	v_mfma_f32_16x16x32_bf16 v[20:23], v[164:167], v[196:199], v[20:23]
	v_mfma_f32_16x16x32_bf16 v[12:15], v[172:175], v[196:199], v[12:15]
	v_mfma_f32_16x16x32_bf16 v[4:7], v[164:167], v[204:207], v[4:7]
	v_mfma_f32_16x16x32_bf16 v[0:3], v[172:175], v[204:207], v[0:3]
	v_mfma_f32_16x16x32_bf16 v[52:55], v[168:171], v[184:187], v[52:55]
	v_mfma_f32_16x16x32_bf16 v[44:47], v[176:179], v[184:187], v[44:47]
	v_mfma_f32_16x16x32_bf16 v[36:39], v[168:171], v[192:195], v[36:39]
	v_mfma_f32_16x16x32_bf16 v[28:31], v[176:179], v[192:195], v[28:31]
	v_mfma_f32_16x16x32_bf16 v[20:23], v[168:171], v[200:203], v[20:23]
	v_mfma_f32_16x16x32_bf16 v[12:15], v[176:179], v[200:203], v[12:15]
	v_mfma_f32_16x16x32_bf16 v[4:7], v[168:171], v[208:211], v[4:7]
	v_mfma_f32_16x16x32_bf16 v[0:3], v[176:179], v[208:211], v[0:3]
	s_barrier
; #define PG8_STAGE(bufoff, gbase, voff) do { _Pragma("unroll") for (int _i = 0; _i < 2; ++_i) \
;         __builtin_amdgcn_global_load_lds((const unsigned*)((const char*)(gbase) + (voff)[_i]), (LAS unsigned*)(lds + (bufoff) + ldsw + _i * 8192), 16, 0, 0); } while (0)
; #define PG8_LDA(dst, b, h) do { _Pragma("unroll") for (int m = 0; m < 4; ++m) _Pragma("unroll") for (int k = 0; k < 2; ++k) dst[m][k] = *(const LAS bf16x8*)(lds + PG8_SA(b, h) + aoff + m * 2048 + k * 1024); } while (0)
; #define PG8_LDB(dst, b, h) do { _Pragma("unroll") for (int n = 0; n < 2; ++n) _Pragma("unroll") for (int k = 0; k < 2; ++k) dst[n][k] = *(const LAS bf16x8*)(lds + PG8_SB(b, h) + boff + n * 2048 + k * 1024); } while (0)
; #define PG8_MMA(ai, bj, At, Bt) do { __builtin_amdgcn_s_setprio(1); _Pragma("unroll") for (int m = 0; m < 4; ++m) _Pragma("unroll") for (int n = 0; n < 2; ++n) _Pragma("unroll") for (int k = 0; k < 2; ++k) \
;         acc[ai][bj][m][n] = __builtin_amdgcn_mfma_f32_16x16x32_bf16(Bt[n][k], At[m][k], acc[ai][bj][m][n], 0, 0, 0); __builtin_amdgcn_s_setprio(0); } while (0)
; #define PG8_WAIT_V(n) asm volatile("s_waitcnt vmcnt(" #n ")" ::: "memory")
; #define PG8_WAIT_L(n) asm volatile("s_waitcnt lgkmcnt(" #n ")" ::: "memory")
; #define PG8_BAR __builtin_amdgcn_s_barrier()
; #define PG8_SCHED __builtin_amdgcn_sched_barrier(0)
; template <class Epi>
; __device__ __forceinline__ void gemm_phase(LAS unsigned char* lds, const Gemm g, const StaticOrder S, const Epi E) {
;     ...
;             PG8_LDB(B0, 1, 0); PG8_LDB(B1, 1, 1); PG8_SCHED; PG8_LDA(At, 1, 0); PG8_STAGE(PG8_SA(0, 1), a2 + hstepA, voffA);
;             PG8_WAIT_V(8); PG8_WAIT_L(0); PG8_BAR; PG8_MMA(0, 0, At, B0); PG8_MMA(0, 1, At, B1); PG8_BAR; PG8_SCHED;
;             PG8_LDA(At, 1, 1); PG8_STAGE(PG8_SB(1, 0), b3, voffB); PG8_STAGE(PG8_SB(1, 1), b3 + hstepB, voffB); PG8_STAGE(PG8_SA(1, 0), a3, voffA);
;             PG8_WAIT_V(8); PG8_WAIT_L(0); PG8_BAR; PG8_MMA(1, 0, At, B0); PG8_MMA(1, 1, At, B1); PG8_BAR; PG8_SCHED;
;         }
	s_add_i32 s72, 0, 0x18000
	s_add_i32 s73, 0, 0x1c000
	ds_read_b128 v[148:151], v254 offset:32768
	ds_read_b128 v[152:155], v254 offset:33792
	ds_read_b128 v[156:159], v254 offset:34816
	ds_read_b128 v[160:163], v254 offset:35840
	ds_read_b128 v[164:167], v254 offset:49152
	ds_read_b128 v[168:171], v254 offset:50176
	ds_read_b128 v[172:175], v254 offset:51200
	ds_read_b128 v[176:179], v254 offset:52224
	s_add_u32 s50, s50, 0x80000
	s_addc_u32 s51, s51, 0
	s_mov_b32 m0, s56
	ds_read_b128 v[180:183], v145 offset:32768
	ds_read_b128 v[184:187], v145 offset:33792
	ds_read_b128 v[188:191], v145 offset:34816
	ds_read_b128 v[192:195], v145 offset:35840
	ds_read_b128 v[196:199], v145 offset:36864
	ds_read_b128 v[200:203], v145 offset:37888
	ds_read_b128 v[204:207], v145 offset:38912
	ds_read_b128 v[208:211], v145 offset:39936
	global_load_lds_dwordx4 v128, s[50:51]
	s_mov_b32 m0, s57
	s_nop 0
	global_load_lds_dwordx4 v132, s[50:51]
	s_waitcnt vmcnt(8)
	s_waitcnt lgkmcnt(0)
	s_barrier
	s_waitcnt lgkmcnt(0)
	v_mfma_f32_16x16x32_bf16 v[124:127], v[148:151], v[180:183], v[124:127]
	v_mfma_f32_16x16x32_bf16 v[120:123], v[156:159], v[180:183], v[120:123]
	v_mfma_f32_16x16x32_bf16 v[116:119], v[148:151], v[188:191], v[116:119]
	v_mfma_f32_16x16x32_bf16 v[112:115], v[156:159], v[188:191], v[112:115]
	v_mfma_f32_16x16x32_bf16 v[108:111], v[148:151], v[196:199], v[108:111]
	v_mfma_f32_16x16x32_bf16 v[100:103], v[156:159], v[196:199], v[100:103]
	v_mfma_f32_16x16x32_bf16 v[76:79], v[148:151], v[204:207], v[76:79]
	v_mfma_f32_16x16x32_bf16 v[72:75], v[156:159], v[204:207], v[72:75]
	v_mfma_f32_16x16x32_bf16 v[124:127], v[152:155], v[184:187], v[124:127]
	v_mfma_f32_16x16x32_bf16 v[120:123], v[160:163], v[184:187], v[120:123]
	v_mfma_f32_16x16x32_bf16 v[116:119], v[152:155], v[192:195], v[116:119]
	v_mfma_f32_16x16x32_bf16 v[112:115], v[160:163], v[192:195], v[112:115]
	v_mfma_f32_16x16x32_bf16 v[108:111], v[152:155], v[200:203], v[108:111]
	v_mfma_f32_16x16x32_bf16 v[100:103], v[160:163], v[200:203], v[100:103]
	v_mfma_f32_16x16x32_bf16 v[76:79], v[152:155], v[208:211], v[76:79]
	v_mfma_f32_16x16x32_bf16 v[72:75], v[160:163], v[208:211], v[72:75]
	v_mfma_f32_16x16x32_bf16 v[104:107], v[164:167], v[180:183], v[104:107]
	v_mfma_f32_16x16x32_bf16 v[96:99], v[172:175], v[180:183], v[96:99]
	v_mfma_f32_16x16x32_bf16 v[92:95], v[164:167], v[188:191], v[92:95]
	v_mfma_f32_16x16x32_bf16 v[88:91], v[172:175], v[188:191], v[88:91]
	v_mfma_f32_16x16x32_bf16 v[84:87], v[164:167], v[196:199], v[84:87]
	v_mfma_f32_16x16x32_bf16 v[80:83], v[172:175], v[196:199], v[80:83]
	v_mfma_f32_16x16x32_bf16 v[68:71], v[164:167], v[204:207], v[68:71]
	v_mfma_f32_16x16x32_bf16 v[64:67], v[172:175], v[204:207], v[64:67]
	v_mfma_f32_16x16x32_bf16 v[104:107], v[168:171], v[184:187], v[104:107]
	v_mfma_f32_16x16x32_bf16 v[96:99], v[176:179], v[184:187], v[96:99]
	v_mfma_f32_16x16x32_bf16 v[92:95], v[168:171], v[192:195], v[92:95]
	v_mfma_f32_16x16x32_bf16 v[88:91], v[176:179], v[192:195], v[88:91]
	v_mfma_f32_16x16x32_bf16 v[84:87], v[168:171], v[200:203], v[84:87]
	v_mfma_f32_16x16x32_bf16 v[80:83], v[176:179], v[200:203], v[80:83]
	v_mfma_f32_16x16x32_bf16 v[68:71], v[168:171], v[208:211], v[68:71]
	v_mfma_f32_16x16x32_bf16 v[64:67], v[176:179], v[208:211], v[64:67]
	s_barrier
	s_add_u32 s46, s46, s48
	s_addc_u32 s47, s47, s49
	s_add_i32 s48, s72, s54
	s_mov_b32 m0, s48
	ds_read_b128 v[180:183], v145 offset:49152
	ds_read_b128 v[184:187], v145 offset:50176
	ds_read_b128 v[188:191], v145 offset:51200
	ds_read_b128 v[192:195], v145 offset:52224
	ds_read_b128 v[196:199], v145 offset:53248
	ds_read_b128 v[200:203], v145 offset:54272
	ds_read_b128 v[204:207], v145 offset:55296
	ds_read_b128 v[208:211], v145 offset:56320
	global_load_lds_dwordx4 v130, s[46:47]
	s_add_i32 m0, s48, 0x2000
	s_nop 0
	global_load_lds_dwordx4 v134, s[46:47]
	s_add_u32 s46, s46, 0x80000
	s_addc_u32 s47, s47, 0
	s_add_i32 s48, s73, s54
	s_mov_b32 m0, s48
	s_nop 0
	global_load_lds_dwordx4 v130, s[46:47]
	s_add_i32 m0, s48, 0x2000
	s_nop 0
	global_load_lds_dwordx4 v134, s[46:47]
	s_mov_b32 m0, s58
	s_nop 0
	global_load_lds_dwordx4 v128, s[52:53]
	s_mov_b32 m0, s59
	s_nop 0
	global_load_lds_dwordx4 v132, s[52:53]
	s_waitcnt vmcnt(8)
	s_waitcnt lgkmcnt(0)
	s_barrier
	s_waitcnt lgkmcnt(0)
	v_mfma_f32_16x16x32_bf16 v[60:63], v[148:151], v[180:183], v[60:63]
	v_mfma_f32_16x16x32_bf16 v[56:59], v[156:159], v[180:183], v[56:59]
	v_mfma_f32_16x16x32_bf16 v[48:51], v[148:151], v[188:191], v[48:51]
	v_mfma_f32_16x16x32_bf16 v[40:43], v[156:159], v[188:191], v[40:43]
	v_mfma_f32_16x16x32_bf16 v[32:35], v[148:151], v[196:199], v[32:35]
	v_mfma_f32_16x16x32_bf16 v[24:27], v[156:159], v[196:199], v[24:27]
	v_mfma_f32_16x16x32_bf16 v[16:19], v[148:151], v[204:207], v[16:19]
	v_mfma_f32_16x16x32_bf16 v[8:11], v[156:159], v[204:207], v[8:11]
	v_mfma_f32_16x16x32_bf16 v[60:63], v[152:155], v[184:187], v[60:63]
	v_mfma_f32_16x16x32_bf16 v[56:59], v[160:163], v[184:187], v[56:59]
	v_mfma_f32_16x16x32_bf16 v[48:51], v[152:155], v[192:195], v[48:51]
	v_mfma_f32_16x16x32_bf16 v[40:43], v[160:163], v[192:195], v[40:43]
	v_mfma_f32_16x16x32_bf16 v[32:35], v[152:155], v[200:203], v[32:35]
	v_mfma_f32_16x16x32_bf16 v[24:27], v[160:163], v[200:203], v[24:27]
	v_mfma_f32_16x16x32_bf16 v[16:19], v[152:155], v[208:211], v[16:19]
	v_mfma_f32_16x16x32_bf16 v[8:11], v[160:163], v[208:211], v[8:11]
	v_mfma_f32_16x16x32_bf16 v[52:55], v[164:167], v[180:183], v[52:55]
	v_mfma_f32_16x16x32_bf16 v[44:47], v[172:175], v[180:183], v[44:47]
	v_mfma_f32_16x16x32_bf16 v[36:39], v[164:167], v[188:191], v[36:39]
	v_mfma_f32_16x16x32_bf16 v[28:31], v[172:175], v[188:191], v[28:31]
	v_mfma_f32_16x16x32_bf16 v[20:23], v[164:167], v[196:199], v[20:23]
	v_mfma_f32_16x16x32_bf16 v[12:15], v[172:175], v[196:199], v[12:15]
	v_mfma_f32_16x16x32_bf16 v[4:7], v[164:167], v[204:207], v[4:7]
	v_mfma_f32_16x16x32_bf16 v[0:3], v[172:175], v[204:207], v[0:3]
	v_mfma_f32_16x16x32_bf16 v[52:55], v[168:171], v[184:187], v[52:55]
	v_mfma_f32_16x16x32_bf16 v[44:47], v[176:179], v[184:187], v[44:47]
	v_mfma_f32_16x16x32_bf16 v[36:39], v[168:171], v[192:195], v[36:39]
	v_mfma_f32_16x16x32_bf16 v[28:31], v[176:179], v[192:195], v[28:31]
	v_mfma_f32_16x16x32_bf16 v[20:23], v[168:171], v[200:203], v[20:23]
	v_mfma_f32_16x16x32_bf16 v[12:15], v[176:179], v[200:203], v[12:15]
	v_mfma_f32_16x16x32_bf16 v[4:7], v[168:171], v[208:211], v[4:7]
	v_mfma_f32_16x16x32_bf16 v[0:3], v[176:179], v[208:211], v[0:3]
	s_barrier
	s_cmp_gt_u32 s70, 29
	s_mov_b32 s70, s71
	s_cbranch_scc1 .LBB0_315

; #define PG8_STAGE(bufoff, gbase, voff) do { _Pragma("unroll") for (int _i = 0; _i < 2; ++_i) \
;         __builtin_amdgcn_global_load_lds((const unsigned*)((const char*)(gbase) + (voff)[_i]), (LAS unsigned*)(lds + (bufoff) + ldsw + _i * 8192), 16, 0, 0); } while (0)
; #define PG8_LDA(dst, b, h) do { _Pragma("unroll") for (int m = 0; m < 4; ++m) _Pragma("unroll") for (int k = 0; k < 2; ++k) dst[m][k] = *(const LAS bf16x8*)(lds + PG8_SA(b, h) + aoff + m * 2048 + k * 1024); } while (0)
; #define PG8_LDB(dst, b, h) do { _Pragma("unroll") for (int n = 0; n < 2; ++n) _Pragma("unroll") for (int k = 0; k < 2; ++k) dst[n][k] = *(const LAS bf16x8*)(lds + PG8_SB(b, h) + boff + n * 2048 + k * 1024); } while (0)
; #define PG8_MMA(ai, bj, At, Bt) do { __builtin_amdgcn_s_setprio(1); _Pragma("unroll") for (int m = 0; m < 4; ++m) _Pragma("unroll") for (int n = 0; n < 2; ++n) _Pragma("unroll") for (int k = 0; k < 2; ++k) \
;         acc[ai][bj][m][n] = __builtin_amdgcn_mfma_f32_16x16x32_bf16(Bt[n][k], At[m][k], acc[ai][bj][m][n], 0, 0, 0); __builtin_amdgcn_s_setprio(0); } while (0)
; #define PG8_WAIT_V(n) asm volatile("s_waitcnt vmcnt(" #n ")" ::: "memory")
; #define PG8_WAIT_L(n) asm volatile("s_waitcnt lgkmcnt(" #n ")" ::: "memory")
; #define PG8_BAR __builtin_amdgcn_s_barrier()
; #define PG8_SCHED __builtin_amdgcn_sched_barrier(0)
; template <class Epi>
; __device__ __forceinline__ void gemm_phase(LAS unsigned char* lds, const Gemm g, const StaticOrder S, const Epi E) {
;     ...
;             PG8_LDB(B0, 0, 0); PG8_LDB(B1, 0, 1); PG8_SCHED; PG8_LDA(At, 0, 0); PG8_STAGE(PG8_SA(1, 1), a1 + hstepA, voffA);
;             PG8_WAIT_V(8); PG8_WAIT_L(0); PG8_BAR; PG8_MMA(0, 0, At, B0); PG8_MMA(0, 1, At, B1); PG8_BAR; PG8_SCHED;
;             PG8_LDA(At, 0, 1); PG8_STAGE(PG8_SB(0, 0), b2, voffB); PG8_STAGE(PG8_SB(0, 1), b2 + hstepB, voffB); PG8_STAGE(PG8_SA(0, 0), a2, voffA);
;             PG8_WAIT_V(8); PG8_WAIT_L(0); PG8_BAR; PG8_MMA(1, 0, At, B0); PG8_MMA(1, 1, At, B1); PG8_BAR; PG8_SCHED;
.LBB0_480:
	ds_read_b128 v[0:3], v163
	ds_read_b128 v[4:7], v163 offset:1024
	ds_read_b128 v[8:11], v163 offset:2048
	ds_read_b128 v[12:15], v163 offset:3072
	ds_read_b128 v[16:19], v164
	ds_read_b128 v[20:23], v164 offset:1024
	ds_read_b128 v[24:27], v164 offset:2048
	ds_read_b128 v[28:31], v164 offset:3072
	s_and_b64 s[34:35], s[34:35], exec
	s_movk_i32 s25, 0xff80
	s_cselect_b32 s35, -1, 0
	s_cselect_b32 s34, s25, 0x80
	s_and_b64 s[2:3], s[2:3], exec
	s_cselect_b32 s25, s35, s49
	s_cselect_b32 s27, s34, s48
	s_lshl_b64 s[2:3], s[48:49], 1
	s_add_u32 s58, s52, s2
	s_addc_u32 s59, s53, s3
	s_add_u32 s56, s50, s2
	s_addc_u32 s57, s51, s3
	s_add_u32 s54, s58, s48
	s_addc_u32 s55, s59, s49
	s_add_u32 s50, s52, s48
	s_addc_u32 s51, s53, s49
	s_add_u32 s50, s50, 0x40000
	s_addc_u32 s51, s51, 0
	s_add_i32 s74, s45, 0xc000
	s_mov_b32 m0, s74
	s_add_i32 s52, s45, 0xe000
	ds_read_b128 v[32:35], v165
	ds_read_b128 v[36:39], v165 offset:1024
	ds_read_b128 v[40:43], v165 offset:2048
	ds_read_b128 v[44:47], v165 offset:3072
	ds_read_b128 v[48:51], v165 offset:4096
	ds_read_b128 v[52:55], v165 offset:5120
	ds_read_b128 v[56:59], v165 offset:6144
	ds_read_b128 v[60:63], v165 offset:7168
	global_load_lds_dwordx4 v144, s[50:51]
	s_mov_b32 m0, s52
	s_nop 0
	global_load_lds_dwordx4 v148, s[50:51]
	s_waitcnt vmcnt(8)
	s_waitcnt lgkmcnt(0)
	s_barrier
	s_waitcnt lgkmcnt(0)
	v_mfma_f32_16x16x32_bf16 v[64:67], v[0:3], v[32:35], 0
	v_mfma_f32_16x16x32_bf16 v[68:71], v[8:11], v[32:35], 0
	v_mfma_f32_16x16x32_bf16 v[72:75], v[0:3], v[40:43], 0
	v_mfma_f32_16x16x32_bf16 v[76:79], v[8:11], v[40:43], 0
	v_mfma_f32_16x16x32_bf16 v[80:83], v[0:3], v[48:51], 0
	v_mfma_f32_16x16x32_bf16 v[84:87], v[8:11], v[48:51], 0
	v_mfma_f32_16x16x32_bf16 v[88:91], v[0:3], v[56:59], 0
	v_mfma_f32_16x16x32_bf16 v[92:95], v[8:11], v[56:59], 0
	v_mfma_f32_16x16x32_bf16 v[64:67], v[4:7], v[36:39], v[64:67]
	v_mfma_f32_16x16x32_bf16 v[68:71], v[12:15], v[36:39], v[68:71]
	v_mfma_f32_16x16x32_bf16 v[72:75], v[4:7], v[44:47], v[72:75]
	v_mfma_f32_16x16x32_bf16 v[76:79], v[12:15], v[44:47], v[76:79]
	v_mfma_f32_16x16x32_bf16 v[80:83], v[4:7], v[52:55], v[80:83]
	v_mfma_f32_16x16x32_bf16 v[84:87], v[12:15], v[52:55], v[84:87]
	v_mfma_f32_16x16x32_bf16 v[88:91], v[4:7], v[60:63], v[88:91]
	v_mfma_f32_16x16x32_bf16 v[92:95], v[12:15], v[60:63], v[92:95]
	v_mfma_f32_16x16x32_bf16 v[96:99], v[16:19], v[32:35], 0
	v_mfma_f32_16x16x32_bf16 v[32:35], v[24:27], v[32:35], 0
	v_mfma_f32_16x16x32_bf16 v[96:99], v[20:23], v[36:39], v[96:99]
	v_mfma_f32_16x16x32_bf16 v[32:35], v[28:31], v[36:39], v[32:35]
	v_mfma_f32_16x16x32_bf16 v[36:39], v[16:19], v[40:43], 0
	v_mfma_f32_16x16x32_bf16 v[40:43], v[24:27], v[40:43], 0
	v_mfma_f32_16x16x32_bf16 v[36:39], v[20:23], v[44:47], v[36:39]
	v_mfma_f32_16x16x32_bf16 v[40:43], v[28:31], v[44:47], v[40:43]
	v_mfma_f32_16x16x32_bf16 v[44:47], v[16:19], v[48:51], 0
	v_mfma_f32_16x16x32_bf16 v[48:51], v[24:27], v[48:51], 0
	v_mfma_f32_16x16x32_bf16 v[44:47], v[20:23], v[52:55], v[44:47]
	v_mfma_f32_16x16x32_bf16 v[48:51], v[28:31], v[52:55], v[48:51]
	v_mfma_f32_16x16x32_bf16 v[52:55], v[16:19], v[56:59], 0
	v_mfma_f32_16x16x32_bf16 v[56:59], v[24:27], v[56:59], 0
	v_mfma_f32_16x16x32_bf16 v[52:55], v[20:23], v[60:63], v[52:55]
	v_mfma_f32_16x16x32_bf16 v[56:59], v[28:31], v[60:63], v[56:59]
	s_barrier
	s_add_i32 s73, s66, s33
	s_add_i32 s53, s73, 0x2000
	s_mov_b32 m0, s73
	s_add_u32 s76, s56, 0x10000
	ds_read_b128 v[60:63], v165 offset:16384
	ds_read_b128 v[100:103], v165 offset:17408
	ds_read_b128 v[104:107], v165 offset:18432
	ds_read_b128 v[108:111], v165 offset:19456
	ds_read_b128 v[112:115], v165 offset:20480
	ds_read_b128 v[116:119], v165 offset:21504
	ds_read_b128 v[120:123], v165 offset:22528
	ds_read_b128 v[124:127], v165 offset:23552
	global_load_lds_dwordx4 v146, s[56:57]
	s_mov_b32 m0, s53
	s_addc_u32 s77, s57, 0
	s_add_i32 s71, s67, s33
	global_load_lds_dwordx4 v150, s[56:57]
	s_mov_b32 m0, s71
	s_add_i32 s72, s71, 0x2000
	global_load_lds_dwordx4 v146, s[76:77]
	s_mov_b32 m0, s72
	s_nop 0
	global_load_lds_dwordx4 v150, s[76:77]
	s_mov_b32 m0, s45
	s_nop 0
	global_load_lds_dwordx4 v144, s[58:59]
	s_mov_b32 m0, s47
	s_nop 0
	global_load_lds_dwordx4 v148, s[58:59]
	s_waitcnt vmcnt(8)
	s_waitcnt lgkmcnt(0)
	s_barrier
	s_waitcnt lgkmcnt(0)
	v_mfma_f32_16x16x32_bf16 v[128:131], v[0:3], v[60:63], 0
	v_mfma_f32_16x16x32_bf16 v[136:139], v[0:3], v[104:107], 0
	v_mfma_f32_16x16x32_bf16 v[156:159], v[0:3], v[112:115], 0
	v_mfma_f32_16x16x32_bf16 v[0:3], v[0:3], v[120:123], 0
	v_mfma_f32_16x16x32_bf16 v[128:131], v[4:7], v[100:103], v[128:131]
	v_mfma_f32_16x16x32_bf16 v[132:135], v[8:11], v[60:63], 0
	v_mfma_f32_16x16x32_bf16 v[136:139], v[4:7], v[108:111], v[136:139]
	v_mfma_f32_16x16x32_bf16 v[140:143], v[8:11], v[104:107], 0
	v_mfma_f32_16x16x32_bf16 v[156:159], v[4:7], v[116:119], v[156:159]
	v_mfma_f32_16x16x32_bf16 v[0:3], v[4:7], v[124:127], v[0:3]
	v_mfma_f32_16x16x32_bf16 v[4:7], v[8:11], v[120:123], 0
	v_mfma_f32_16x16x32_bf16 v[132:135], v[12:15], v[100:103], v[132:135]
	v_mfma_f32_16x16x32_bf16 v[140:143], v[12:15], v[108:111], v[140:143]
	v_mfma_f32_16x16x32_bf16 v[166:169], v[8:11], v[112:115], 0
	v_mfma_f32_16x16x32_bf16 v[4:7], v[12:15], v[124:127], v[4:7]
	v_mfma_f32_16x16x32_bf16 v[166:169], v[12:15], v[116:119], v[166:169]
	v_mfma_f32_16x16x32_bf16 v[8:11], v[16:19], v[60:63], 0
	v_mfma_f32_16x16x32_bf16 v[12:15], v[24:27], v[60:63], 0
	v_mfma_f32_16x16x32_bf16 v[8:11], v[20:23], v[100:103], v[8:11]
	v_mfma_f32_16x16x32_bf16 v[12:15], v[28:31], v[100:103], v[12:15]
	v_mfma_f32_16x16x32_bf16 v[60:63], v[16:19], v[104:107], 0
	v_mfma_f32_16x16x32_bf16 v[100:103], v[24:27], v[104:107], 0
	v_mfma_f32_16x16x32_bf16 v[104:107], v[16:19], v[112:115], 0
	v_mfma_f32_16x16x32_bf16 v[16:19], v[16:19], v[120:123], 0
	v_mfma_f32_16x16x32_bf16 v[60:63], v[20:23], v[108:111], v[60:63]
	v_mfma_f32_16x16x32_bf16 v[100:103], v[28:31], v[108:111], v[100:103]
	v_mfma_f32_16x16x32_bf16 v[104:107], v[20:23], v[116:119], v[104:107]
	v_mfma_f32_16x16x32_bf16 v[108:111], v[24:27], v[112:115], 0
	v_mfma_f32_16x16x32_bf16 v[16:19], v[20:23], v[124:127], v[16:19]
	v_mfma_f32_16x16x32_bf16 v[20:23], v[24:27], v[120:123], 0
	v_mfma_f32_16x16x32_bf16 v[108:111], v[28:31], v[116:119], v[108:111]
	v_mfma_f32_16x16x32_bf16 v[20:23], v[28:31], v[124:127], v[20:23]
	s_barrier
; #define PG8_STAGE(bufoff, gbase, voff) do { _Pragma("unroll") for (int _i = 0; _i < 2; ++_i) \
;         __builtin_amdgcn_global_load_lds((const unsigned*)((const char*)(gbase) + (voff)[_i]), (LAS unsigned*)(lds + (bufoff) + ldsw + _i * 8192), 16, 0, 0); } while (0)
; #define PG8_LDA(dst, b, h) do { _Pragma("unroll") for (int m = 0; m < 4; ++m) _Pragma("unroll") for (int k = 0; k < 2; ++k) dst[m][k] = *(const LAS bf16x8*)(lds + PG8_SA(b, h) + aoff + m * 2048 + k * 1024); } while (0)
; #define PG8_LDB(dst, b, h) do { _Pragma("unroll") for (int n = 0; n < 2; ++n) _Pragma("unroll") for (int k = 0; k < 2; ++k) dst[n][k] = *(const LAS bf16x8*)(lds + PG8_SB(b, h) + boff + n * 2048 + k * 1024); } while (0)
; #define PG8_MMA(ai, bj, At, Bt) do { __builtin_amdgcn_s_setprio(1); _Pragma("unroll") for (int m = 0; m < 4; ++m) _Pragma("unroll") for (int n = 0; n < 2; ++n) _Pragma("unroll") for (int k = 0; k < 2; ++k) \
;         acc[ai][bj][m][n] = __builtin_amdgcn_mfma_f32_16x16x32_bf16(Bt[n][k], At[m][k], acc[ai][bj][m][n], 0, 0, 0); __builtin_amdgcn_s_setprio(0); } while (0)
; #define PG8_WAIT_V(n) asm volatile("s_waitcnt vmcnt(" #n ")" ::: "memory")
; #define PG8_WAIT_L(n) asm volatile("s_waitcnt lgkmcnt(" #n ")" ::: "memory")
; #define PG8_BAR __builtin_amdgcn_s_barrier()
; #define PG8_SCHED __builtin_amdgcn_sched_barrier(0)
; template <class Epi>
; __device__ __forceinline__ void gemm_phase(LAS unsigned char* lds, const Gemm g, const StaticOrder S, const Epi E) {
;     ...
;             PG8_LDB(B0, 1, 0); PG8_LDB(B1, 1, 1); PG8_SCHED; PG8_LDA(At, 1, 0); PG8_STAGE(PG8_SA(0, 1), a2 + hstepA, voffA);
;             PG8_WAIT_V(8); PG8_WAIT_L(0); PG8_BAR; PG8_MMA(0, 0, At, B0); PG8_MMA(0, 1, At, B1); PG8_BAR; PG8_SCHED;
;             PG8_LDA(At, 1, 1); PG8_STAGE(PG8_SB(1, 0), b3, voffB); PG8_STAGE(PG8_SB(1, 1), b3 + hstepB, voffB); PG8_STAGE(PG8_SA(1, 0), a3, voffA);
;             PG8_WAIT_V(8); PG8_WAIT_L(0); PG8_BAR; PG8_MMA(1, 0, At, B0); PG8_MMA(1, 1, At, B1); PG8_BAR; PG8_SCHED;
	s_add_i32 s75, 0, 0x18000
	s_add_i32 s76, 0, 0x1c000
	v_add_u32_e32 v222, s75, v161
	v_add_u32_e32 v223, s76, v161
	ds_read_b128 v[24:27], v222
	ds_read_b128 v[28:31], v222 offset:1024
	ds_read_b128 v[112:115], v222 offset:2048
	ds_read_b128 v[116:119], v222 offset:3072
	ds_read_b128 v[120:123], v223
	ds_read_b128 v[124:127], v223 offset:1024
	ds_read_b128 v[170:173], v223 offset:2048
	ds_read_b128 v[174:177], v223 offset:3072
	s_add_u32 s58, s58, 0x40000
	s_addc_u32 s59, s59, 0
	s_mov_b32 m0, s60
	ds_read_b128 v[178:181], v165 offset:32768
	ds_read_b128 v[182:185], v165 offset:33792
	ds_read_b128 v[186:189], v165 offset:34816
	ds_read_b128 v[190:193], v165 offset:35840
	ds_read_b128 v[194:197], v165 offset:36864
	ds_read_b128 v[198:201], v165 offset:37888
	ds_read_b128 v[202:205], v165 offset:38912
	ds_read_b128 v[206:209], v165 offset:39936
	global_load_lds_dwordx4 v144, s[58:59]
	s_mov_b32 m0, s61
	s_nop 0
	global_load_lds_dwordx4 v148, s[58:59]
	s_waitcnt vmcnt(8)
	s_waitcnt lgkmcnt(0)
	s_barrier
	s_waitcnt lgkmcnt(0)
	v_mfma_f32_16x16x32_bf16 v[64:67], v[24:27], v[178:181], v[64:67]
	v_mfma_f32_16x16x32_bf16 v[68:71], v[112:115], v[178:181], v[68:71]
	v_mfma_f32_16x16x32_bf16 v[72:75], v[24:27], v[186:189], v[72:75]
	v_mfma_f32_16x16x32_bf16 v[76:79], v[112:115], v[186:189], v[76:79]
	v_mfma_f32_16x16x32_bf16 v[80:83], v[24:27], v[194:197], v[80:83]
	v_mfma_f32_16x16x32_bf16 v[84:87], v[112:115], v[194:197], v[84:87]
	v_mfma_f32_16x16x32_bf16 v[88:91], v[24:27], v[202:205], v[88:91]
	v_mfma_f32_16x16x32_bf16 v[92:95], v[112:115], v[202:205], v[92:95]
	v_mfma_f32_16x16x32_bf16 v[64:67], v[28:31], v[182:185], v[64:67]
	v_mfma_f32_16x16x32_bf16 v[68:71], v[116:119], v[182:185], v[68:71]
	v_mfma_f32_16x16x32_bf16 v[72:75], v[28:31], v[190:193], v[72:75]
	v_mfma_f32_16x16x32_bf16 v[76:79], v[116:119], v[190:193], v[76:79]
	v_mfma_f32_16x16x32_bf16 v[80:83], v[28:31], v[198:201], v[80:83]
	v_mfma_f32_16x16x32_bf16 v[84:87], v[116:119], v[198:201], v[84:87]
	v_mfma_f32_16x16x32_bf16 v[88:91], v[28:31], v[206:209], v[88:91]
	v_mfma_f32_16x16x32_bf16 v[92:95], v[116:119], v[206:209], v[92:95]
	v_mfma_f32_16x16x32_bf16 v[96:99], v[120:123], v[178:181], v[96:99]
	v_mfma_f32_16x16x32_bf16 v[32:35], v[170:173], v[178:181], v[32:35]
	v_mfma_f32_16x16x32_bf16 v[36:39], v[120:123], v[186:189], v[36:39]
	v_mfma_f32_16x16x32_bf16 v[48:51], v[170:173], v[194:197], v[48:51]
	v_mfma_f32_16x16x32_bf16 v[52:55], v[120:123], v[202:205], v[52:55]
	v_mfma_f32_16x16x32_bf16 v[56:59], v[170:173], v[202:205], v[56:59]
	v_mfma_f32_16x16x32_bf16 v[96:99], v[124:127], v[182:185], v[96:99]
	v_mfma_f32_16x16x32_bf16 v[32:35], v[174:177], v[182:185], v[32:35]
	v_mfma_f32_16x16x32_bf16 v[36:39], v[124:127], v[190:193], v[36:39]
	v_mfma_f32_16x16x32_bf16 v[40:43], v[170:173], v[186:189], v[40:43]
	v_mfma_f32_16x16x32_bf16 v[44:47], v[120:123], v[194:197], v[44:47]
	v_mfma_f32_16x16x32_bf16 v[48:51], v[174:177], v[198:201], v[48:51]
	v_mfma_f32_16x16x32_bf16 v[52:55], v[124:127], v[206:209], v[52:55]
	v_mfma_f32_16x16x32_bf16 v[56:59], v[174:177], v[206:209], v[56:59]
	v_mfma_f32_16x16x32_bf16 v[40:43], v[174:177], v[190:193], v[40:43]
	v_mfma_f32_16x16x32_bf16 v[44:47], v[124:127], v[198:201], v[44:47]
	s_barrier
	s_add_u32 s48, s56, s48
	s_addc_u32 s49, s57, s49
	s_add_i32 s59, s75, s33
	s_mov_b32 m0, s59
	s_add_i32 s56, s59, 0x2000
	ds_read_b128 v[178:181], v165 offset:49152
	ds_read_b128 v[182:185], v165 offset:50176
	ds_read_b128 v[186:189], v165 offset:51200
	ds_read_b128 v[190:193], v165 offset:52224
	ds_read_b128 v[194:197], v165 offset:53248
	ds_read_b128 v[198:201], v165 offset:54272
	ds_read_b128 v[202:205], v165 offset:55296
	ds_read_b128 v[206:209], v165 offset:56320
	global_load_lds_dwordx4 v146, s[48:49]
	v_lshl_add_u64 v[210:211], s[48:49], 0, v[150:151]
	s_add_u32 s48, s48, 0x10000
	s_mov_b32 m0, s56
	s_addc_u32 s49, s49, 0
	s_add_i32 s57, s76, s33
	global_load_lds_dwordx4 v[210:211], off
	s_mov_b32 m0, s57
	s_add_i32 s58, s57, 0x2000
	global_load_lds_dwordx4 v146, s[48:49]
	s_mov_b32 m0, s58
	s_nop 0
	global_load_lds_dwordx4 v150, s[48:49]
	s_mov_b32 m0, s63
	s_nop 0
	global_load_lds_dwordx4 v144, s[54:55]
	s_mov_b32 m0, s64
	s_nop 0
	global_load_lds_dwordx4 v148, s[54:55]
	s_waitcnt vmcnt(8)
	s_waitcnt lgkmcnt(0)
	s_barrier
	s_waitcnt lgkmcnt(0)
	v_mfma_f32_16x16x32_bf16 v[128:131], v[24:27], v[178:181], v[128:131]
	v_mfma_f32_16x16x32_bf16 v[132:135], v[112:115], v[178:181], v[132:135]
	v_mfma_f32_16x16x32_bf16 v[136:139], v[24:27], v[186:189], v[136:139]
	v_mfma_f32_16x16x32_bf16 v[140:143], v[112:115], v[186:189], v[140:143]
	v_mfma_f32_16x16x32_bf16 v[0:3], v[24:27], v[202:205], v[0:3]
	v_mfma_f32_16x16x32_bf16 v[4:7], v[112:115], v[202:205], v[4:7]
	v_mfma_f32_16x16x32_bf16 v[128:131], v[28:31], v[182:185], v[128:131]
	v_mfma_f32_16x16x32_bf16 v[132:135], v[116:119], v[182:185], v[132:135]
	v_mfma_f32_16x16x32_bf16 v[136:139], v[28:31], v[190:193], v[136:139]
	v_mfma_f32_16x16x32_bf16 v[140:143], v[116:119], v[190:193], v[140:143]
	v_mfma_f32_16x16x32_bf16 v[156:159], v[24:27], v[194:197], v[156:159]
	v_mfma_f32_16x16x32_bf16 v[166:169], v[112:115], v[194:197], v[166:169]
	v_mfma_f32_16x16x32_bf16 v[0:3], v[28:31], v[206:209], v[0:3]
	v_mfma_f32_16x16x32_bf16 v[4:7], v[116:119], v[206:209], v[4:7]
	v_mfma_f32_16x16x32_bf16 v[156:159], v[28:31], v[198:201], v[156:159]
	v_mfma_f32_16x16x32_bf16 v[166:169], v[116:119], v[198:201], v[166:169]
	v_mfma_f32_16x16x32_bf16 v[8:11], v[120:123], v[178:181], v[8:11]
	v_mfma_f32_16x16x32_bf16 v[12:15], v[170:173], v[178:181], v[12:15]
	v_mfma_f32_16x16x32_bf16 v[24:27], v[120:123], v[186:189], v[60:63]
	v_mfma_f32_16x16x32_bf16 v[28:31], v[170:173], v[186:189], v[100:103]
	v_mfma_f32_16x16x32_bf16 v[60:63], v[120:123], v[194:197], v[104:107]
	v_mfma_f32_16x16x32_bf16 v[100:103], v[170:173], v[194:197], v[108:111]
	v_mfma_f32_16x16x32_bf16 v[20:23], v[170:173], v[202:205], v[20:23]
	v_mfma_f32_16x16x32_bf16 v[8:11], v[124:127], v[182:185], v[8:11]
	v_mfma_f32_16x16x32_bf16 v[12:15], v[174:177], v[182:185], v[12:15]
	v_mfma_f32_16x16x32_bf16 v[24:27], v[124:127], v[190:193], v[24:27]
	v_mfma_f32_16x16x32_bf16 v[60:63], v[124:127], v[198:201], v[60:63]
	v_mfma_f32_16x16x32_bf16 v[100:103], v[174:177], v[198:201], v[100:103]
	v_mfma_f32_16x16x32_bf16 v[16:19], v[120:123], v[202:205], v[16:19]
	v_mfma_f32_16x16x32_bf16 v[20:23], v[174:177], v[206:209], v[20:23]
	v_mfma_f32_16x16x32_bf16 v[28:31], v[174:177], v[190:193], v[28:31]
	v_mfma_f32_16x16x32_bf16 v[16:19], v[124:127], v[206:209], v[16:19]
	s_barrier
; #define PG8_STAGE(bufoff, gbase, voff) do { _Pragma("unroll") for (int _i = 0; _i < 2; ++_i) \
;         __builtin_amdgcn_global_load_lds((const unsigned*)((const char*)(gbase) + (voff)[_i]), (LAS unsigned*)(lds + (bufoff) + ldsw + _i * 8192), 16, 0, 0); } while (0)
; #define PG8_LDA(dst, b, h) do { _Pragma("unroll") for (int m = 0; m < 4; ++m) _Pragma("unroll") for (int k = 0; k < 2; ++k) dst[m][k] = *(const LAS bf16x8*)(lds + PG8_SA(b, h) + aoff + m * 2048 + k * 1024); } while (0)
; #define PG8_LDB(dst, b, h) do { _Pragma("unroll") for (int n = 0; n < 2; ++n) _Pragma("unroll") for (int k = 0; k < 2; ++k) dst[n][k] = *(const LAS bf16x8*)(lds + PG8_SB(b, h) + boff + n * 2048 + k * 1024); } while (0)
; #define PG8_MMA(ai, bj, At, Bt) do { __builtin_amdgcn_s_setprio(1); _Pragma("unroll") for (int m = 0; m < 4; ++m) _Pragma("unroll") for (int n = 0; n < 2; ++n) _Pragma("unroll") for (int k = 0; k < 2; ++k) \
;         acc[ai][bj][m][n] = __builtin_amdgcn_mfma_f32_16x16x32_bf16(Bt[n][k], At[m][k], acc[ai][bj][m][n], 0, 0, 0); __builtin_amdgcn_s_setprio(0); } while (0)
; #define PG8_WAIT_V(n) asm volatile("s_waitcnt vmcnt(" #n ")" ::: "memory")
; #define PG8_WAIT_L(n) asm volatile("s_waitcnt lgkmcnt(" #n ")" ::: "memory")
; #define PG8_BAR __builtin_amdgcn_s_barrier()
; #define PG8_SCHED __builtin_amdgcn_sched_barrier(0)
; template <class Epi>
; __device__ __forceinline__ void gemm_phase(LAS unsigned char* lds, const Gemm g, const StaticOrder S, const Epi E) {
;     ...
;             PG8_LDB(B0, 0, 0); PG8_LDB(B1, 0, 1); PG8_SCHED; PG8_LDA(At, 0, 0); PG8_STAGE(PG8_SA(1, 1), a1 + hstepA, voffA);
;             PG8_WAIT_V(8); PG8_WAIT_L(0); PG8_BAR; PG8_MMA(0, 0, At, B0); PG8_MMA(0, 1, At, B1); PG8_BAR; PG8_SCHED;
;             PG8_LDA(At, 0, 1); PG8_STAGE(PG8_SB(0, 0), b2, voffB); PG8_STAGE(PG8_SB(0, 1), b2 + hstepB, voffB); PG8_STAGE(PG8_SA(0, 0), a2, voffA);
;             PG8_WAIT_V(8); PG8_WAIT_L(0); PG8_BAR; PG8_MMA(1, 0, At, B0); PG8_MMA(1, 1, At, B1); PG8_BAR; PG8_SCHED;
	ds_read_b128 v[104:107], v163
	ds_read_b128 v[108:111], v163 offset:1024
	ds_read_b128 v[112:115], v163 offset:2048
	ds_read_b128 v[116:119], v163 offset:3072
	ds_read_b128 v[120:123], v164
	ds_read_b128 v[124:127], v164 offset:1024
	ds_read_b128 v[170:173], v164 offset:2048
	ds_read_b128 v[174:177], v164 offset:3072
	s_add_u32 s48, s28, s27
	s_addc_u32 s49, s29, s25
	s_add_u32 s2, s50, s2
	s_addc_u32 s3, s51, s3
	s_mov_b32 m0, s74
	ds_read_b128 v[178:181], v165
	ds_read_b128 v[182:185], v165 offset:1024
	ds_read_b128 v[186:189], v165 offset:2048
	ds_read_b128 v[190:193], v165 offset:3072
	ds_read_b128 v[194:197], v165 offset:4096
	ds_read_b128 v[198:201], v165 offset:5120
	ds_read_b128 v[202:205], v165 offset:6144
	ds_read_b128 v[206:209], v165 offset:7168
	global_load_lds_dwordx4 v144, s[2:3]
	s_mov_b32 m0, s52
	s_nop 0
	global_load_lds_dwordx4 v148, s[2:3]
	s_waitcnt vmcnt(8)
	s_waitcnt lgkmcnt(0)
	s_barrier
	s_waitcnt lgkmcnt(0)
	v_mfma_f32_16x16x32_bf16 v[64:67], v[104:107], v[178:181], v[64:67]
	v_mfma_f32_16x16x32_bf16 v[68:71], v[112:115], v[178:181], v[68:71]
	v_mfma_f32_16x16x32_bf16 v[72:75], v[104:107], v[186:189], v[72:75]
	v_mfma_f32_16x16x32_bf16 v[76:79], v[112:115], v[186:189], v[76:79]
	v_mfma_f32_16x16x32_bf16 v[80:83], v[104:107], v[194:197], v[80:83]
	v_mfma_f32_16x16x32_bf16 v[84:87], v[112:115], v[194:197], v[84:87]
	v_mfma_f32_16x16x32_bf16 v[88:91], v[104:107], v[202:205], v[88:91]
	v_mfma_f32_16x16x32_bf16 v[92:95], v[112:115], v[202:205], v[92:95]
	v_mfma_f32_16x16x32_bf16 v[64:67], v[108:111], v[182:185], v[64:67]
	v_mfma_f32_16x16x32_bf16 v[68:71], v[116:119], v[182:185], v[68:71]
	v_mfma_f32_16x16x32_bf16 v[72:75], v[108:111], v[190:193], v[72:75]
	v_mfma_f32_16x16x32_bf16 v[76:79], v[116:119], v[190:193], v[76:79]
	v_mfma_f32_16x16x32_bf16 v[80:83], v[108:111], v[198:201], v[80:83]
	v_mfma_f32_16x16x32_bf16 v[84:87], v[116:119], v[198:201], v[84:87]
	v_mfma_f32_16x16x32_bf16 v[88:91], v[108:111], v[206:209], v[88:91]
	v_mfma_f32_16x16x32_bf16 v[92:95], v[116:119], v[206:209], v[92:95]
	v_mfma_f32_16x16x32_bf16 v[96:99], v[120:123], v[178:181], v[96:99]
	v_mfma_f32_16x16x32_bf16 v[32:35], v[170:173], v[178:181], v[32:35]
	v_mfma_f32_16x16x32_bf16 v[36:39], v[120:123], v[186:189], v[36:39]
	v_mfma_f32_16x16x32_bf16 v[48:51], v[170:173], v[194:197], v[48:51]
	v_mfma_f32_16x16x32_bf16 v[52:55], v[120:123], v[202:205], v[52:55]
	v_mfma_f32_16x16x32_bf16 v[56:59], v[170:173], v[202:205], v[56:59]
	v_mfma_f32_16x16x32_bf16 v[96:99], v[124:127], v[182:185], v[96:99]
	v_mfma_f32_16x16x32_bf16 v[32:35], v[174:177], v[182:185], v[32:35]
	v_mfma_f32_16x16x32_bf16 v[36:39], v[124:127], v[190:193], v[36:39]
	v_mfma_f32_16x16x32_bf16 v[40:43], v[170:173], v[186:189], v[40:43]
	v_mfma_f32_16x16x32_bf16 v[44:47], v[120:123], v[194:197], v[44:47]
	v_mfma_f32_16x16x32_bf16 v[48:51], v[174:177], v[198:201], v[48:51]
	v_mfma_f32_16x16x32_bf16 v[52:55], v[124:127], v[206:209], v[52:55]
	v_mfma_f32_16x16x32_bf16 v[56:59], v[174:177], v[206:209], v[56:59]
	v_mfma_f32_16x16x32_bf16 v[40:43], v[174:177], v[190:193], v[40:43]
	v_mfma_f32_16x16x32_bf16 v[44:47], v[124:127], v[198:201], v[44:47]
	s_barrier
	s_mov_b32 m0, s73
	s_add_u32 s2, s30, 0x10000
	ds_read_b128 v[178:181], v165 offset:16384
	ds_read_b128 v[182:185], v165 offset:17408
	ds_read_b128 v[186:189], v165 offset:18432
	ds_read_b128 v[190:193], v165 offset:19456
	ds_read_b128 v[194:197], v165 offset:20480
	ds_read_b128 v[198:201], v165 offset:21504
	ds_read_b128 v[202:205], v165 offset:22528
	ds_read_b128 v[206:209], v165 offset:23552
	global_load_lds_dwordx4 v146, s[30:31]
	s_mov_b32 m0, s53
	s_addc_u32 s3, s31, 0
	global_load_lds_dwordx4 v150, s[30:31]
	s_mov_b32 m0, s71
	s_nop 0
	global_load_lds_dwordx4 v146, s[2:3]
	s_mov_b32 m0, s72
	s_nop 0
	global_load_lds_dwordx4 v150, s[2:3]
	s_mov_b32 m0, s45
	s_nop 0
	global_load_lds_dwordx4 v144, s[28:29]
	s_mov_b32 m0, s47
	s_nop 0
	global_load_lds_dwordx4 v148, s[28:29]
	s_waitcnt vmcnt(8)
	s_waitcnt lgkmcnt(0)
	s_barrier
	s_waitcnt lgkmcnt(0)
	v_mfma_f32_16x16x32_bf16 v[128:131], v[104:107], v[178:181], v[128:131]
	v_mfma_f32_16x16x32_bf16 v[210:213], v[108:111], v[182:185], v[128:131]
	v_mfma_f32_16x16x32_bf16 v[128:131], v[112:115], v[178:181], v[132:135]
	v_mfma_f32_16x16x32_bf16 v[214:217], v[116:119], v[182:185], v[128:131]
	v_mfma_f32_16x16x32_bf16 v[128:131], v[104:107], v[186:189], v[136:139]
	v_mfma_f32_16x16x32_bf16 v[218:221], v[108:111], v[190:193], v[128:131]
	v_mfma_f32_16x16x32_bf16 v[128:131], v[112:115], v[186:189], v[140:143]
	v_mfma_f32_16x16x32_bf16 v[226:229], v[116:119], v[190:193], v[128:131]
	v_mfma_f32_16x16x32_bf16 v[128:131], v[104:107], v[194:197], v[156:159]
	v_mfma_f32_16x16x32_bf16 v[0:3], v[104:107], v[202:205], v[0:3]
	v_mfma_f32_16x16x32_bf16 v[4:7], v[112:115], v[202:205], v[4:7]
	v_mfma_f32_16x16x32_bf16 v[156:159], v[108:111], v[198:201], v[128:131]
	v_mfma_f32_16x16x32_bf16 v[128:131], v[112:115], v[194:197], v[166:169]
	v_mfma_f32_16x16x32_bf16 v[0:3], v[108:111], v[206:209], v[0:3]
	v_mfma_f32_16x16x32_bf16 v[4:7], v[116:119], v[206:209], v[4:7]
	v_mfma_f32_16x16x32_bf16 v[166:169], v[116:119], v[198:201], v[128:131]
	v_mfma_f32_16x16x32_bf16 v[8:11], v[120:123], v[178:181], v[8:11]
	v_mfma_f32_16x16x32_bf16 v[230:233], v[124:127], v[182:185], v[8:11]
	v_mfma_f32_16x16x32_bf16 v[8:11], v[170:173], v[178:181], v[12:15]
	v_mfma_f32_16x16x32_bf16 v[178:181], v[174:177], v[182:185], v[8:11]
	v_mfma_f32_16x16x32_bf16 v[8:11], v[120:123], v[186:189], v[24:27]
	v_mfma_f32_16x16x32_bf16 v[24:27], v[124:127], v[190:193], v[8:11]
	v_mfma_f32_16x16x32_bf16 v[8:11], v[170:173], v[186:189], v[28:31]
	v_mfma_f32_16x16x32_bf16 v[28:31], v[174:177], v[190:193], v[8:11]
	v_mfma_f32_16x16x32_bf16 v[8:11], v[120:123], v[194:197], v[60:63]
	v_mfma_f32_16x16x32_bf16 v[182:185], v[124:127], v[198:201], v[8:11]
	v_mfma_f32_16x16x32_bf16 v[8:11], v[170:173], v[194:197], v[100:103]
	v_mfma_f32_16x16x32_bf16 v[186:189], v[174:177], v[198:201], v[8:11]
	v_mfma_f32_16x16x32_bf16 v[8:11], v[120:123], v[202:205], v[16:19]
	v_mfma_f32_16x16x32_bf16 v[16:19], v[124:127], v[206:209], v[8:11]
	v_mfma_f32_16x16x32_bf16 v[8:11], v[170:173], v[202:205], v[20:23]
	v_mfma_f32_16x16x32_bf16 v[170:173], v[174:177], v[206:209], v[8:11]
	s_barrier
; #define PG8_STAGE(bufoff, gbase, voff) do { _Pragma("unroll") for (int _i = 0; _i < 2; ++_i) \
;         __builtin_amdgcn_global_load_lds((const unsigned*)((const char*)(gbase) + (voff)[_i]), (LAS unsigned*)(lds + (bufoff) + ldsw + _i * 8192), 16, 0, 0); } while (0)
; #define PG8_LDA(dst, b, h) do { _Pragma("unroll") for (int m = 0; m < 4; ++m) _Pragma("unroll") for (int k = 0; k < 2; ++k) dst[m][k] = *(const LAS bf16x8*)(lds + PG8_SA(b, h) + aoff + m * 2048 + k * 1024); } while (0)
; #define PG8_LDB(dst, b, h) do { _Pragma("unroll") for (int n = 0; n < 2; ++n) _Pragma("unroll") for (int k = 0; k < 2; ++k) dst[n][k] = *(const LAS bf16x8*)(lds + PG8_SB(b, h) + boff + n * 2048 + k * 1024); } while (0)
; #define PG8_MMA(ai, bj, At, Bt) do { __builtin_amdgcn_s_setprio(1); _Pragma("unroll") for (int m = 0; m < 4; ++m) _Pragma("unroll") for (int n = 0; n < 2; ++n) _Pragma("unroll") for (int k = 0; k < 2; ++k) \
;         acc[ai][bj][m][n] = __builtin_amdgcn_mfma_f32_16x16x32_bf16(Bt[n][k], At[m][k], acc[ai][bj][m][n], 0, 0, 0); __builtin_amdgcn_s_setprio(0); } while (0)
; #define PG8_WAIT_V(n) asm volatile("s_waitcnt vmcnt(" #n ")" ::: "memory")
; #define PG8_WAIT_L(n) asm volatile("s_waitcnt lgkmcnt(" #n ")" ::: "memory")
; #define PG8_BAR __builtin_amdgcn_s_barrier()
; #define PG8_SCHED __builtin_amdgcn_sched_barrier(0)
; template <class Epi>
; __device__ __forceinline__ void gemm_phase(LAS unsigned char* lds, const Gemm g, const StaticOrder S, const Epi E) {
;     ...
;             PG8_LDB(B0, 1, 0); PG8_LDB(B1, 1, 1); PG8_SCHED; PG8_LDA(At, 1, 0); PG8_STAGE(PG8_SA(0, 1), a2 + hstepA, voffA);
;             PG8_WAIT_V(8); PG8_WAIT_L(0); PG8_BAR; PG8_MMA(0, 0, At, B0); PG8_MMA(0, 1, At, B1); PG8_BAR; PG8_SCHED;
;             PG8_LDA(At, 1, 1); PG8_STAGE(PG8_SB(1, 0), b3, voffB); PG8_STAGE(PG8_SB(1, 1), b3 + hstepB, voffB); PG8_STAGE(PG8_SA(1, 0), a3, voffA);
;             PG8_WAIT_V(8); PG8_WAIT_L(0); PG8_BAR; PG8_MMA(1, 0, At, B0); PG8_MMA(1, 1, At, B1); PG8_BAR; PG8_SCHED;
;         }
;         if (wr == 0) PG8_BAR;
	s_nop 4
	ds_read_b128 v[8:11], v222
	ds_read_b128 v[12:15], v222 offset:1024
	ds_read_b128 v[20:23], v222 offset:2048
	ds_read_b128 v[174:177], v222 offset:3072
	ds_read_b128 v[190:193], v223
	ds_read_b128 v[194:197], v223 offset:1024
	ds_read_b128 v[198:201], v223 offset:2048
	ds_read_b128 v[202:205], v223 offset:3072
	s_add_u32 s2, s28, 0x40000
	s_addc_u32 s3, s29, 0
	s_mov_b32 m0, s60
	ds_read_b128 v[60:63], v165 offset:32768
	ds_read_b128 v[100:103], v165 offset:33792
	ds_read_b128 v[112:115], v165 offset:34816
	ds_read_b128 v[206:209], v165 offset:35840
	ds_read_b128 v[234:237], v165 offset:36864
	ds_read_b128 v[238:241], v165 offset:37888
	ds_read_b128 v[242:245], v165 offset:38912
	ds_read_b128 v[246:249], v165 offset:39936
	global_load_lds_dwordx4 v144, s[2:3]
	s_mov_b32 m0, s61
	s_nop 0
	global_load_lds_dwordx4 v148, s[2:3]
	s_waitcnt vmcnt(8)
	s_waitcnt lgkmcnt(0)
	s_barrier
	s_waitcnt lgkmcnt(0)
	v_mfma_f32_16x16x32_bf16 v[64:67], v[8:11], v[60:63], v[64:67]
	v_mfma_f32_16x16x32_bf16 v[140:143], v[12:15], v[100:103], v[64:67]
	v_mfma_f32_16x16x32_bf16 v[64:67], v[20:23], v[60:63], v[68:71]
	v_mfma_f32_16x16x32_bf16 v[136:139], v[174:177], v[100:103], v[64:67]
	v_mfma_f32_16x16x32_bf16 v[64:67], v[8:11], v[112:115], v[72:75]
	v_mfma_f32_16x16x32_bf16 v[124:127], v[12:15], v[206:209], v[64:67]
	v_mfma_f32_16x16x32_bf16 v[64:67], v[20:23], v[112:115], v[76:79]
	v_mfma_f32_16x16x32_bf16 v[120:123], v[174:177], v[206:209], v[64:67]
	v_mfma_f32_16x16x32_bf16 v[64:67], v[8:11], v[234:237], v[80:83]
	v_mfma_f32_16x16x32_bf16 v[108:111], v[12:15], v[238:241], v[64:67]
	v_mfma_f32_16x16x32_bf16 v[64:67], v[20:23], v[234:237], v[84:87]
	v_mfma_f32_16x16x32_bf16 v[104:107], v[174:177], v[238:241], v[64:67]
	v_mfma_f32_16x16x32_bf16 v[64:67], v[8:11], v[242:245], v[88:91]
	v_mfma_f32_16x16x32_bf16 v[80:83], v[12:15], v[246:249], v[64:67]
	v_mfma_f32_16x16x32_bf16 v[64:67], v[20:23], v[242:245], v[92:95]
	v_mfma_f32_16x16x32_bf16 v[72:75], v[174:177], v[246:249], v[64:67]
	v_mfma_f32_16x16x32_bf16 v[32:35], v[198:201], v[60:63], v[32:35]
	v_mfma_f32_16x16x32_bf16 v[128:131], v[202:205], v[100:103], v[32:35]
	v_mfma_f32_16x16x32_bf16 v[32:35], v[190:193], v[112:115], v[36:39]
	v_mfma_f32_16x16x32_bf16 v[116:119], v[194:197], v[206:209], v[32:35]
	v_mfma_f32_16x16x32_bf16 v[32:35], v[198:201], v[112:115], v[40:43]
	v_mfma_f32_16x16x32_bf16 v[64:67], v[190:193], v[60:63], v[96:99]
	v_mfma_f32_16x16x32_bf16 v[112:115], v[202:205], v[206:209], v[32:35]
	v_mfma_f32_16x16x32_bf16 v[32:35], v[190:193], v[234:237], v[44:47]
	v_mfma_f32_16x16x32_bf16 v[132:135], v[194:197], v[100:103], v[64:67]
	v_mfma_f32_16x16x32_bf16 v[100:103], v[194:197], v[238:241], v[32:35]
	v_mfma_f32_16x16x32_bf16 v[32:35], v[198:201], v[234:237], v[48:51]
	v_mfma_f32_16x16x32_bf16 v[96:99], v[202:205], v[238:241], v[32:35]
	v_mfma_f32_16x16x32_bf16 v[32:35], v[190:193], v[242:245], v[52:55]
	v_mfma_f32_16x16x32_bf16 v[68:71], v[194:197], v[246:249], v[32:35]
	v_mfma_f32_16x16x32_bf16 v[32:35], v[198:201], v[242:245], v[56:59]
	v_mfma_f32_16x16x32_bf16 v[64:67], v[202:205], v[246:249], v[32:35]
	s_barrier
	s_add_u32 s2, s30, s27
	s_addc_u32 s3, s31, s25
	s_mov_b32 m0, s59
	s_nop 1
	ds_read_b128 v[40:43], v165 offset:49152
	ds_read_b128 v[44:47], v165 offset:50176
	ds_read_b128 v[48:51], v165 offset:51200
	ds_read_b128 v[206:209], v165 offset:52224
	ds_read_b128 v[234:237], v165 offset:53248
	ds_read_b128 v[238:241], v165 offset:54272
	ds_read_b128 v[242:245], v165 offset:55296
	ds_read_b128 v[246:249], v165 offset:56320
	global_load_lds_dwordx4 v146, s[2:3]
	v_lshl_add_u64 v[32:33], s[2:3], 0, v[150:151]
	s_add_u32 s2, s2, 0x10000
	s_mov_b32 m0, s56
	s_addc_u32 s3, s3, 0
	global_load_lds_dwordx4 v[32:33], off
	s_mov_b32 m0, s57
	s_nop 0
	global_load_lds_dwordx4 v146, s[2:3]
	s_mov_b32 m0, s58
	s_nop 0
	global_load_lds_dwordx4 v150, s[2:3]
	s_mov_b32 m0, s63
	s_nop 0
	global_load_lds_dwordx4 v144, s[48:49]
	s_mov_b32 m0, s64
	s_nop 0
	global_load_lds_dwordx4 v148, s[48:49]
	s_waitcnt vmcnt(8)
	s_waitcnt lgkmcnt(0)
	s_barrier
	s_waitcnt lgkmcnt(0)
	v_mfma_f32_16x16x32_bf16 v[32:35], v[8:11], v[40:43], v[210:213]
	v_mfma_f32_16x16x32_bf16 v[92:95], v[12:15], v[44:47], v[32:35]
	v_mfma_f32_16x16x32_bf16 v[32:35], v[20:23], v[40:43], v[214:217]
	v_mfma_f32_16x16x32_bf16 v[88:91], v[174:177], v[44:47], v[32:35]
	v_mfma_f32_16x16x32_bf16 v[32:35], v[8:11], v[48:51], v[218:221]
	v_mfma_f32_16x16x32_bf16 v[60:63], v[12:15], v[206:209], v[32:35]
	v_mfma_f32_16x16x32_bf16 v[32:35], v[20:23], v[48:51], v[226:229]
	v_mfma_f32_16x16x32_bf16 v[56:59], v[174:177], v[206:209], v[32:35]
	v_mfma_f32_16x16x32_bf16 v[32:35], v[8:11], v[234:237], v[156:159]
	v_mfma_f32_16x16x32_bf16 v[0:3], v[8:11], v[242:245], v[0:3]
	v_mfma_f32_16x16x32_bf16 v[36:39], v[12:15], v[238:241], v[32:35]
	v_mfma_f32_16x16x32_bf16 v[32:35], v[20:23], v[234:237], v[166:169]
	v_mfma_f32_16x16x32_bf16 v[12:15], v[12:15], v[246:249], v[0:3]
	v_mfma_f32_16x16x32_bf16 v[0:3], v[20:23], v[242:245], v[4:7]
	v_mfma_f32_16x16x32_bf16 v[32:35], v[174:177], v[238:241], v[32:35]
	v_mfma_f32_16x16x32_bf16 v[8:11], v[174:177], v[246:249], v[0:3]
	v_mfma_f32_16x16x32_bf16 v[0:3], v[190:193], v[40:43], v[230:233]
	v_mfma_f32_16x16x32_bf16 v[84:87], v[194:197], v[44:47], v[0:3]
	v_mfma_f32_16x16x32_bf16 v[0:3], v[198:201], v[40:43], v[178:181]
	v_mfma_f32_16x16x32_bf16 v[76:79], v[202:205], v[44:47], v[0:3]
	v_mfma_f32_16x16x32_bf16 v[0:3], v[190:193], v[48:51], v[24:27]
	v_mfma_f32_16x16x32_bf16 v[52:55], v[194:197], v[206:209], v[0:3]
	v_mfma_f32_16x16x32_bf16 v[0:3], v[198:201], v[48:51], v[28:31]
	v_mfma_f32_16x16x32_bf16 v[48:51], v[202:205], v[206:209], v[0:3]
	v_mfma_f32_16x16x32_bf16 v[0:3], v[190:193], v[234:237], v[182:185]
	v_mfma_f32_16x16x32_bf16 v[24:27], v[194:197], v[238:241], v[0:3]
	v_mfma_f32_16x16x32_bf16 v[0:3], v[198:201], v[234:237], v[186:189]
	v_mfma_f32_16x16x32_bf16 v[20:23], v[202:205], v[238:241], v[0:3]
	v_mfma_f32_16x16x32_bf16 v[0:3], v[190:193], v[242:245], v[16:19]
	v_mfma_f32_16x16x32_bf16 v[4:7], v[194:197], v[246:249], v[0:3]
	v_mfma_f32_16x16x32_bf16 v[0:3], v[198:201], v[242:245], v[170:173]
	v_mfma_f32_16x16x32_bf16 v[0:3], v[202:205], v[246:249], v[0:3]
	s_barrier
	s_andn2_b64 vcc, exec, s[12:13]
	s_cbranch_vccnz .LBB0_482
	s_barrier

; #define PG8_STAGE(bufoff, gbase, voff) do { _Pragma("unroll") for (int _i = 0; _i < 2; ++_i) \
;         __builtin_amdgcn_global_load_lds((const unsigned*)((const char*)(gbase) + (voff)[_i]), (LAS unsigned*)(lds + (bufoff) + ldsw + _i * 8192), 16, 0, 0); } while (0)
; #define PG8_LDA(dst, b, h) do { _Pragma("unroll") for (int m = 0; m < 4; ++m) _Pragma("unroll") for (int k = 0; k < 2; ++k) dst[m][k] = *(const LAS bf16x8*)(lds + PG8_SA(b, h) + aoff + m * 2048 + k * 1024); } while (0)
; #define PG8_LDB(dst, b, h) do { _Pragma("unroll") for (int n = 0; n < 2; ++n) _Pragma("unroll") for (int k = 0; k < 2; ++k) dst[n][k] = *(const LAS bf16x8*)(lds + PG8_SB(b, h) + boff + n * 2048 + k * 1024); } while (0)
; #define PG8_MMA(ai, bj, At, Bt) do { __builtin_amdgcn_s_setprio(1); _Pragma("unroll") for (int m = 0; m < 4; ++m) _Pragma("unroll") for (int n = 0; n < 2; ++n) _Pragma("unroll") for (int k = 0; k < 2; ++k) \
;         acc[ai][bj][m][n] = __builtin_amdgcn_mfma_f32_16x16x32_bf16(Bt[n][k], At[m][k], acc[ai][bj][m][n], 0, 0, 0); __builtin_amdgcn_s_setprio(0); } while (0)
; #define PG8_WAIT_V(n) asm volatile("s_waitcnt vmcnt(" #n ")" ::: "memory")
; #define PG8_WAIT_L(n) asm volatile("s_waitcnt lgkmcnt(" #n ")" ::: "memory")
; #define PG8_BAR __builtin_amdgcn_s_barrier()
; #define PG8_SCHED __builtin_amdgcn_sched_barrier(0)
; template <class Epi>
; __device__ __forceinline__ void gemm_phase(LAS unsigned char* lds, const Gemm g, const StaticOrder S, const Epi E) {
;     ...
;             const char* a1 = cA + (long)(t + 1) * ksc;
;             const char* a2 = last ? nA : cA + (long)(t + 2) * ksc; const char* b2 = last ? nB : cB + (long)(t + 2) * ksc;
;             const long ks3 = last ? ksn : ksc;
;             const char* a3 = a2 + ks3; const char* b3 = b2 + ks3;
;             PG8_LDB(B0, 0, 0); PG8_LDB(B1, 0, 1); PG8_SCHED; PG8_LDA(At, 0, 0); PG8_STAGE(PG8_SA(1, 1), a1 + hstepA, voffA);
;             PG8_WAIT_V(8); PG8_WAIT_L(0); PG8_BAR; PG8_MMA(0, 0, At, B0); PG8_MMA(0, 1, At, B1); PG8_BAR; PG8_SCHED;
;             PG8_LDA(At, 0, 1); PG8_STAGE(PG8_SB(0, 0), b2, voffB); PG8_STAGE(PG8_SB(0, 1), b2 + hstepB, voffB); PG8_STAGE(PG8_SA(0, 0), a2, voffA);
;             PG8_WAIT_V(8); PG8_WAIT_L(0); PG8_BAR; PG8_MMA(1, 0, At, B0); PG8_MMA(1, 1, At, B1); PG8_BAR; PG8_SCHED;
.LBB0_566:
	v_add_u32_e32 v152, s67, v164
	v_add_u32_e32 v176, s68, v164
	ds_read_b128 v[128:131], v152
	ds_read_b128 v[132:135], v152 offset:1024
	ds_read_b128 v[136:139], v152 offset:2048
	ds_read_b128 v[152:155], v152 offset:3072
	ds_read_b128 v[156:159], v176
	ds_read_b128 v[168:171], v176 offset:1024
	ds_read_b128 v[172:175], v176 offset:2048
	ds_read_b128 v[176:179], v176 offset:3072
	s_or_b32 s21, s29, 1
	s_mul_i32 s58, s45, s21
	s_mul_hi_u32 s59, s44, s21
	s_add_i32 s59, s59, s58
	s_mul_i32 s21, s44, s21
	s_add_u32 s21, s42, s21
	s_addc_u32 s75, s43, s59
	s_add_u32 s58, s56, s54
	s_addc_u32 s59, s57, s55
	s_add_u32 s74, s21, 0x80000
	s_addc_u32 s75, s75, 0
	s_add_i32 m0, s31, 0xc000
	ds_read_b128 v[180:183], v166
	ds_read_b128 v[184:187], v166 offset:1024
	ds_read_b128 v[188:191], v166 offset:2048
	ds_read_b128 v[192:195], v166 offset:3072
	ds_read_b128 v[196:199], v166 offset:4096
	ds_read_b128 v[200:203], v166 offset:5120
	ds_read_b128 v[204:207], v166 offset:6144
	ds_read_b128 v[208:211], v166 offset:7168
	global_load_lds_dwordx4 v140, s[74:75]
	s_add_i32 m0, s31, 0xe000
	s_nop 0
	global_load_lds_dwordx4 v144, s[74:75]
	s_waitcnt vmcnt(8)
	s_waitcnt lgkmcnt(0)
	s_barrier
	s_waitcnt lgkmcnt(0)
	v_mfma_f32_16x16x32_bf16 v[124:127], v[128:131], v[180:183], v[124:127]
	v_mfma_f32_16x16x32_bf16 v[120:123], v[136:139], v[180:183], v[120:123]
	v_mfma_f32_16x16x32_bf16 v[108:111], v[128:131], v[188:191], v[108:111]
	v_mfma_f32_16x16x32_bf16 v[104:107], v[136:139], v[188:191], v[104:107]
	v_mfma_f32_16x16x32_bf16 v[92:95], v[128:131], v[196:199], v[92:95]
	v_mfma_f32_16x16x32_bf16 v[88:91], v[136:139], v[196:199], v[88:91]
	v_mfma_f32_16x16x32_bf16 v[76:79], v[128:131], v[204:207], v[76:79]
	v_mfma_f32_16x16x32_bf16 v[72:75], v[136:139], v[204:207], v[72:75]
	v_mfma_f32_16x16x32_bf16 v[124:127], v[132:135], v[184:187], v[124:127]
	v_mfma_f32_16x16x32_bf16 v[120:123], v[152:155], v[184:187], v[120:123]
	v_mfma_f32_16x16x32_bf16 v[108:111], v[132:135], v[192:195], v[108:111]
	v_mfma_f32_16x16x32_bf16 v[104:107], v[152:155], v[192:195], v[104:107]
	v_mfma_f32_16x16x32_bf16 v[92:95], v[132:135], v[200:203], v[92:95]
	v_mfma_f32_16x16x32_bf16 v[88:91], v[152:155], v[200:203], v[88:91]
	v_mfma_f32_16x16x32_bf16 v[76:79], v[132:135], v[208:211], v[76:79]
	v_mfma_f32_16x16x32_bf16 v[72:75], v[152:155], v[208:211], v[72:75]
	v_mfma_f32_16x16x32_bf16 v[116:119], v[156:159], v[180:183], v[116:119]
	v_mfma_f32_16x16x32_bf16 v[112:115], v[172:175], v[180:183], v[112:115]
	v_mfma_f32_16x16x32_bf16 v[100:103], v[156:159], v[188:191], v[100:103]
	v_mfma_f32_16x16x32_bf16 v[96:99], v[172:175], v[188:191], v[96:99]
	v_mfma_f32_16x16x32_bf16 v[84:87], v[156:159], v[196:199], v[84:87]
	v_mfma_f32_16x16x32_bf16 v[80:83], v[172:175], v[196:199], v[80:83]
	v_mfma_f32_16x16x32_bf16 v[68:71], v[156:159], v[204:207], v[68:71]
	v_mfma_f32_16x16x32_bf16 v[64:67], v[172:175], v[204:207], v[64:67]
	v_mfma_f32_16x16x32_bf16 v[116:119], v[168:171], v[184:187], v[116:119]
	v_mfma_f32_16x16x32_bf16 v[112:115], v[176:179], v[184:187], v[112:115]
	v_mfma_f32_16x16x32_bf16 v[100:103], v[168:171], v[192:195], v[100:103]
	v_mfma_f32_16x16x32_bf16 v[96:99], v[176:179], v[192:195], v[96:99]
	v_mfma_f32_16x16x32_bf16 v[84:87], v[168:171], v[200:203], v[84:87]
	v_mfma_f32_16x16x32_bf16 v[80:83], v[176:179], v[200:203], v[80:83]
	v_mfma_f32_16x16x32_bf16 v[68:71], v[168:171], v[208:211], v[68:71]
	v_mfma_f32_16x16x32_bf16 v[64:67], v[176:179], v[208:211], v[64:67]
	s_barrier
	s_add_i32 s21, s67, s33
	s_mov_b32 m0, s21
	ds_read_b128 v[180:183], v166 offset:16384
	ds_read_b128 v[184:187], v166 offset:17408
	ds_read_b128 v[188:191], v166 offset:18432
	ds_read_b128 v[192:195], v166 offset:19456
	ds_read_b128 v[196:199], v166 offset:20480
	ds_read_b128 v[200:203], v166 offset:21504
	ds_read_b128 v[204:207], v166 offset:22528
	ds_read_b128 v[208:211], v166 offset:23552
	global_load_lds_dwordx4 v142, s[52:53]
	s_add_i32 m0, s21, 0x2000
	s_add_u32 s74, s52, 0x80000
	s_addc_u32 s75, s53, 0
	s_add_i32 s21, s68, s33
	global_load_lds_dwordx4 v146, s[52:53]
	s_mov_b32 m0, s21
	s_nop 0
	global_load_lds_dwordx4 v142, s[74:75]
	s_add_i32 m0, s21, 0x2000
	s_nop 0
	global_load_lds_dwordx4 v146, s[74:75]
	s_mov_b32 m0, s31
	s_nop 0
	global_load_lds_dwordx4 v140, s[56:57]
	s_mov_b32 m0, s60
	s_nop 0
	global_load_lds_dwordx4 v144, s[56:57]
	s_waitcnt vmcnt(8)
	s_waitcnt lgkmcnt(0)
	s_barrier
	s_waitcnt lgkmcnt(0)
	v_mfma_f32_16x16x32_bf16 v[60:63], v[128:131], v[180:183], v[60:63]
	v_mfma_f32_16x16x32_bf16 v[56:59], v[136:139], v[180:183], v[56:59]
	v_mfma_f32_16x16x32_bf16 v[44:47], v[128:131], v[188:191], v[44:47]
	v_mfma_f32_16x16x32_bf16 v[40:43], v[136:139], v[188:191], v[40:43]
	v_mfma_f32_16x16x32_bf16 v[28:31], v[128:131], v[196:199], v[28:31]
	v_mfma_f32_16x16x32_bf16 v[24:27], v[136:139], v[196:199], v[24:27]
	v_mfma_f32_16x16x32_bf16 v[12:15], v[128:131], v[204:207], v[12:15]
	v_mfma_f32_16x16x32_bf16 v[8:11], v[136:139], v[204:207], v[8:11]
	v_mfma_f32_16x16x32_bf16 v[60:63], v[132:135], v[184:187], v[60:63]
	v_mfma_f32_16x16x32_bf16 v[56:59], v[152:155], v[184:187], v[56:59]
	v_mfma_f32_16x16x32_bf16 v[44:47], v[132:135], v[192:195], v[44:47]
	v_mfma_f32_16x16x32_bf16 v[40:43], v[152:155], v[192:195], v[40:43]
	v_mfma_f32_16x16x32_bf16 v[28:31], v[132:135], v[200:203], v[28:31]
	v_mfma_f32_16x16x32_bf16 v[24:27], v[152:155], v[200:203], v[24:27]
	v_mfma_f32_16x16x32_bf16 v[12:15], v[132:135], v[208:211], v[12:15]
	v_mfma_f32_16x16x32_bf16 v[8:11], v[152:155], v[208:211], v[8:11]
	v_mfma_f32_16x16x32_bf16 v[52:55], v[156:159], v[180:183], v[52:55]
	v_mfma_f32_16x16x32_bf16 v[48:51], v[172:175], v[180:183], v[48:51]
	v_mfma_f32_16x16x32_bf16 v[36:39], v[156:159], v[188:191], v[36:39]
	v_mfma_f32_16x16x32_bf16 v[32:35], v[172:175], v[188:191], v[32:35]
	v_mfma_f32_16x16x32_bf16 v[20:23], v[156:159], v[196:199], v[20:23]
	v_mfma_f32_16x16x32_bf16 v[16:19], v[172:175], v[196:199], v[16:19]
	v_mfma_f32_16x16x32_bf16 v[4:7], v[156:159], v[204:207], v[4:7]
	v_mfma_f32_16x16x32_bf16 v[0:3], v[172:175], v[204:207], v[0:3]
	v_mfma_f32_16x16x32_bf16 v[52:55], v[168:171], v[184:187], v[52:55]
	v_mfma_f32_16x16x32_bf16 v[48:51], v[176:179], v[184:187], v[48:51]
	v_mfma_f32_16x16x32_bf16 v[36:39], v[168:171], v[192:195], v[36:39]
	v_mfma_f32_16x16x32_bf16 v[32:35], v[176:179], v[192:195], v[32:35]
	v_mfma_f32_16x16x32_bf16 v[20:23], v[168:171], v[200:203], v[20:23]
	v_mfma_f32_16x16x32_bf16 v[16:19], v[176:179], v[200:203], v[16:19]
	v_mfma_f32_16x16x32_bf16 v[4:7], v[168:171], v[208:211], v[4:7]
	v_mfma_f32_16x16x32_bf16 v[0:3], v[176:179], v[208:211], v[0:3]
	s_barrier
; #define PG8_STAGE(bufoff, gbase, voff) do { _Pragma("unroll") for (int _i = 0; _i < 2; ++_i) \
;         __builtin_amdgcn_global_load_lds((const unsigned*)((const char*)(gbase) + (voff)[_i]), (LAS unsigned*)(lds + (bufoff) + ldsw + _i * 8192), 16, 0, 0); } while (0)
; #define PG8_LDA(dst, b, h) do { _Pragma("unroll") for (int m = 0; m < 4; ++m) _Pragma("unroll") for (int k = 0; k < 2; ++k) dst[m][k] = *(const LAS bf16x8*)(lds + PG8_SA(b, h) + aoff + m * 2048 + k * 1024); } while (0)
; #define PG8_LDB(dst, b, h) do { _Pragma("unroll") for (int n = 0; n < 2; ++n) _Pragma("unroll") for (int k = 0; k < 2; ++k) dst[n][k] = *(const LAS bf16x8*)(lds + PG8_SB(b, h) + boff + n * 2048 + k * 1024); } while (0)
; #define PG8_MMA(ai, bj, At, Bt) do { __builtin_amdgcn_s_setprio(1); _Pragma("unroll") for (int m = 0; m < 4; ++m) _Pragma("unroll") for (int n = 0; n < 2; ++n) _Pragma("unroll") for (int k = 0; k < 2; ++k) \
;         acc[ai][bj][m][n] = __builtin_amdgcn_mfma_f32_16x16x32_bf16(Bt[n][k], At[m][k], acc[ai][bj][m][n], 0, 0, 0); __builtin_amdgcn_s_setprio(0); } while (0)
; #define PG8_WAIT_V(n) asm volatile("s_waitcnt vmcnt(" #n ")" ::: "memory")
; #define PG8_WAIT_L(n) asm volatile("s_waitcnt lgkmcnt(" #n ")" ::: "memory")
; #define PG8_BAR __builtin_amdgcn_s_barrier()
; #define PG8_SCHED __builtin_amdgcn_sched_barrier(0)
; template <class Epi>
; __device__ __forceinline__ void gemm_phase(LAS unsigned char* lds, const Gemm g, const StaticOrder S, const Epi E) {
;     ...
;             PG8_LDB(B0, 1, 0); PG8_LDB(B1, 1, 1); PG8_SCHED; PG8_LDA(At, 1, 0); PG8_STAGE(PG8_SA(0, 1), a2 + hstepA, voffA);
;             PG8_WAIT_V(8); PG8_WAIT_L(0); PG8_BAR; PG8_MMA(0, 0, At, B0); PG8_MMA(0, 1, At, B1); PG8_BAR; PG8_SCHED;
;             PG8_LDA(At, 1, 1); PG8_STAGE(PG8_SB(1, 0), b3, voffB); PG8_STAGE(PG8_SB(1, 1), b3 + hstepB, voffB); PG8_STAGE(PG8_SA(1, 0), a3, voffA);
;             PG8_WAIT_V(8); PG8_WAIT_L(0); PG8_BAR; PG8_MMA(1, 0, At, B0); PG8_MMA(1, 1, At, B1); PG8_BAR; PG8_SCHED;
;         }
	s_add_i32 s21, 0, 0x18000
	s_add_i32 s74, 0, 0x1c000
	v_add_u32_e32 v152, s21, v164
	v_add_u32_e32 v176, s74, v164
	ds_read_b128 v[128:131], v152
	ds_read_b128 v[132:135], v152 offset:1024
	ds_read_b128 v[136:139], v152 offset:2048
	ds_read_b128 v[152:155], v152 offset:3072
	ds_read_b128 v[156:159], v176
	ds_read_b128 v[168:171], v176 offset:1024
	ds_read_b128 v[172:175], v176 offset:2048
	ds_read_b128 v[176:179], v176 offset:3072
	s_add_u32 s56, s56, 0x80000
	s_addc_u32 s57, s57, 0
	s_mov_b32 m0, s61
	ds_read_b128 v[180:183], v166 offset:32768
	ds_read_b128 v[184:187], v166 offset:33792
	ds_read_b128 v[188:191], v166 offset:34816
	ds_read_b128 v[192:195], v166 offset:35840
	ds_read_b128 v[196:199], v166 offset:36864
	ds_read_b128 v[200:203], v166 offset:37888
	ds_read_b128 v[204:207], v166 offset:38912
	ds_read_b128 v[208:211], v166 offset:39936
	global_load_lds_dwordx4 v140, s[56:57]
	s_mov_b32 m0, s62
	s_nop 0
	global_load_lds_dwordx4 v144, s[56:57]
	s_waitcnt vmcnt(8)
	s_waitcnt lgkmcnt(0)
	s_barrier
	s_waitcnt lgkmcnt(0)
	v_mfma_f32_16x16x32_bf16 v[124:127], v[128:131], v[180:183], v[124:127]
	v_mfma_f32_16x16x32_bf16 v[120:123], v[136:139], v[180:183], v[120:123]
	v_mfma_f32_16x16x32_bf16 v[108:111], v[128:131], v[188:191], v[108:111]
	v_mfma_f32_16x16x32_bf16 v[104:107], v[136:139], v[188:191], v[104:107]
	v_mfma_f32_16x16x32_bf16 v[92:95], v[128:131], v[196:199], v[92:95]
	v_mfma_f32_16x16x32_bf16 v[88:91], v[136:139], v[196:199], v[88:91]
	v_mfma_f32_16x16x32_bf16 v[76:79], v[128:131], v[204:207], v[76:79]
	v_mfma_f32_16x16x32_bf16 v[72:75], v[136:139], v[204:207], v[72:75]
	v_mfma_f32_16x16x32_bf16 v[124:127], v[132:135], v[184:187], v[124:127]
	v_mfma_f32_16x16x32_bf16 v[120:123], v[152:155], v[184:187], v[120:123]
	v_mfma_f32_16x16x32_bf16 v[108:111], v[132:135], v[192:195], v[108:111]
	v_mfma_f32_16x16x32_bf16 v[104:107], v[152:155], v[192:195], v[104:107]
	v_mfma_f32_16x16x32_bf16 v[92:95], v[132:135], v[200:203], v[92:95]
	v_mfma_f32_16x16x32_bf16 v[88:91], v[152:155], v[200:203], v[88:91]
	v_mfma_f32_16x16x32_bf16 v[76:79], v[132:135], v[208:211], v[76:79]
	v_mfma_f32_16x16x32_bf16 v[72:75], v[152:155], v[208:211], v[72:75]
	v_mfma_f32_16x16x32_bf16 v[116:119], v[156:159], v[180:183], v[116:119]
	v_mfma_f32_16x16x32_bf16 v[112:115], v[172:175], v[180:183], v[112:115]
	v_mfma_f32_16x16x32_bf16 v[100:103], v[156:159], v[188:191], v[100:103]
	v_mfma_f32_16x16x32_bf16 v[96:99], v[172:175], v[188:191], v[96:99]
	v_mfma_f32_16x16x32_bf16 v[84:87], v[156:159], v[196:199], v[84:87]
	v_mfma_f32_16x16x32_bf16 v[80:83], v[172:175], v[196:199], v[80:83]
	v_mfma_f32_16x16x32_bf16 v[68:71], v[156:159], v[204:207], v[68:71]
	v_mfma_f32_16x16x32_bf16 v[64:67], v[172:175], v[204:207], v[64:67]
	v_mfma_f32_16x16x32_bf16 v[116:119], v[168:171], v[184:187], v[116:119]
	v_mfma_f32_16x16x32_bf16 v[112:115], v[176:179], v[184:187], v[112:115]
	v_mfma_f32_16x16x32_bf16 v[100:103], v[168:171], v[192:195], v[100:103]
	v_mfma_f32_16x16x32_bf16 v[96:99], v[176:179], v[192:195], v[96:99]
	v_mfma_f32_16x16x32_bf16 v[84:87], v[168:171], v[200:203], v[84:87]
	v_mfma_f32_16x16x32_bf16 v[80:83], v[176:179], v[200:203], v[80:83]
	v_mfma_f32_16x16x32_bf16 v[68:71], v[168:171], v[208:211], v[68:71]
	v_mfma_f32_16x16x32_bf16 v[64:67], v[176:179], v[208:211], v[64:67]
	s_barrier
	s_add_u32 s52, s52, s54
	s_addc_u32 s53, s53, s55
	s_add_i32 s21, s21, s33
	s_mov_b32 m0, s21
	ds_read_b128 v[180:183], v166 offset:49152
	ds_read_b128 v[184:187], v166 offset:50176
	ds_read_b128 v[188:191], v166 offset:51200
	ds_read_b128 v[192:195], v166 offset:52224
	ds_read_b128 v[196:199], v166 offset:53248
	ds_read_b128 v[200:203], v166 offset:54272
	ds_read_b128 v[204:207], v166 offset:55296
	ds_read_b128 v[208:211], v166 offset:56320
	global_load_lds_dwordx4 v142, s[52:53]
	s_add_i32 m0, s21, 0x2000
	s_nop 0
	global_load_lds_dwordx4 v146, s[52:53]
	s_add_u32 s52, s52, 0x80000
	s_addc_u32 s53, s53, 0
	s_add_i32 s21, s74, s33
	s_mov_b32 m0, s21
	s_nop 0
	global_load_lds_dwordx4 v142, s[52:53]
	s_add_i32 m0, s21, 0x2000
	s_nop 0
	global_load_lds_dwordx4 v146, s[52:53]
	s_mov_b32 m0, s64
	s_nop 0
	global_load_lds_dwordx4 v140, s[58:59]
	s_mov_b32 m0, s65
	s_nop 0
	global_load_lds_dwordx4 v144, s[58:59]
	s_waitcnt vmcnt(8)
	s_waitcnt lgkmcnt(0)
	s_barrier
	s_waitcnt lgkmcnt(0)
	v_mfma_f32_16x16x32_bf16 v[60:63], v[128:131], v[180:183], v[60:63]
	v_mfma_f32_16x16x32_bf16 v[56:59], v[136:139], v[180:183], v[56:59]
	v_mfma_f32_16x16x32_bf16 v[44:47], v[128:131], v[188:191], v[44:47]
	v_mfma_f32_16x16x32_bf16 v[40:43], v[136:139], v[188:191], v[40:43]
	v_mfma_f32_16x16x32_bf16 v[28:31], v[128:131], v[196:199], v[28:31]
	v_mfma_f32_16x16x32_bf16 v[24:27], v[136:139], v[196:199], v[24:27]
	v_mfma_f32_16x16x32_bf16 v[12:15], v[128:131], v[204:207], v[12:15]
	v_mfma_f32_16x16x32_bf16 v[8:11], v[136:139], v[204:207], v[8:11]
	v_mfma_f32_16x16x32_bf16 v[60:63], v[132:135], v[184:187], v[60:63]
	v_mfma_f32_16x16x32_bf16 v[56:59], v[152:155], v[184:187], v[56:59]
	v_mfma_f32_16x16x32_bf16 v[44:47], v[132:135], v[192:195], v[44:47]
	v_mfma_f32_16x16x32_bf16 v[40:43], v[152:155], v[192:195], v[40:43]
	v_mfma_f32_16x16x32_bf16 v[28:31], v[132:135], v[200:203], v[28:31]
	v_mfma_f32_16x16x32_bf16 v[24:27], v[152:155], v[200:203], v[24:27]
	v_mfma_f32_16x16x32_bf16 v[12:15], v[132:135], v[208:211], v[12:15]
	v_mfma_f32_16x16x32_bf16 v[8:11], v[152:155], v[208:211], v[8:11]
	v_mfma_f32_16x16x32_bf16 v[52:55], v[156:159], v[180:183], v[52:55]
	v_mfma_f32_16x16x32_bf16 v[48:51], v[172:175], v[180:183], v[48:51]
	v_mfma_f32_16x16x32_bf16 v[36:39], v[156:159], v[188:191], v[36:39]
	v_mfma_f32_16x16x32_bf16 v[32:35], v[172:175], v[188:191], v[32:35]
	v_mfma_f32_16x16x32_bf16 v[20:23], v[156:159], v[196:199], v[20:23]
	v_mfma_f32_16x16x32_bf16 v[16:19], v[172:175], v[196:199], v[16:19]
	v_mfma_f32_16x16x32_bf16 v[4:7], v[156:159], v[204:207], v[4:7]
	v_mfma_f32_16x16x32_bf16 v[0:3], v[172:175], v[204:207], v[0:3]
	v_mfma_f32_16x16x32_bf16 v[52:55], v[168:171], v[184:187], v[52:55]
	v_mfma_f32_16x16x32_bf16 v[48:51], v[176:179], v[184:187], v[48:51]
	v_mfma_f32_16x16x32_bf16 v[36:39], v[168:171], v[192:195], v[36:39]
	v_mfma_f32_16x16x32_bf16 v[32:35], v[176:179], v[192:195], v[32:35]
	v_mfma_f32_16x16x32_bf16 v[20:23], v[168:171], v[200:203], v[20:23]
	v_mfma_f32_16x16x32_bf16 v[16:19], v[176:179], v[200:203], v[16:19]
	v_mfma_f32_16x16x32_bf16 v[4:7], v[168:171], v[208:211], v[4:7]
	v_mfma_f32_16x16x32_bf16 v[0:3], v[176:179], v[208:211], v[0:3]
	s_barrier
	s_cmp_gt_u32 s29, 29
	s_mov_b32 s29, s19
	s_cbranch_scc1 .LBB0_571

; #define PG8_STAGE(bufoff, gbase, voff) do { _Pragma("unroll") for (int _i = 0; _i < 2; ++_i) \
;         __builtin_amdgcn_global_load_lds((const unsigned*)((const char*)(gbase) + (voff)[_i]), (LAS unsigned*)(lds + (bufoff) + ldsw + _i * 8192), 16, 0, 0); } while (0)
; #define PG8_LDA(dst, b, h) do { _Pragma("unroll") for (int m = 0; m < 4; ++m) _Pragma("unroll") for (int k = 0; k < 2; ++k) dst[m][k] = *(const LAS bf16x8*)(lds + PG8_SA(b, h) + aoff + m * 2048 + k * 1024); } while (0)
; #define PG8_LDB(dst, b, h) do { _Pragma("unroll") for (int n = 0; n < 2; ++n) _Pragma("unroll") for (int k = 0; k < 2; ++k) dst[n][k] = *(const LAS bf16x8*)(lds + PG8_SB(b, h) + boff + n * 2048 + k * 1024); } while (0)
; #define PG8_MMA(ai, bj, At, Bt) do { __builtin_amdgcn_s_setprio(1); _Pragma("unroll") for (int m = 0; m < 4; ++m) _Pragma("unroll") for (int n = 0; n < 2; ++n) _Pragma("unroll") for (int k = 0; k < 2; ++k) \
;         acc[ai][bj][m][n] = __builtin_amdgcn_mfma_f32_16x16x32_bf16(Bt[n][k], At[m][k], acc[ai][bj][m][n], 0, 0, 0); __builtin_amdgcn_s_setprio(0); } while (0)
; #define PG8_WAIT_V(n) asm volatile("s_waitcnt vmcnt(" #n ")" ::: "memory")
; #define PG8_WAIT_L(n) asm volatile("s_waitcnt lgkmcnt(" #n ")" ::: "memory")
; #define PG8_BAR __builtin_amdgcn_s_barrier()
; #define PG8_SCHED __builtin_amdgcn_sched_barrier(0)
; template <class Epi>
; __device__ __forceinline__ void gemm_phase(LAS unsigned char* lds, const Gemm g, const StaticOrder S, const Epi E) {
;     ...
;             const char* a1 = cA + (long)(t + 1) * ksc;
;             const char* a2 = last ? nA : cA + (long)(t + 2) * ksc; const char* b2 = last ? nB : cB + (long)(t + 2) * ksc;
;             const long ks3 = last ? ksn : ksc;
;             const char* a3 = a2 + ks3; const char* b3 = b2 + ks3;
;             PG8_LDB(B0, 0, 0); PG8_LDB(B1, 0, 1); PG8_SCHED; PG8_LDA(At, 0, 0); PG8_STAGE(PG8_SA(1, 1), a1 + hstepA, voffA);
;             PG8_WAIT_V(8); PG8_WAIT_L(0); PG8_BAR; PG8_MMA(0, 0, At, B0); PG8_MMA(0, 1, At, B1); PG8_BAR; PG8_SCHED;
;             PG8_LDA(At, 0, 1); PG8_STAGE(PG8_SB(0, 0), b2, voffB); PG8_STAGE(PG8_SB(0, 1), b2 + hstepB, voffB); PG8_STAGE(PG8_SA(0, 0), a2, voffA);
;             PG8_WAIT_V(8); PG8_WAIT_L(0); PG8_BAR; PG8_MMA(1, 0, At, B0); PG8_MMA(1, 1, At, B1); PG8_BAR; PG8_SCHED;
.LBB0_666:
	ds_read_b128 v[148:151], v254
	ds_read_b128 v[152:155], v254 offset:1024
	ds_read_b128 v[156:159], v254 offset:2048
	ds_read_b128 v[160:163], v254 offset:3072
	ds_read_b128 v[164:167], v254 offset:16384
	ds_read_b128 v[168:171], v254 offset:17408
	ds_read_b128 v[172:175], v254 offset:18432
	ds_read_b128 v[176:179], v254 offset:19456
	s_or_b32 s13, s66, 1
	s_mul_i32 s48, s27, s13
	s_mul_hi_u32 s49, s26, s13
	s_add_i32 s49, s49, s48
	s_mul_i32 s13, s26, s13
	s_add_u32 s13, s24, s13
	s_addc_u32 s67, s25, s49
	s_add_u32 s48, s46, s44
	s_addc_u32 s49, s47, s45
	s_add_u32 s68, s13, 0x80000
	s_addc_u32 s69, s67, 0
	s_add_i32 m0, s21, 0xc000
	ds_read_b128 v[180:183], v145
	ds_read_b128 v[184:187], v145 offset:1024
	ds_read_b128 v[188:191], v145 offset:2048
	ds_read_b128 v[192:195], v145 offset:3072
	ds_read_b128 v[196:199], v145 offset:4096
	ds_read_b128 v[200:203], v145 offset:5120
	ds_read_b128 v[204:207], v145 offset:6144
	ds_read_b128 v[208:211], v145 offset:7168
	global_load_lds_dwordx4 v134, s[68:69]
	s_add_i32 m0, s21, 0xe000
	s_nop 0
	global_load_lds_dwordx4 v130, s[68:69]
	s_waitcnt vmcnt(8)
	s_waitcnt lgkmcnt(0)
	s_barrier
	s_waitcnt lgkmcnt(0)
	v_mfma_f32_16x16x32_bf16 v[116:119], v[148:151], v[180:183], v[116:119]
	v_mfma_f32_16x16x32_bf16 v[112:115], v[156:159], v[180:183], v[112:115]
	v_mfma_f32_16x16x32_bf16 v[108:111], v[148:151], v[188:191], v[108:111]
	v_mfma_f32_16x16x32_bf16 v[104:107], v[156:159], v[188:191], v[104:107]
	v_mfma_f32_16x16x32_bf16 v[92:95], v[148:151], v[196:199], v[92:95]
	v_mfma_f32_16x16x32_bf16 v[88:91], v[156:159], v[196:199], v[88:91]
	v_mfma_f32_16x16x32_bf16 v[76:79], v[148:151], v[204:207], v[76:79]
	v_mfma_f32_16x16x32_bf16 v[72:75], v[156:159], v[204:207], v[72:75]
	v_mfma_f32_16x16x32_bf16 v[116:119], v[152:155], v[184:187], v[116:119]
	v_mfma_f32_16x16x32_bf16 v[112:115], v[160:163], v[184:187], v[112:115]
	v_mfma_f32_16x16x32_bf16 v[108:111], v[152:155], v[192:195], v[108:111]
	v_mfma_f32_16x16x32_bf16 v[104:107], v[160:163], v[192:195], v[104:107]
	v_mfma_f32_16x16x32_bf16 v[92:95], v[152:155], v[200:203], v[92:95]
	v_mfma_f32_16x16x32_bf16 v[88:91], v[160:163], v[200:203], v[88:91]
	v_mfma_f32_16x16x32_bf16 v[76:79], v[152:155], v[208:211], v[76:79]
	v_mfma_f32_16x16x32_bf16 v[72:75], v[160:163], v[208:211], v[72:75]
	v_mfma_f32_16x16x32_bf16 v[124:127], v[164:167], v[180:183], v[124:127]
	v_mfma_f32_16x16x32_bf16 v[120:123], v[172:175], v[180:183], v[120:123]
	v_mfma_f32_16x16x32_bf16 v[100:103], v[164:167], v[188:191], v[100:103]
	v_mfma_f32_16x16x32_bf16 v[96:99], v[172:175], v[188:191], v[96:99]
	v_mfma_f32_16x16x32_bf16 v[84:87], v[164:167], v[196:199], v[84:87]
	v_mfma_f32_16x16x32_bf16 v[80:83], v[172:175], v[196:199], v[80:83]
	v_mfma_f32_16x16x32_bf16 v[68:71], v[164:167], v[204:207], v[68:71]
	v_mfma_f32_16x16x32_bf16 v[64:67], v[172:175], v[204:207], v[64:67]
	v_mfma_f32_16x16x32_bf16 v[124:127], v[168:171], v[184:187], v[124:127]
	v_mfma_f32_16x16x32_bf16 v[120:123], v[176:179], v[184:187], v[120:123]
	v_mfma_f32_16x16x32_bf16 v[100:103], v[168:171], v[192:195], v[100:103]
	v_mfma_f32_16x16x32_bf16 v[96:99], v[176:179], v[192:195], v[96:99]
	v_mfma_f32_16x16x32_bf16 v[84:87], v[168:171], v[200:203], v[84:87]
	v_mfma_f32_16x16x32_bf16 v[80:83], v[176:179], v[200:203], v[80:83]
	v_mfma_f32_16x16x32_bf16 v[68:71], v[168:171], v[208:211], v[68:71]
	v_mfma_f32_16x16x32_bf16 v[64:67], v[176:179], v[208:211], v[64:67]
	s_barrier
	s_add_i32 s13, s61, s51
	s_mov_b32 m0, s13
	ds_read_b128 v[180:183], v145 offset:16384
	ds_read_b128 v[184:187], v145 offset:17408
	ds_read_b128 v[188:191], v145 offset:18432
	ds_read_b128 v[192:195], v145 offset:19456
	ds_read_b128 v[196:199], v145 offset:20480
	ds_read_b128 v[200:203], v145 offset:21504
	ds_read_b128 v[204:207], v145 offset:22528
	ds_read_b128 v[208:211], v145 offset:23552
	global_load_lds_dwordx4 v132, s[42:43]
	s_add_i32 m0, s13, 0x2000
	s_add_u32 s68, s42, 0x80000
	s_addc_u32 s69, s43, 0
	s_add_i32 s13, s62, s51
	global_load_lds_dwordx4 v128, s[42:43]
	s_mov_b32 m0, s13
	s_nop 0
	global_load_lds_dwordx4 v132, s[68:69]
	s_add_i32 m0, s13, 0x2000
	s_nop 0
	global_load_lds_dwordx4 v128, s[68:69]
	s_mov_b32 m0, s21
	s_nop 0
	global_load_lds_dwordx4 v134, s[46:47]
	s_mov_b32 m0, s54
	s_nop 0
	global_load_lds_dwordx4 v130, s[46:47]
	s_waitcnt vmcnt(8)
	s_waitcnt lgkmcnt(0)
	s_barrier
	s_waitcnt lgkmcnt(0)
	v_mfma_f32_16x16x32_bf16 v[60:63], v[148:151], v[180:183], v[60:63]
	v_mfma_f32_16x16x32_bf16 v[56:59], v[156:159], v[180:183], v[56:59]
	v_mfma_f32_16x16x32_bf16 v[44:47], v[148:151], v[188:191], v[44:47]
	v_mfma_f32_16x16x32_bf16 v[40:43], v[156:159], v[188:191], v[40:43]
	v_mfma_f32_16x16x32_bf16 v[28:31], v[148:151], v[196:199], v[28:31]
	v_mfma_f32_16x16x32_bf16 v[24:27], v[156:159], v[196:199], v[24:27]
	v_mfma_f32_16x16x32_bf16 v[12:15], v[148:151], v[204:207], v[12:15]
	v_mfma_f32_16x16x32_bf16 v[8:11], v[156:159], v[204:207], v[8:11]
	v_mfma_f32_16x16x32_bf16 v[60:63], v[152:155], v[184:187], v[60:63]
	v_mfma_f32_16x16x32_bf16 v[56:59], v[160:163], v[184:187], v[56:59]
	v_mfma_f32_16x16x32_bf16 v[44:47], v[152:155], v[192:195], v[44:47]
	v_mfma_f32_16x16x32_bf16 v[40:43], v[160:163], v[192:195], v[40:43]
	v_mfma_f32_16x16x32_bf16 v[28:31], v[152:155], v[200:203], v[28:31]
	v_mfma_f32_16x16x32_bf16 v[24:27], v[160:163], v[200:203], v[24:27]
	v_mfma_f32_16x16x32_bf16 v[12:15], v[152:155], v[208:211], v[12:15]
	v_mfma_f32_16x16x32_bf16 v[8:11], v[160:163], v[208:211], v[8:11]
	v_mfma_f32_16x16x32_bf16 v[52:55], v[164:167], v[180:183], v[52:55]
	v_mfma_f32_16x16x32_bf16 v[48:51], v[172:175], v[180:183], v[48:51]
	v_mfma_f32_16x16x32_bf16 v[36:39], v[164:167], v[188:191], v[36:39]
	v_mfma_f32_16x16x32_bf16 v[32:35], v[172:175], v[188:191], v[32:35]
	v_mfma_f32_16x16x32_bf16 v[20:23], v[164:167], v[196:199], v[20:23]
	v_mfma_f32_16x16x32_bf16 v[16:19], v[172:175], v[196:199], v[16:19]
	v_mfma_f32_16x16x32_bf16 v[4:7], v[164:167], v[204:207], v[4:7]
	v_mfma_f32_16x16x32_bf16 v[0:3], v[172:175], v[204:207], v[0:3]
	v_mfma_f32_16x16x32_bf16 v[52:55], v[168:171], v[184:187], v[52:55]
	v_mfma_f32_16x16x32_bf16 v[48:51], v[176:179], v[184:187], v[48:51]
	v_mfma_f32_16x16x32_bf16 v[36:39], v[168:171], v[192:195], v[36:39]
	v_mfma_f32_16x16x32_bf16 v[32:35], v[176:179], v[192:195], v[32:35]
	v_mfma_f32_16x16x32_bf16 v[20:23], v[168:171], v[200:203], v[20:23]
	v_mfma_f32_16x16x32_bf16 v[16:19], v[176:179], v[200:203], v[16:19]
	v_mfma_f32_16x16x32_bf16 v[4:7], v[168:171], v[208:211], v[4:7]
	v_mfma_f32_16x16x32_bf16 v[0:3], v[176:179], v[208:211], v[0:3]
	s_barrier
; #define PG8_STAGE(bufoff, gbase, voff) do { _Pragma("unroll") for (int _i = 0; _i < 2; ++_i) \
;         __builtin_amdgcn_global_load_lds((const unsigned*)((const char*)(gbase) + (voff)[_i]), (LAS unsigned*)(lds + (bufoff) + ldsw + _i * 8192), 16, 0, 0); } while (0)
; #define PG8_LDA(dst, b, h) do { _Pragma("unroll") for (int m = 0; m < 4; ++m) _Pragma("unroll") for (int k = 0; k < 2; ++k) dst[m][k] = *(const LAS bf16x8*)(lds + PG8_SA(b, h) + aoff + m * 2048 + k * 1024); } while (0)
; #define PG8_LDB(dst, b, h) do { _Pragma("unroll") for (int n = 0; n < 2; ++n) _Pragma("unroll") for (int k = 0; k < 2; ++k) dst[n][k] = *(const LAS bf16x8*)(lds + PG8_SB(b, h) + boff + n * 2048 + k * 1024); } while (0)
; #define PG8_MMA(ai, bj, At, Bt) do { __builtin_amdgcn_s_setprio(1); _Pragma("unroll") for (int m = 0; m < 4; ++m) _Pragma("unroll") for (int n = 0; n < 2; ++n) _Pragma("unroll") for (int k = 0; k < 2; ++k) \
;         acc[ai][bj][m][n] = __builtin_amdgcn_mfma_f32_16x16x32_bf16(Bt[n][k], At[m][k], acc[ai][bj][m][n], 0, 0, 0); __builtin_amdgcn_s_setprio(0); } while (0)
; #define PG8_WAIT_V(n) asm volatile("s_waitcnt vmcnt(" #n ")" ::: "memory")
; #define PG8_WAIT_L(n) asm volatile("s_waitcnt lgkmcnt(" #n ")" ::: "memory")
; #define PG8_BAR __builtin_amdgcn_s_barrier()
; #define PG8_SCHED __builtin_amdgcn_sched_barrier(0)
; template <class Epi>
; __device__ __forceinline__ void gemm_phase(LAS unsigned char* lds, const Gemm g, const StaticOrder S, const Epi E) {
;     ...
;             PG8_LDB(B0, 1, 0); PG8_LDB(B1, 1, 1); PG8_SCHED; PG8_LDA(At, 1, 0); PG8_STAGE(PG8_SA(0, 1), a2 + hstepA, voffA);
;             PG8_WAIT_V(8); PG8_WAIT_L(0); PG8_BAR; PG8_MMA(0, 0, At, B0); PG8_MMA(0, 1, At, B1); PG8_BAR; PG8_SCHED;
;             PG8_LDA(At, 1, 1); PG8_STAGE(PG8_SB(1, 0), b3, voffB); PG8_STAGE(PG8_SB(1, 1), b3 + hstepB, voffB); PG8_STAGE(PG8_SA(1, 0), a3, voffA);
;             PG8_WAIT_V(8); PG8_WAIT_L(0); PG8_BAR; PG8_MMA(1, 0, At, B0); PG8_MMA(1, 1, At, B1); PG8_BAR; PG8_SCHED;
;         }
	s_add_i32 s13, 0, 0x18000
	s_add_i32 s67, 0, 0x1c000
	ds_read_b128 v[148:151], v254 offset:32768
	ds_read_b128 v[152:155], v254 offset:33792
	ds_read_b128 v[156:159], v254 offset:34816
	ds_read_b128 v[160:163], v254 offset:35840
	ds_read_b128 v[164:167], v254 offset:49152
	ds_read_b128 v[168:171], v254 offset:50176
	ds_read_b128 v[172:175], v254 offset:51200
	ds_read_b128 v[176:179], v254 offset:52224
	s_add_u32 s46, s46, 0x80000
	s_addc_u32 s47, s47, 0
	s_mov_b32 m0, s55
	ds_read_b128 v[180:183], v145 offset:32768
	ds_read_b128 v[184:187], v145 offset:33792
	ds_read_b128 v[188:191], v145 offset:34816
	ds_read_b128 v[192:195], v145 offset:35840
	ds_read_b128 v[196:199], v145 offset:36864
	ds_read_b128 v[200:203], v145 offset:37888
	ds_read_b128 v[204:207], v145 offset:38912
	ds_read_b128 v[208:211], v145 offset:39936
	global_load_lds_dwordx4 v134, s[46:47]
	s_mov_b32 m0, s56
	s_nop 0
	global_load_lds_dwordx4 v130, s[46:47]
	s_waitcnt vmcnt(8)
	s_waitcnt lgkmcnt(0)
	s_barrier
	s_waitcnt lgkmcnt(0)
	v_mfma_f32_16x16x32_bf16 v[116:119], v[148:151], v[180:183], v[116:119]
	v_mfma_f32_16x16x32_bf16 v[112:115], v[156:159], v[180:183], v[112:115]
	v_mfma_f32_16x16x32_bf16 v[108:111], v[148:151], v[188:191], v[108:111]
	v_mfma_f32_16x16x32_bf16 v[104:107], v[156:159], v[188:191], v[104:107]
	v_mfma_f32_16x16x32_bf16 v[92:95], v[148:151], v[196:199], v[92:95]
	v_mfma_f32_16x16x32_bf16 v[88:91], v[156:159], v[196:199], v[88:91]
	v_mfma_f32_16x16x32_bf16 v[76:79], v[148:151], v[204:207], v[76:79]
	v_mfma_f32_16x16x32_bf16 v[72:75], v[156:159], v[204:207], v[72:75]
	v_mfma_f32_16x16x32_bf16 v[116:119], v[152:155], v[184:187], v[116:119]
	v_mfma_f32_16x16x32_bf16 v[112:115], v[160:163], v[184:187], v[112:115]
	v_mfma_f32_16x16x32_bf16 v[108:111], v[152:155], v[192:195], v[108:111]
	v_mfma_f32_16x16x32_bf16 v[104:107], v[160:163], v[192:195], v[104:107]
	v_mfma_f32_16x16x32_bf16 v[92:95], v[152:155], v[200:203], v[92:95]
	v_mfma_f32_16x16x32_bf16 v[88:91], v[160:163], v[200:203], v[88:91]
	v_mfma_f32_16x16x32_bf16 v[76:79], v[152:155], v[208:211], v[76:79]
	v_mfma_f32_16x16x32_bf16 v[72:75], v[160:163], v[208:211], v[72:75]
	v_mfma_f32_16x16x32_bf16 v[124:127], v[164:167], v[180:183], v[124:127]
	v_mfma_f32_16x16x32_bf16 v[120:123], v[172:175], v[180:183], v[120:123]
	v_mfma_f32_16x16x32_bf16 v[100:103], v[164:167], v[188:191], v[100:103]
	v_mfma_f32_16x16x32_bf16 v[96:99], v[172:175], v[188:191], v[96:99]
	v_mfma_f32_16x16x32_bf16 v[84:87], v[164:167], v[196:199], v[84:87]
	v_mfma_f32_16x16x32_bf16 v[80:83], v[172:175], v[196:199], v[80:83]
	v_mfma_f32_16x16x32_bf16 v[68:71], v[164:167], v[204:207], v[68:71]
	v_mfma_f32_16x16x32_bf16 v[64:67], v[172:175], v[204:207], v[64:67]
	v_mfma_f32_16x16x32_bf16 v[124:127], v[168:171], v[184:187], v[124:127]
	v_mfma_f32_16x16x32_bf16 v[120:123], v[176:179], v[184:187], v[120:123]
	v_mfma_f32_16x16x32_bf16 v[100:103], v[168:171], v[192:195], v[100:103]
	v_mfma_f32_16x16x32_bf16 v[96:99], v[176:179], v[192:195], v[96:99]
	v_mfma_f32_16x16x32_bf16 v[84:87], v[168:171], v[200:203], v[84:87]
	v_mfma_f32_16x16x32_bf16 v[80:83], v[176:179], v[200:203], v[80:83]
	v_mfma_f32_16x16x32_bf16 v[68:71], v[168:171], v[208:211], v[68:71]
	v_mfma_f32_16x16x32_bf16 v[64:67], v[176:179], v[208:211], v[64:67]
	s_barrier
	s_add_u32 s42, s42, s44
	s_addc_u32 s43, s43, s45
	s_add_i32 s13, s13, s51
	s_mov_b32 m0, s13
	ds_read_b128 v[180:183], v145 offset:49152
	ds_read_b128 v[184:187], v145 offset:50176
	ds_read_b128 v[188:191], v145 offset:51200
	ds_read_b128 v[192:195], v145 offset:52224
	ds_read_b128 v[196:199], v145 offset:53248
	ds_read_b128 v[200:203], v145 offset:54272
	ds_read_b128 v[204:207], v145 offset:55296
	ds_read_b128 v[208:211], v145 offset:56320
	global_load_lds_dwordx4 v132, s[42:43]
	s_add_i32 m0, s13, 0x2000
	s_nop 0
	global_load_lds_dwordx4 v128, s[42:43]
	s_add_u32 s42, s42, 0x80000
	s_addc_u32 s43, s43, 0
	s_add_i32 s13, s67, s51
	s_mov_b32 m0, s13
	s_nop 0
	global_load_lds_dwordx4 v132, s[42:43]
	s_add_i32 m0, s13, 0x2000
	s_nop 0
	global_load_lds_dwordx4 v128, s[42:43]
	s_mov_b32 m0, s57
	s_nop 0
	global_load_lds_dwordx4 v134, s[48:49]
	s_mov_b32 m0, s58
	s_nop 0
	global_load_lds_dwordx4 v130, s[48:49]
	s_waitcnt vmcnt(8)
	s_waitcnt lgkmcnt(0)
	s_barrier
	s_waitcnt lgkmcnt(0)
	v_mfma_f32_16x16x32_bf16 v[60:63], v[148:151], v[180:183], v[60:63]
	v_mfma_f32_16x16x32_bf16 v[56:59], v[156:159], v[180:183], v[56:59]
	v_mfma_f32_16x16x32_bf16 v[44:47], v[148:151], v[188:191], v[44:47]
	v_mfma_f32_16x16x32_bf16 v[40:43], v[156:159], v[188:191], v[40:43]
	v_mfma_f32_16x16x32_bf16 v[28:31], v[148:151], v[196:199], v[28:31]
	v_mfma_f32_16x16x32_bf16 v[24:27], v[156:159], v[196:199], v[24:27]
	v_mfma_f32_16x16x32_bf16 v[12:15], v[148:151], v[204:207], v[12:15]
	v_mfma_f32_16x16x32_bf16 v[8:11], v[156:159], v[204:207], v[8:11]
	v_mfma_f32_16x16x32_bf16 v[60:63], v[152:155], v[184:187], v[60:63]
	v_mfma_f32_16x16x32_bf16 v[56:59], v[160:163], v[184:187], v[56:59]
	v_mfma_f32_16x16x32_bf16 v[44:47], v[152:155], v[192:195], v[44:47]
	v_mfma_f32_16x16x32_bf16 v[40:43], v[160:163], v[192:195], v[40:43]
	v_mfma_f32_16x16x32_bf16 v[28:31], v[152:155], v[200:203], v[28:31]
	v_mfma_f32_16x16x32_bf16 v[24:27], v[160:163], v[200:203], v[24:27]
	v_mfma_f32_16x16x32_bf16 v[12:15], v[152:155], v[208:211], v[12:15]
	v_mfma_f32_16x16x32_bf16 v[8:11], v[160:163], v[208:211], v[8:11]
	v_mfma_f32_16x16x32_bf16 v[52:55], v[164:167], v[180:183], v[52:55]
	v_mfma_f32_16x16x32_bf16 v[48:51], v[172:175], v[180:183], v[48:51]
	v_mfma_f32_16x16x32_bf16 v[36:39], v[164:167], v[188:191], v[36:39]
	v_mfma_f32_16x16x32_bf16 v[32:35], v[172:175], v[188:191], v[32:35]
	v_mfma_f32_16x16x32_bf16 v[20:23], v[164:167], v[196:199], v[20:23]
	v_mfma_f32_16x16x32_bf16 v[16:19], v[172:175], v[196:199], v[16:19]
	v_mfma_f32_16x16x32_bf16 v[4:7], v[164:167], v[204:207], v[4:7]
	v_mfma_f32_16x16x32_bf16 v[0:3], v[172:175], v[204:207], v[0:3]
	v_mfma_f32_16x16x32_bf16 v[52:55], v[168:171], v[184:187], v[52:55]
	v_mfma_f32_16x16x32_bf16 v[48:51], v[176:179], v[184:187], v[48:51]
	v_mfma_f32_16x16x32_bf16 v[36:39], v[168:171], v[192:195], v[36:39]
	v_mfma_f32_16x16x32_bf16 v[32:35], v[176:179], v[192:195], v[32:35]
	v_mfma_f32_16x16x32_bf16 v[20:23], v[168:171], v[200:203], v[20:23]
	v_mfma_f32_16x16x32_bf16 v[16:19], v[176:179], v[200:203], v[16:19]
	v_mfma_f32_16x16x32_bf16 v[4:7], v[168:171], v[208:211], v[4:7]
	v_mfma_f32_16x16x32_bf16 v[0:3], v[176:179], v[208:211], v[0:3]
	s_barrier
	s_cmp_gt_u32 s66, 29
	s_mov_b32 s66, s11
	s_cbranch_scc1 .LBB0_671

; #define PG8_STAGE(bufoff, gbase, voff) do { _Pragma("unroll") for (int _i = 0; _i < 2; ++_i) \
;         __builtin_amdgcn_global_load_lds((const unsigned*)((const char*)(gbase) + (voff)[_i]), (LAS unsigned*)(lds + (bufoff) + ldsw + _i * 8192), 16, 0, 0); } while (0)
; #define PG8_LDA(dst, b, h) do { _Pragma("unroll") for (int m = 0; m < 4; ++m) _Pragma("unroll") for (int k = 0; k < 2; ++k) dst[m][k] = *(const LAS bf16x8*)(lds + PG8_SA(b, h) + aoff + m * 2048 + k * 1024); } while (0)
; #define PG8_LDB(dst, b, h) do { _Pragma("unroll") for (int n = 0; n < 2; ++n) _Pragma("unroll") for (int k = 0; k < 2; ++k) dst[n][k] = *(const LAS bf16x8*)(lds + PG8_SB(b, h) + boff + n * 2048 + k * 1024); } while (0)
; #define PG8_MMA(ai, bj, At, Bt) do { __builtin_amdgcn_s_setprio(1); _Pragma("unroll") for (int m = 0; m < 4; ++m) _Pragma("unroll") for (int n = 0; n < 2; ++n) _Pragma("unroll") for (int k = 0; k < 2; ++k) \
;         acc[ai][bj][m][n] = __builtin_amdgcn_mfma_f32_16x16x32_bf16(Bt[n][k], At[m][k], acc[ai][bj][m][n], 0, 0, 0); __builtin_amdgcn_s_setprio(0); } while (0)
; #define PG8_WAIT_V(n) asm volatile("s_waitcnt vmcnt(" #n ")" ::: "memory")
; #define PG8_WAIT_L(n) asm volatile("s_waitcnt lgkmcnt(" #n ")" ::: "memory")
; #define PG8_BAR __builtin_amdgcn_s_barrier()
; #define PG8_SCHED __builtin_amdgcn_sched_barrier(0)
; template <class Epi>
; __device__ __forceinline__ void gemm_phase(LAS unsigned char* lds, const Gemm g, const StaticOrder S, const Epi E) {
;     ...
;             const char* a1 = cA + (long)(t + 1) * ksc;
;             const char* a2 = last ? nA : cA + (long)(t + 2) * ksc; const char* b2 = last ? nB : cB + (long)(t + 2) * ksc;
;             const long ks3 = last ? ksn : ksc;
;             const char* a3 = a2 + ks3; const char* b3 = b2 + ks3;
;             PG8_LDB(B0, 0, 0); PG8_LDB(B1, 0, 1); PG8_SCHED; PG8_LDA(At, 0, 0); PG8_STAGE(PG8_SA(1, 1), a1 + hstepA, voffA);
;             PG8_WAIT_V(8); PG8_WAIT_L(0); PG8_BAR; PG8_MMA(0, 0, At, B0); PG8_MMA(0, 1, At, B1); PG8_BAR; PG8_SCHED;
;             PG8_LDA(At, 0, 1); PG8_STAGE(PG8_SB(0, 0), b2, voffB); PG8_STAGE(PG8_SB(0, 1), b2 + hstepB, voffB); PG8_STAGE(PG8_SA(0, 0), a2, voffA);
;             PG8_WAIT_V(8); PG8_WAIT_L(0); PG8_BAR; PG8_MMA(1, 0, At, B0); PG8_MMA(1, 1, At, B1); PG8_BAR; PG8_SCHED;
.LBB0_753:
	v_add_u32_e32 v152, s60, v164
	v_add_u32_e32 v176, s61, v164
	ds_read_b128 v[128:131], v152
	ds_read_b128 v[132:135], v152 offset:1024
	ds_read_b128 v[136:139], v152 offset:2048
	ds_read_b128 v[152:155], v152 offset:3072
	ds_read_b128 v[156:159], v176
	ds_read_b128 v[168:171], v176 offset:1024
	ds_read_b128 v[172:175], v176 offset:2048
	ds_read_b128 v[176:179], v176 offset:3072
	s_or_b32 s48, s71, 1
	s_mul_i32 s49, s35, s48
	s_mul_hi_u32 s73, s34, s48
	s_add_i32 s73, s73, s49
	s_mul_i32 s48, s34, s48
	s_add_u32 s74, s30, s48
	s_addc_u32 s73, s31, s73
	s_add_u32 s48, s46, s44
	s_addc_u32 s49, s47, s45
	s_add_u32 s74, s74, 0x160000
	s_addc_u32 s75, s73, 0
	s_add_i32 m0, s52, 0xc000
	ds_read_b128 v[180:183], v166
	ds_read_b128 v[184:187], v166 offset:1024
	ds_read_b128 v[188:191], v166 offset:2048
	ds_read_b128 v[192:195], v166 offset:3072
	ds_read_b128 v[196:199], v166 offset:4096
	ds_read_b128 v[200:203], v166 offset:5120
	ds_read_b128 v[204:207], v166 offset:6144
	ds_read_b128 v[208:211], v166 offset:7168
	global_load_lds_dwordx4 v140, s[74:75]
	s_add_i32 m0, s52, 0xe000
	s_nop 0
	global_load_lds_dwordx4 v144, s[74:75]
	s_waitcnt vmcnt(8)
	s_waitcnt lgkmcnt(0)
	s_barrier
	s_waitcnt lgkmcnt(0)
	v_mfma_f32_16x16x32_bf16 v[124:127], v[128:131], v[180:183], v[124:127]
	v_mfma_f32_16x16x32_bf16 v[120:123], v[136:139], v[180:183], v[120:123]
	v_mfma_f32_16x16x32_bf16 v[108:111], v[128:131], v[188:191], v[108:111]
	v_mfma_f32_16x16x32_bf16 v[104:107], v[136:139], v[188:191], v[104:107]
	v_mfma_f32_16x16x32_bf16 v[92:95], v[128:131], v[196:199], v[92:95]
	v_mfma_f32_16x16x32_bf16 v[88:91], v[136:139], v[196:199], v[88:91]
	v_mfma_f32_16x16x32_bf16 v[76:79], v[128:131], v[204:207], v[76:79]
	v_mfma_f32_16x16x32_bf16 v[72:75], v[136:139], v[204:207], v[72:75]
	v_mfma_f32_16x16x32_bf16 v[124:127], v[132:135], v[184:187], v[124:127]
	v_mfma_f32_16x16x32_bf16 v[120:123], v[152:155], v[184:187], v[120:123]
	v_mfma_f32_16x16x32_bf16 v[108:111], v[132:135], v[192:195], v[108:111]
	v_mfma_f32_16x16x32_bf16 v[104:107], v[152:155], v[192:195], v[104:107]
	v_mfma_f32_16x16x32_bf16 v[92:95], v[132:135], v[200:203], v[92:95]
	v_mfma_f32_16x16x32_bf16 v[88:91], v[152:155], v[200:203], v[88:91]
	v_mfma_f32_16x16x32_bf16 v[76:79], v[132:135], v[208:211], v[76:79]
	v_mfma_f32_16x16x32_bf16 v[72:75], v[152:155], v[208:211], v[72:75]
	v_mfma_f32_16x16x32_bf16 v[116:119], v[156:159], v[180:183], v[116:119]
	v_mfma_f32_16x16x32_bf16 v[112:115], v[172:175], v[180:183], v[112:115]
	v_mfma_f32_16x16x32_bf16 v[100:103], v[156:159], v[188:191], v[100:103]
	v_mfma_f32_16x16x32_bf16 v[96:99], v[172:175], v[188:191], v[96:99]
	v_mfma_f32_16x16x32_bf16 v[84:87], v[156:159], v[196:199], v[84:87]
	v_mfma_f32_16x16x32_bf16 v[80:83], v[172:175], v[196:199], v[80:83]
	v_mfma_f32_16x16x32_bf16 v[68:71], v[156:159], v[204:207], v[68:71]
	v_mfma_f32_16x16x32_bf16 v[64:67], v[172:175], v[204:207], v[64:67]
	v_mfma_f32_16x16x32_bf16 v[116:119], v[168:171], v[184:187], v[116:119]
	v_mfma_f32_16x16x32_bf16 v[112:115], v[176:179], v[184:187], v[112:115]
	v_mfma_f32_16x16x32_bf16 v[100:103], v[168:171], v[192:195], v[100:103]
	v_mfma_f32_16x16x32_bf16 v[96:99], v[176:179], v[192:195], v[96:99]
	v_mfma_f32_16x16x32_bf16 v[84:87], v[168:171], v[200:203], v[84:87]
	v_mfma_f32_16x16x32_bf16 v[80:83], v[176:179], v[200:203], v[80:83]
	v_mfma_f32_16x16x32_bf16 v[68:71], v[168:171], v[208:211], v[68:71]
	v_mfma_f32_16x16x32_bf16 v[64:67], v[176:179], v[208:211], v[64:67]
	s_barrier
	s_add_i32 s73, s60, s51
	s_mov_b32 m0, s73
	ds_read_b128 v[180:183], v166 offset:16384
	ds_read_b128 v[184:187], v166 offset:17408
	ds_read_b128 v[188:191], v166 offset:18432
	ds_read_b128 v[192:195], v166 offset:19456
	ds_read_b128 v[196:199], v166 offset:20480
	ds_read_b128 v[200:203], v166 offset:21504
	ds_read_b128 v[204:207], v166 offset:22528
	ds_read_b128 v[208:211], v166 offset:23552
	global_load_lds_dwordx4 v142, s[42:43]
	s_add_i32 m0, s73, 0x2000
	s_add_u32 s74, s42, 0x160000
	s_addc_u32 s75, s43, 0
	s_add_i32 s73, s61, s51
	global_load_lds_dwordx4 v146, s[42:43]
	s_mov_b32 m0, s73
	s_nop 0
	global_load_lds_dwordx4 v142, s[74:75]
	s_add_i32 m0, s73, 0x2000
	s_nop 0
	global_load_lds_dwordx4 v146, s[74:75]
	s_mov_b32 m0, s52
	s_nop 0
	global_load_lds_dwordx4 v140, s[46:47]
	s_mov_b32 m0, s53
	s_nop 0
	global_load_lds_dwordx4 v144, s[46:47]
	s_waitcnt vmcnt(8)
	s_waitcnt lgkmcnt(0)
	s_barrier
	s_waitcnt lgkmcnt(0)
	v_mfma_f32_16x16x32_bf16 v[60:63], v[128:131], v[180:183], v[60:63]
	v_mfma_f32_16x16x32_bf16 v[56:59], v[136:139], v[180:183], v[56:59]
	v_mfma_f32_16x16x32_bf16 v[44:47], v[128:131], v[188:191], v[44:47]
	v_mfma_f32_16x16x32_bf16 v[40:43], v[136:139], v[188:191], v[40:43]
	v_mfma_f32_16x16x32_bf16 v[28:31], v[128:131], v[196:199], v[28:31]
	v_mfma_f32_16x16x32_bf16 v[24:27], v[136:139], v[196:199], v[24:27]
	v_mfma_f32_16x16x32_bf16 v[12:15], v[128:131], v[204:207], v[12:15]
	v_mfma_f32_16x16x32_bf16 v[8:11], v[136:139], v[204:207], v[8:11]
	v_mfma_f32_16x16x32_bf16 v[60:63], v[132:135], v[184:187], v[60:63]
	v_mfma_f32_16x16x32_bf16 v[56:59], v[152:155], v[184:187], v[56:59]
	v_mfma_f32_16x16x32_bf16 v[44:47], v[132:135], v[192:195], v[44:47]
	v_mfma_f32_16x16x32_bf16 v[40:43], v[152:155], v[192:195], v[40:43]
	v_mfma_f32_16x16x32_bf16 v[28:31], v[132:135], v[200:203], v[28:31]
	v_mfma_f32_16x16x32_bf16 v[24:27], v[152:155], v[200:203], v[24:27]
	v_mfma_f32_16x16x32_bf16 v[12:15], v[132:135], v[208:211], v[12:15]
	v_mfma_f32_16x16x32_bf16 v[8:11], v[152:155], v[208:211], v[8:11]
	v_mfma_f32_16x16x32_bf16 v[52:55], v[156:159], v[180:183], v[52:55]
	v_mfma_f32_16x16x32_bf16 v[48:51], v[172:175], v[180:183], v[48:51]
	v_mfma_f32_16x16x32_bf16 v[36:39], v[156:159], v[188:191], v[36:39]
	v_mfma_f32_16x16x32_bf16 v[32:35], v[172:175], v[188:191], v[32:35]
	v_mfma_f32_16x16x32_bf16 v[20:23], v[156:159], v[196:199], v[20:23]
	v_mfma_f32_16x16x32_bf16 v[16:19], v[172:175], v[196:199], v[16:19]
	v_mfma_f32_16x16x32_bf16 v[4:7], v[156:159], v[204:207], v[4:7]
	v_mfma_f32_16x16x32_bf16 v[0:3], v[172:175], v[204:207], v[0:3]
	v_mfma_f32_16x16x32_bf16 v[52:55], v[168:171], v[184:187], v[52:55]
	v_mfma_f32_16x16x32_bf16 v[48:51], v[176:179], v[184:187], v[48:51]
	v_mfma_f32_16x16x32_bf16 v[36:39], v[168:171], v[192:195], v[36:39]
	v_mfma_f32_16x16x32_bf16 v[32:35], v[176:179], v[192:195], v[32:35]
	v_mfma_f32_16x16x32_bf16 v[20:23], v[168:171], v[200:203], v[20:23]
	v_mfma_f32_16x16x32_bf16 v[16:19], v[176:179], v[200:203], v[16:19]
	v_mfma_f32_16x16x32_bf16 v[4:7], v[168:171], v[208:211], v[4:7]
	v_mfma_f32_16x16x32_bf16 v[0:3], v[176:179], v[208:211], v[0:3]
	s_barrier
; #define PG8_STAGE(bufoff, gbase, voff) do { _Pragma("unroll") for (int _i = 0; _i < 2; ++_i) \
;         __builtin_amdgcn_global_load_lds((const unsigned*)((const char*)(gbase) + (voff)[_i]), (LAS unsigned*)(lds + (bufoff) + ldsw + _i * 8192), 16, 0, 0); } while (0)
; #define PG8_LDA(dst, b, h) do { _Pragma("unroll") for (int m = 0; m < 4; ++m) _Pragma("unroll") for (int k = 0; k < 2; ++k) dst[m][k] = *(const LAS bf16x8*)(lds + PG8_SA(b, h) + aoff + m * 2048 + k * 1024); } while (0)
; #define PG8_LDB(dst, b, h) do { _Pragma("unroll") for (int n = 0; n < 2; ++n) _Pragma("unroll") for (int k = 0; k < 2; ++k) dst[n][k] = *(const LAS bf16x8*)(lds + PG8_SB(b, h) + boff + n * 2048 + k * 1024); } while (0)
; #define PG8_MMA(ai, bj, At, Bt) do { __builtin_amdgcn_s_setprio(1); _Pragma("unroll") for (int m = 0; m < 4; ++m) _Pragma("unroll") for (int n = 0; n < 2; ++n) _Pragma("unroll") for (int k = 0; k < 2; ++k) \
;         acc[ai][bj][m][n] = __builtin_amdgcn_mfma_f32_16x16x32_bf16(Bt[n][k], At[m][k], acc[ai][bj][m][n], 0, 0, 0); __builtin_amdgcn_s_setprio(0); } while (0)
; #define PG8_WAIT_V(n) asm volatile("s_waitcnt vmcnt(" #n ")" ::: "memory")
; #define PG8_WAIT_L(n) asm volatile("s_waitcnt lgkmcnt(" #n ")" ::: "memory")
; #define PG8_BAR __builtin_amdgcn_s_barrier()
; #define PG8_SCHED __builtin_amdgcn_sched_barrier(0)
; template <class Epi>
; __device__ __forceinline__ void gemm_phase(LAS unsigned char* lds, const Gemm g, const StaticOrder S, const Epi E) {
;     ...
;             PG8_LDB(B0, 1, 0); PG8_LDB(B1, 1, 1); PG8_SCHED; PG8_LDA(At, 1, 0); PG8_STAGE(PG8_SA(0, 1), a2 + hstepA, voffA);
;             PG8_WAIT_V(8); PG8_WAIT_L(0); PG8_BAR; PG8_MMA(0, 0, At, B0); PG8_MMA(0, 1, At, B1); PG8_BAR; PG8_SCHED;
;             PG8_LDA(At, 1, 1); PG8_STAGE(PG8_SB(1, 0), b3, voffB); PG8_STAGE(PG8_SB(1, 1), b3 + hstepB, voffB); PG8_STAGE(PG8_SA(1, 0), a3, voffA);
;             PG8_WAIT_V(8); PG8_WAIT_L(0); PG8_BAR; PG8_MMA(1, 0, At, B0); PG8_MMA(1, 1, At, B1); PG8_BAR; PG8_SCHED;
;         }
	s_add_i32 s73, 0, 0x18000
	s_add_i32 s74, 0, 0x1c000
	v_add_u32_e32 v152, s73, v164
	v_add_u32_e32 v176, s74, v164
	ds_read_b128 v[128:131], v152
	ds_read_b128 v[132:135], v152 offset:1024
	ds_read_b128 v[136:139], v152 offset:2048
	ds_read_b128 v[152:155], v152 offset:3072
	ds_read_b128 v[156:159], v176
	ds_read_b128 v[168:171], v176 offset:1024
	ds_read_b128 v[172:175], v176 offset:2048
	ds_read_b128 v[176:179], v176 offset:3072
	s_add_u32 s46, s46, 0x160000
	s_addc_u32 s47, s47, 0
	s_mov_b32 m0, s54
	ds_read_b128 v[180:183], v166 offset:32768
	ds_read_b128 v[184:187], v166 offset:33792
	ds_read_b128 v[188:191], v166 offset:34816
	ds_read_b128 v[192:195], v166 offset:35840
	ds_read_b128 v[196:199], v166 offset:36864
	ds_read_b128 v[200:203], v166 offset:37888
	ds_read_b128 v[204:207], v166 offset:38912
	ds_read_b128 v[208:211], v166 offset:39936
	global_load_lds_dwordx4 v140, s[46:47]
	s_mov_b32 m0, s55
	s_nop 0
	global_load_lds_dwordx4 v144, s[46:47]
	s_waitcnt vmcnt(8)
	s_waitcnt lgkmcnt(0)
	s_barrier
	s_waitcnt lgkmcnt(0)
	v_mfma_f32_16x16x32_bf16 v[124:127], v[128:131], v[180:183], v[124:127]
	v_mfma_f32_16x16x32_bf16 v[120:123], v[136:139], v[180:183], v[120:123]
	v_mfma_f32_16x16x32_bf16 v[108:111], v[128:131], v[188:191], v[108:111]
	v_mfma_f32_16x16x32_bf16 v[104:107], v[136:139], v[188:191], v[104:107]
	v_mfma_f32_16x16x32_bf16 v[92:95], v[128:131], v[196:199], v[92:95]
	v_mfma_f32_16x16x32_bf16 v[88:91], v[136:139], v[196:199], v[88:91]
	v_mfma_f32_16x16x32_bf16 v[76:79], v[128:131], v[204:207], v[76:79]
	v_mfma_f32_16x16x32_bf16 v[72:75], v[136:139], v[204:207], v[72:75]
	v_mfma_f32_16x16x32_bf16 v[124:127], v[132:135], v[184:187], v[124:127]
	v_mfma_f32_16x16x32_bf16 v[120:123], v[152:155], v[184:187], v[120:123]
	v_mfma_f32_16x16x32_bf16 v[108:111], v[132:135], v[192:195], v[108:111]
	v_mfma_f32_16x16x32_bf16 v[104:107], v[152:155], v[192:195], v[104:107]
	v_mfma_f32_16x16x32_bf16 v[92:95], v[132:135], v[200:203], v[92:95]
	v_mfma_f32_16x16x32_bf16 v[88:91], v[152:155], v[200:203], v[88:91]
	v_mfma_f32_16x16x32_bf16 v[76:79], v[132:135], v[208:211], v[76:79]
	v_mfma_f32_16x16x32_bf16 v[72:75], v[152:155], v[208:211], v[72:75]
	v_mfma_f32_16x16x32_bf16 v[116:119], v[156:159], v[180:183], v[116:119]
	v_mfma_f32_16x16x32_bf16 v[112:115], v[172:175], v[180:183], v[112:115]
	v_mfma_f32_16x16x32_bf16 v[100:103], v[156:159], v[188:191], v[100:103]
	v_mfma_f32_16x16x32_bf16 v[96:99], v[172:175], v[188:191], v[96:99]
	v_mfma_f32_16x16x32_bf16 v[84:87], v[156:159], v[196:199], v[84:87]
	v_mfma_f32_16x16x32_bf16 v[80:83], v[172:175], v[196:199], v[80:83]
	v_mfma_f32_16x16x32_bf16 v[68:71], v[156:159], v[204:207], v[68:71]
	v_mfma_f32_16x16x32_bf16 v[64:67], v[172:175], v[204:207], v[64:67]
	v_mfma_f32_16x16x32_bf16 v[116:119], v[168:171], v[184:187], v[116:119]
	v_mfma_f32_16x16x32_bf16 v[112:115], v[176:179], v[184:187], v[112:115]
	v_mfma_f32_16x16x32_bf16 v[100:103], v[168:171], v[192:195], v[100:103]
	v_mfma_f32_16x16x32_bf16 v[96:99], v[176:179], v[192:195], v[96:99]
	v_mfma_f32_16x16x32_bf16 v[84:87], v[168:171], v[200:203], v[84:87]
	v_mfma_f32_16x16x32_bf16 v[80:83], v[176:179], v[200:203], v[80:83]
	v_mfma_f32_16x16x32_bf16 v[68:71], v[168:171], v[208:211], v[68:71]
	v_mfma_f32_16x16x32_bf16 v[64:67], v[176:179], v[208:211], v[64:67]
	s_barrier
	s_add_u32 s42, s42, s44
	s_addc_u32 s43, s43, s45
	s_add_i32 s44, s73, s51
	s_mov_b32 m0, s44
	ds_read_b128 v[180:183], v166 offset:49152
	ds_read_b128 v[184:187], v166 offset:50176
	ds_read_b128 v[188:191], v166 offset:51200
	ds_read_b128 v[192:195], v166 offset:52224
	ds_read_b128 v[196:199], v166 offset:53248
	ds_read_b128 v[200:203], v166 offset:54272
	ds_read_b128 v[204:207], v166 offset:55296
	ds_read_b128 v[208:211], v166 offset:56320
	global_load_lds_dwordx4 v142, s[42:43]
	s_add_i32 m0, s44, 0x2000
	s_nop 0
	global_load_lds_dwordx4 v146, s[42:43]
	s_add_u32 s42, s42, 0x160000
	s_addc_u32 s43, s43, 0
	s_add_i32 s44, s74, s51
	s_mov_b32 m0, s44
	s_nop 0
	global_load_lds_dwordx4 v142, s[42:43]
	s_add_i32 m0, s44, 0x2000
	s_nop 0
	global_load_lds_dwordx4 v146, s[42:43]
	s_mov_b32 m0, s57
	s_nop 0
	global_load_lds_dwordx4 v140, s[48:49]
	s_mov_b32 m0, s58
	s_nop 0
	global_load_lds_dwordx4 v144, s[48:49]
	s_waitcnt vmcnt(8)
	s_waitcnt lgkmcnt(0)
	s_barrier
	s_waitcnt lgkmcnt(0)
	v_mfma_f32_16x16x32_bf16 v[60:63], v[128:131], v[180:183], v[60:63]
	v_mfma_f32_16x16x32_bf16 v[56:59], v[136:139], v[180:183], v[56:59]
	v_mfma_f32_16x16x32_bf16 v[44:47], v[128:131], v[188:191], v[44:47]
	v_mfma_f32_16x16x32_bf16 v[40:43], v[136:139], v[188:191], v[40:43]
	v_mfma_f32_16x16x32_bf16 v[28:31], v[128:131], v[196:199], v[28:31]
	v_mfma_f32_16x16x32_bf16 v[24:27], v[136:139], v[196:199], v[24:27]
	v_mfma_f32_16x16x32_bf16 v[12:15], v[128:131], v[204:207], v[12:15]
	v_mfma_f32_16x16x32_bf16 v[8:11], v[136:139], v[204:207], v[8:11]
	v_mfma_f32_16x16x32_bf16 v[60:63], v[132:135], v[184:187], v[60:63]
	v_mfma_f32_16x16x32_bf16 v[56:59], v[152:155], v[184:187], v[56:59]
	v_mfma_f32_16x16x32_bf16 v[44:47], v[132:135], v[192:195], v[44:47]
	v_mfma_f32_16x16x32_bf16 v[40:43], v[152:155], v[192:195], v[40:43]
	v_mfma_f32_16x16x32_bf16 v[28:31], v[132:135], v[200:203], v[28:31]
	v_mfma_f32_16x16x32_bf16 v[24:27], v[152:155], v[200:203], v[24:27]
	v_mfma_f32_16x16x32_bf16 v[12:15], v[132:135], v[208:211], v[12:15]
	v_mfma_f32_16x16x32_bf16 v[8:11], v[152:155], v[208:211], v[8:11]
	v_mfma_f32_16x16x32_bf16 v[52:55], v[156:159], v[180:183], v[52:55]
	v_mfma_f32_16x16x32_bf16 v[48:51], v[172:175], v[180:183], v[48:51]
	v_mfma_f32_16x16x32_bf16 v[36:39], v[156:159], v[188:191], v[36:39]
	v_mfma_f32_16x16x32_bf16 v[32:35], v[172:175], v[188:191], v[32:35]
	v_mfma_f32_16x16x32_bf16 v[20:23], v[156:159], v[196:199], v[20:23]
	v_mfma_f32_16x16x32_bf16 v[16:19], v[172:175], v[196:199], v[16:19]
	v_mfma_f32_16x16x32_bf16 v[4:7], v[156:159], v[204:207], v[4:7]
	v_mfma_f32_16x16x32_bf16 v[0:3], v[172:175], v[204:207], v[0:3]
	v_mfma_f32_16x16x32_bf16 v[52:55], v[168:171], v[184:187], v[52:55]
	v_mfma_f32_16x16x32_bf16 v[48:51], v[176:179], v[184:187], v[48:51]
	v_mfma_f32_16x16x32_bf16 v[36:39], v[168:171], v[192:195], v[36:39]
	v_mfma_f32_16x16x32_bf16 v[32:35], v[176:179], v[192:195], v[32:35]
	v_mfma_f32_16x16x32_bf16 v[20:23], v[168:171], v[200:203], v[20:23]
	v_mfma_f32_16x16x32_bf16 v[16:19], v[176:179], v[200:203], v[16:19]
	v_mfma_f32_16x16x32_bf16 v[4:7], v[168:171], v[208:211], v[4:7]
	v_mfma_f32_16x16x32_bf16 v[0:3], v[176:179], v[208:211], v[0:3]
	s_barrier
	s_cmpk_gt_u32 s71, 0x55
	s_mov_b32 s71, s72
	s_cbranch_scc1 .LBB0_758

; #define PG8_STAGE(bufoff, gbase, voff) do { _Pragma("unroll") for (int _i = 0; _i < 2; ++_i) \
;         __builtin_amdgcn_global_load_lds((const unsigned*)((const char*)(gbase) + (voff)[_i]), (LAS unsigned*)(lds + (bufoff) + ldsw + _i * 8192), 16, 0, 0); } while (0)
; #define PG8_LDA(dst, b, h) do { _Pragma("unroll") for (int m = 0; m < 4; ++m) _Pragma("unroll") for (int k = 0; k < 2; ++k) dst[m][k] = *(const LAS bf16x8*)(lds + PG8_SA(b, h) + aoff + m * 2048 + k * 1024); } while (0)
; #define PG8_LDB(dst, b, h) do { _Pragma("unroll") for (int n = 0; n < 2; ++n) _Pragma("unroll") for (int k = 0; k < 2; ++k) dst[n][k] = *(const LAS bf16x8*)(lds + PG8_SB(b, h) + boff + n * 2048 + k * 1024); } while (0)
; #define PG8_MMA(ai, bj, At, Bt) do { __builtin_amdgcn_s_setprio(1); _Pragma("unroll") for (int m = 0; m < 4; ++m) _Pragma("unroll") for (int n = 0; n < 2; ++n) _Pragma("unroll") for (int k = 0; k < 2; ++k) \
;         acc[ai][bj][m][n] = __builtin_amdgcn_mfma_f32_16x16x32_bf16(Bt[n][k], At[m][k], acc[ai][bj][m][n], 0, 0, 0); __builtin_amdgcn_s_setprio(0); } while (0)
; #define PG8_WAIT_V(n) asm volatile("s_waitcnt vmcnt(" #n ")" ::: "memory")
; #define PG8_WAIT_L(n) asm volatile("s_waitcnt lgkmcnt(" #n ")" ::: "memory")
; #define PG8_BAR __builtin_amdgcn_s_barrier()
; #define PG8_SCHED __builtin_amdgcn_sched_barrier(0)
; template <class Epi>
; __device__ __forceinline__ void gemm_phase(LAS unsigned char* lds, const Gemm g, const StaticOrder S, const Epi E) {
;     ...
;             const char* a1 = cA + (long)(t + 1) * ksc;
;             const char* a2 = last ? nA : cA + (long)(t + 2) * ksc; const char* b2 = last ? nB : cB + (long)(t + 2) * ksc;
;             const long ks3 = last ? ksn : ksc;
;             const char* a3 = a2 + ks3; const char* b3 = b2 + ks3;
;             PG8_LDB(B0, 0, 0); PG8_LDB(B1, 0, 1); PG8_SCHED; PG8_LDA(At, 0, 0); PG8_STAGE(PG8_SA(1, 1), a1 + hstepA, voffA);
;             PG8_WAIT_V(8); PG8_WAIT_L(0); PG8_BAR; PG8_MMA(0, 0, At, B0); PG8_MMA(0, 1, At, B1); PG8_BAR; PG8_SCHED;
;             PG8_LDA(At, 0, 1); PG8_STAGE(PG8_SB(0, 0), b2, voffB); PG8_STAGE(PG8_SB(0, 1), b2 + hstepB, voffB); PG8_STAGE(PG8_SA(0, 0), a2, voffA);
;             PG8_WAIT_V(8); PG8_WAIT_L(0); PG8_BAR; PG8_MMA(1, 0, At, B0); PG8_MMA(1, 1, At, B1); PG8_BAR; PG8_SCHED;
.LBB0_853:
	ds_read_b128 v[148:151], v254
	ds_read_b128 v[152:155], v254 offset:1024
	ds_read_b128 v[156:159], v254 offset:2048
	ds_read_b128 v[160:163], v254 offset:3072
	ds_read_b128 v[164:167], v254 offset:16384
	ds_read_b128 v[168:171], v254 offset:17408
	ds_read_b128 v[172:175], v254 offset:18432
	ds_read_b128 v[176:179], v254 offset:19456
	s_or_b32 s13, s64, 1
	s_mul_i32 s48, s27, s13
	s_mul_hi_u32 s49, s26, s13
	s_add_i32 s49, s49, s48
	s_mul_i32 s13, s26, s13
	s_add_u32 s13, s24, s13
	s_addc_u32 s65, s25, s49
	s_add_u32 s48, s46, s44
	s_addc_u32 s49, s47, s45
	s_add_u32 s66, s13, 0x80000
	s_addc_u32 s67, s65, 0
	s_add_i32 m0, s21, 0xc000
	ds_read_b128 v[180:183], v145
	ds_read_b128 v[184:187], v145 offset:1024
	ds_read_b128 v[188:191], v145 offset:2048
	ds_read_b128 v[192:195], v145 offset:3072
	ds_read_b128 v[196:199], v145 offset:4096
	ds_read_b128 v[200:203], v145 offset:5120
	ds_read_b128 v[204:207], v145 offset:6144
	ds_read_b128 v[208:211], v145 offset:7168
	global_load_lds_dwordx4 v134, s[66:67]
	s_add_i32 m0, s21, 0xe000
	s_nop 0
	global_load_lds_dwordx4 v130, s[66:67]
	s_waitcnt vmcnt(8)
	s_waitcnt lgkmcnt(0)
	s_barrier
	s_waitcnt lgkmcnt(0)
	v_mfma_f32_16x16x32_bf16 v[116:119], v[148:151], v[180:183], v[116:119]
	v_mfma_f32_16x16x32_bf16 v[112:115], v[156:159], v[180:183], v[112:115]
	v_mfma_f32_16x16x32_bf16 v[108:111], v[148:151], v[188:191], v[108:111]
	v_mfma_f32_16x16x32_bf16 v[104:107], v[156:159], v[188:191], v[104:107]
	v_mfma_f32_16x16x32_bf16 v[92:95], v[148:151], v[196:199], v[92:95]
	v_mfma_f32_16x16x32_bf16 v[88:91], v[156:159], v[196:199], v[88:91]
	v_mfma_f32_16x16x32_bf16 v[76:79], v[148:151], v[204:207], v[76:79]
	v_mfma_f32_16x16x32_bf16 v[72:75], v[156:159], v[204:207], v[72:75]
	v_mfma_f32_16x16x32_bf16 v[116:119], v[152:155], v[184:187], v[116:119]
	v_mfma_f32_16x16x32_bf16 v[112:115], v[160:163], v[184:187], v[112:115]
	v_mfma_f32_16x16x32_bf16 v[108:111], v[152:155], v[192:195], v[108:111]
	v_mfma_f32_16x16x32_bf16 v[104:107], v[160:163], v[192:195], v[104:107]
	v_mfma_f32_16x16x32_bf16 v[92:95], v[152:155], v[200:203], v[92:95]
	v_mfma_f32_16x16x32_bf16 v[88:91], v[160:163], v[200:203], v[88:91]
	v_mfma_f32_16x16x32_bf16 v[76:79], v[152:155], v[208:211], v[76:79]
	v_mfma_f32_16x16x32_bf16 v[72:75], v[160:163], v[208:211], v[72:75]
	v_mfma_f32_16x16x32_bf16 v[124:127], v[164:167], v[180:183], v[124:127]
	v_mfma_f32_16x16x32_bf16 v[120:123], v[172:175], v[180:183], v[120:123]
	v_mfma_f32_16x16x32_bf16 v[100:103], v[164:167], v[188:191], v[100:103]
	v_mfma_f32_16x16x32_bf16 v[96:99], v[172:175], v[188:191], v[96:99]
	v_mfma_f32_16x16x32_bf16 v[84:87], v[164:167], v[196:199], v[84:87]
	v_mfma_f32_16x16x32_bf16 v[80:83], v[172:175], v[196:199], v[80:83]
	v_mfma_f32_16x16x32_bf16 v[68:71], v[164:167], v[204:207], v[68:71]
	v_mfma_f32_16x16x32_bf16 v[64:67], v[172:175], v[204:207], v[64:67]
	v_mfma_f32_16x16x32_bf16 v[124:127], v[168:171], v[184:187], v[124:127]
	v_mfma_f32_16x16x32_bf16 v[120:123], v[176:179], v[184:187], v[120:123]
	v_mfma_f32_16x16x32_bf16 v[100:103], v[168:171], v[192:195], v[100:103]
	v_mfma_f32_16x16x32_bf16 v[96:99], v[176:179], v[192:195], v[96:99]
	v_mfma_f32_16x16x32_bf16 v[84:87], v[168:171], v[200:203], v[84:87]
	v_mfma_f32_16x16x32_bf16 v[80:83], v[176:179], v[200:203], v[80:83]
	v_mfma_f32_16x16x32_bf16 v[68:71], v[168:171], v[208:211], v[68:71]
	v_mfma_f32_16x16x32_bf16 v[64:67], v[176:179], v[208:211], v[64:67]
	s_barrier
	s_add_i32 s13, s59, s33
	s_mov_b32 m0, s13
	ds_read_b128 v[180:183], v145 offset:16384
	ds_read_b128 v[184:187], v145 offset:17408
	ds_read_b128 v[188:191], v145 offset:18432
	ds_read_b128 v[192:195], v145 offset:19456
	ds_read_b128 v[196:199], v145 offset:20480
	ds_read_b128 v[200:203], v145 offset:21504
	ds_read_b128 v[204:207], v145 offset:22528
	ds_read_b128 v[208:211], v145 offset:23552
	global_load_lds_dwordx4 v132, s[42:43]
	s_add_i32 m0, s13, 0x2000
	s_add_u32 s66, s42, 0x80000
	s_addc_u32 s67, s43, 0
	s_add_i32 s13, s60, s33
	global_load_lds_dwordx4 v128, s[42:43]
	s_mov_b32 m0, s13
	s_nop 0
	global_load_lds_dwordx4 v132, s[66:67]
	s_add_i32 m0, s13, 0x2000
	s_nop 0
	global_load_lds_dwordx4 v128, s[66:67]
	s_mov_b32 m0, s21
	s_nop 0
	global_load_lds_dwordx4 v134, s[46:47]
	s_mov_b32 m0, s52
	s_nop 0
	global_load_lds_dwordx4 v130, s[46:47]
	s_waitcnt vmcnt(8)
	s_waitcnt lgkmcnt(0)
	s_barrier
	s_waitcnt lgkmcnt(0)
	v_mfma_f32_16x16x32_bf16 v[60:63], v[148:151], v[180:183], v[60:63]
	v_mfma_f32_16x16x32_bf16 v[56:59], v[156:159], v[180:183], v[56:59]
	v_mfma_f32_16x16x32_bf16 v[44:47], v[148:151], v[188:191], v[44:47]
	v_mfma_f32_16x16x32_bf16 v[40:43], v[156:159], v[188:191], v[40:43]
	v_mfma_f32_16x16x32_bf16 v[28:31], v[148:151], v[196:199], v[28:31]
	v_mfma_f32_16x16x32_bf16 v[24:27], v[156:159], v[196:199], v[24:27]
	v_mfma_f32_16x16x32_bf16 v[12:15], v[148:151], v[204:207], v[12:15]
	v_mfma_f32_16x16x32_bf16 v[8:11], v[156:159], v[204:207], v[8:11]
	v_mfma_f32_16x16x32_bf16 v[60:63], v[152:155], v[184:187], v[60:63]
	v_mfma_f32_16x16x32_bf16 v[56:59], v[160:163], v[184:187], v[56:59]
	v_mfma_f32_16x16x32_bf16 v[44:47], v[152:155], v[192:195], v[44:47]
	v_mfma_f32_16x16x32_bf16 v[40:43], v[160:163], v[192:195], v[40:43]
	v_mfma_f32_16x16x32_bf16 v[28:31], v[152:155], v[200:203], v[28:31]
	v_mfma_f32_16x16x32_bf16 v[24:27], v[160:163], v[200:203], v[24:27]
	v_mfma_f32_16x16x32_bf16 v[12:15], v[152:155], v[208:211], v[12:15]
	v_mfma_f32_16x16x32_bf16 v[8:11], v[160:163], v[208:211], v[8:11]
	v_mfma_f32_16x16x32_bf16 v[52:55], v[164:167], v[180:183], v[52:55]
	v_mfma_f32_16x16x32_bf16 v[48:51], v[172:175], v[180:183], v[48:51]
	v_mfma_f32_16x16x32_bf16 v[36:39], v[164:167], v[188:191], v[36:39]
	v_mfma_f32_16x16x32_bf16 v[32:35], v[172:175], v[188:191], v[32:35]
	v_mfma_f32_16x16x32_bf16 v[20:23], v[164:167], v[196:199], v[20:23]
	v_mfma_f32_16x16x32_bf16 v[16:19], v[172:175], v[196:199], v[16:19]
	v_mfma_f32_16x16x32_bf16 v[4:7], v[164:167], v[204:207], v[4:7]
	v_mfma_f32_16x16x32_bf16 v[0:3], v[172:175], v[204:207], v[0:3]
	v_mfma_f32_16x16x32_bf16 v[52:55], v[168:171], v[184:187], v[52:55]
	v_mfma_f32_16x16x32_bf16 v[48:51], v[176:179], v[184:187], v[48:51]
	v_mfma_f32_16x16x32_bf16 v[36:39], v[168:171], v[192:195], v[36:39]
	v_mfma_f32_16x16x32_bf16 v[32:35], v[176:179], v[192:195], v[32:35]
	v_mfma_f32_16x16x32_bf16 v[20:23], v[168:171], v[200:203], v[20:23]
	v_mfma_f32_16x16x32_bf16 v[16:19], v[176:179], v[200:203], v[16:19]
	v_mfma_f32_16x16x32_bf16 v[4:7], v[168:171], v[208:211], v[4:7]
	v_mfma_f32_16x16x32_bf16 v[0:3], v[176:179], v[208:211], v[0:3]
	s_barrier
; #define PG8_STAGE(bufoff, gbase, voff) do { _Pragma("unroll") for (int _i = 0; _i < 2; ++_i) \
;         __builtin_amdgcn_global_load_lds((const unsigned*)((const char*)(gbase) + (voff)[_i]), (LAS unsigned*)(lds + (bufoff) + ldsw + _i * 8192), 16, 0, 0); } while (0)
; #define PG8_LDA(dst, b, h) do { _Pragma("unroll") for (int m = 0; m < 4; ++m) _Pragma("unroll") for (int k = 0; k < 2; ++k) dst[m][k] = *(const LAS bf16x8*)(lds + PG8_SA(b, h) + aoff + m * 2048 + k * 1024); } while (0)
; #define PG8_LDB(dst, b, h) do { _Pragma("unroll") for (int n = 0; n < 2; ++n) _Pragma("unroll") for (int k = 0; k < 2; ++k) dst[n][k] = *(const LAS bf16x8*)(lds + PG8_SB(b, h) + boff + n * 2048 + k * 1024); } while (0)
; #define PG8_MMA(ai, bj, At, Bt) do { __builtin_amdgcn_s_setprio(1); _Pragma("unroll") for (int m = 0; m < 4; ++m) _Pragma("unroll") for (int n = 0; n < 2; ++n) _Pragma("unroll") for (int k = 0; k < 2; ++k) \
;         acc[ai][bj][m][n] = __builtin_amdgcn_mfma_f32_16x16x32_bf16(Bt[n][k], At[m][k], acc[ai][bj][m][n], 0, 0, 0); __builtin_amdgcn_s_setprio(0); } while (0)
; #define PG8_WAIT_V(n) asm volatile("s_waitcnt vmcnt(" #n ")" ::: "memory")
; #define PG8_WAIT_L(n) asm volatile("s_waitcnt lgkmcnt(" #n ")" ::: "memory")
; #define PG8_BAR __builtin_amdgcn_s_barrier()
; #define PG8_SCHED __builtin_amdgcn_sched_barrier(0)
; template <class Epi>
; __device__ __forceinline__ void gemm_phase(LAS unsigned char* lds, const Gemm g, const StaticOrder S, const Epi E) {
;     ...
;             PG8_LDB(B0, 1, 0); PG8_LDB(B1, 1, 1); PG8_SCHED; PG8_LDA(At, 1, 0); PG8_STAGE(PG8_SA(0, 1), a2 + hstepA, voffA);
;             PG8_WAIT_V(8); PG8_WAIT_L(0); PG8_BAR; PG8_MMA(0, 0, At, B0); PG8_MMA(0, 1, At, B1); PG8_BAR; PG8_SCHED;
;             PG8_LDA(At, 1, 1); PG8_STAGE(PG8_SB(1, 0), b3, voffB); PG8_STAGE(PG8_SB(1, 1), b3 + hstepB, voffB); PG8_STAGE(PG8_SA(1, 0), a3, voffA);
;             PG8_WAIT_V(8); PG8_WAIT_L(0); PG8_BAR; PG8_MMA(1, 0, At, B0); PG8_MMA(1, 1, At, B1); PG8_BAR; PG8_SCHED;
;         }
	s_add_i32 s13, 0, 0x18000
	s_add_i32 s65, 0, 0x1c000
	ds_read_b128 v[148:151], v254 offset:32768
	ds_read_b128 v[152:155], v254 offset:33792
	ds_read_b128 v[156:159], v254 offset:34816
	ds_read_b128 v[160:163], v254 offset:35840
	ds_read_b128 v[164:167], v254 offset:49152
	ds_read_b128 v[168:171], v254 offset:50176
	ds_read_b128 v[172:175], v254 offset:51200
	ds_read_b128 v[176:179], v254 offset:52224
	s_add_u32 s46, s46, 0x80000
	s_addc_u32 s47, s47, 0
	s_mov_b32 m0, s53
	ds_read_b128 v[180:183], v145 offset:32768
	ds_read_b128 v[184:187], v145 offset:33792
	ds_read_b128 v[188:191], v145 offset:34816
	ds_read_b128 v[192:195], v145 offset:35840
	ds_read_b128 v[196:199], v145 offset:36864
	ds_read_b128 v[200:203], v145 offset:37888
	ds_read_b128 v[204:207], v145 offset:38912
	ds_read_b128 v[208:211], v145 offset:39936
	global_load_lds_dwordx4 v134, s[46:47]
	s_mov_b32 m0, s54
	s_nop 0
	global_load_lds_dwordx4 v130, s[46:47]
	s_waitcnt vmcnt(8)
	s_waitcnt lgkmcnt(0)
	s_barrier
	s_waitcnt lgkmcnt(0)
	v_mfma_f32_16x16x32_bf16 v[116:119], v[148:151], v[180:183], v[116:119]
	v_mfma_f32_16x16x32_bf16 v[112:115], v[156:159], v[180:183], v[112:115]
	v_mfma_f32_16x16x32_bf16 v[108:111], v[148:151], v[188:191], v[108:111]
	v_mfma_f32_16x16x32_bf16 v[104:107], v[156:159], v[188:191], v[104:107]
	v_mfma_f32_16x16x32_bf16 v[92:95], v[148:151], v[196:199], v[92:95]
	v_mfma_f32_16x16x32_bf16 v[88:91], v[156:159], v[196:199], v[88:91]
	v_mfma_f32_16x16x32_bf16 v[76:79], v[148:151], v[204:207], v[76:79]
	v_mfma_f32_16x16x32_bf16 v[72:75], v[156:159], v[204:207], v[72:75]
	v_mfma_f32_16x16x32_bf16 v[116:119], v[152:155], v[184:187], v[116:119]
	v_mfma_f32_16x16x32_bf16 v[112:115], v[160:163], v[184:187], v[112:115]
	v_mfma_f32_16x16x32_bf16 v[108:111], v[152:155], v[192:195], v[108:111]
	v_mfma_f32_16x16x32_bf16 v[104:107], v[160:163], v[192:195], v[104:107]
	v_mfma_f32_16x16x32_bf16 v[92:95], v[152:155], v[200:203], v[92:95]
	v_mfma_f32_16x16x32_bf16 v[88:91], v[160:163], v[200:203], v[88:91]
	v_mfma_f32_16x16x32_bf16 v[76:79], v[152:155], v[208:211], v[76:79]
	v_mfma_f32_16x16x32_bf16 v[72:75], v[160:163], v[208:211], v[72:75]
	v_mfma_f32_16x16x32_bf16 v[124:127], v[164:167], v[180:183], v[124:127]
	v_mfma_f32_16x16x32_bf16 v[120:123], v[172:175], v[180:183], v[120:123]
	v_mfma_f32_16x16x32_bf16 v[100:103], v[164:167], v[188:191], v[100:103]
	v_mfma_f32_16x16x32_bf16 v[96:99], v[172:175], v[188:191], v[96:99]
	v_mfma_f32_16x16x32_bf16 v[84:87], v[164:167], v[196:199], v[84:87]
	v_mfma_f32_16x16x32_bf16 v[80:83], v[172:175], v[196:199], v[80:83]
	v_mfma_f32_16x16x32_bf16 v[68:71], v[164:167], v[204:207], v[68:71]
	v_mfma_f32_16x16x32_bf16 v[64:67], v[172:175], v[204:207], v[64:67]
	v_mfma_f32_16x16x32_bf16 v[124:127], v[168:171], v[184:187], v[124:127]
	v_mfma_f32_16x16x32_bf16 v[120:123], v[176:179], v[184:187], v[120:123]
	v_mfma_f32_16x16x32_bf16 v[100:103], v[168:171], v[192:195], v[100:103]
	v_mfma_f32_16x16x32_bf16 v[96:99], v[176:179], v[192:195], v[96:99]
	v_mfma_f32_16x16x32_bf16 v[84:87], v[168:171], v[200:203], v[84:87]
	v_mfma_f32_16x16x32_bf16 v[80:83], v[176:179], v[200:203], v[80:83]
	v_mfma_f32_16x16x32_bf16 v[68:71], v[168:171], v[208:211], v[68:71]
	v_mfma_f32_16x16x32_bf16 v[64:67], v[176:179], v[208:211], v[64:67]
	s_barrier
	s_add_u32 s42, s42, s44
	s_addc_u32 s43, s43, s45
	s_add_i32 s13, s13, s33
	s_mov_b32 m0, s13
	ds_read_b128 v[180:183], v145 offset:49152
	ds_read_b128 v[184:187], v145 offset:50176
	ds_read_b128 v[188:191], v145 offset:51200
	ds_read_b128 v[192:195], v145 offset:52224
	ds_read_b128 v[196:199], v145 offset:53248
	ds_read_b128 v[200:203], v145 offset:54272
	ds_read_b128 v[204:207], v145 offset:55296
	ds_read_b128 v[208:211], v145 offset:56320
	global_load_lds_dwordx4 v132, s[42:43]
	s_add_i32 m0, s13, 0x2000
	s_nop 0
	global_load_lds_dwordx4 v128, s[42:43]
	s_add_u32 s42, s42, 0x80000
	s_addc_u32 s43, s43, 0
	s_add_i32 s13, s65, s33
	s_mov_b32 m0, s13
	s_nop 0
	global_load_lds_dwordx4 v132, s[42:43]
	s_add_i32 m0, s13, 0x2000
	s_nop 0
	global_load_lds_dwordx4 v128, s[42:43]
	s_mov_b32 m0, s55
	s_nop 0
	global_load_lds_dwordx4 v134, s[48:49]
	s_mov_b32 m0, s56
	s_nop 0
	global_load_lds_dwordx4 v130, s[48:49]
	s_waitcnt vmcnt(8)
	s_waitcnt lgkmcnt(0)
	s_barrier
	s_waitcnt lgkmcnt(0)
	v_mfma_f32_16x16x32_bf16 v[60:63], v[148:151], v[180:183], v[60:63]
	v_mfma_f32_16x16x32_bf16 v[56:59], v[156:159], v[180:183], v[56:59]
	v_mfma_f32_16x16x32_bf16 v[44:47], v[148:151], v[188:191], v[44:47]
	v_mfma_f32_16x16x32_bf16 v[40:43], v[156:159], v[188:191], v[40:43]
	v_mfma_f32_16x16x32_bf16 v[28:31], v[148:151], v[196:199], v[28:31]
	v_mfma_f32_16x16x32_bf16 v[24:27], v[156:159], v[196:199], v[24:27]
	v_mfma_f32_16x16x32_bf16 v[12:15], v[148:151], v[204:207], v[12:15]
	v_mfma_f32_16x16x32_bf16 v[8:11], v[156:159], v[204:207], v[8:11]
	v_mfma_f32_16x16x32_bf16 v[60:63], v[152:155], v[184:187], v[60:63]
	v_mfma_f32_16x16x32_bf16 v[56:59], v[160:163], v[184:187], v[56:59]
	v_mfma_f32_16x16x32_bf16 v[44:47], v[152:155], v[192:195], v[44:47]
	v_mfma_f32_16x16x32_bf16 v[40:43], v[160:163], v[192:195], v[40:43]
	v_mfma_f32_16x16x32_bf16 v[28:31], v[152:155], v[200:203], v[28:31]
	v_mfma_f32_16x16x32_bf16 v[24:27], v[160:163], v[200:203], v[24:27]
	v_mfma_f32_16x16x32_bf16 v[12:15], v[152:155], v[208:211], v[12:15]
	v_mfma_f32_16x16x32_bf16 v[8:11], v[160:163], v[208:211], v[8:11]
	v_mfma_f32_16x16x32_bf16 v[52:55], v[164:167], v[180:183], v[52:55]
	v_mfma_f32_16x16x32_bf16 v[48:51], v[172:175], v[180:183], v[48:51]
	v_mfma_f32_16x16x32_bf16 v[36:39], v[164:167], v[188:191], v[36:39]
	v_mfma_f32_16x16x32_bf16 v[32:35], v[172:175], v[188:191], v[32:35]
	v_mfma_f32_16x16x32_bf16 v[20:23], v[164:167], v[196:199], v[20:23]
	v_mfma_f32_16x16x32_bf16 v[16:19], v[172:175], v[196:199], v[16:19]
	v_mfma_f32_16x16x32_bf16 v[4:7], v[164:167], v[204:207], v[4:7]
	v_mfma_f32_16x16x32_bf16 v[0:3], v[172:175], v[204:207], v[0:3]
	v_mfma_f32_16x16x32_bf16 v[52:55], v[168:171], v[184:187], v[52:55]
	v_mfma_f32_16x16x32_bf16 v[48:51], v[176:179], v[184:187], v[48:51]
	v_mfma_f32_16x16x32_bf16 v[36:39], v[168:171], v[192:195], v[36:39]
	v_mfma_f32_16x16x32_bf16 v[32:35], v[176:179], v[192:195], v[32:35]
	v_mfma_f32_16x16x32_bf16 v[20:23], v[168:171], v[200:203], v[20:23]
	v_mfma_f32_16x16x32_bf16 v[16:19], v[176:179], v[200:203], v[16:19]
	v_mfma_f32_16x16x32_bf16 v[4:7], v[168:171], v[208:211], v[4:7]
	v_mfma_f32_16x16x32_bf16 v[0:3], v[176:179], v[208:211], v[0:3]
	s_barrier
	s_cmp_gt_u32 s64, 29
	s_mov_b32 s64, s11
	s_cbranch_scc1 .LBB0_858

; #define PG8_STAGE(bufoff, gbase, voff) do { _Pragma("unroll") for (int _i = 0; _i < 2; ++_i) \
;         __builtin_amdgcn_global_load_lds((const unsigned*)((const char*)(gbase) + (voff)[_i]), (LAS unsigned*)(lds + (bufoff) + ldsw + _i * 8192), 16, 0, 0); } while (0)
; #define PG8_LDA(dst, b, h) do { _Pragma("unroll") for (int m = 0; m < 4; ++m) _Pragma("unroll") for (int k = 0; k < 2; ++k) dst[m][k] = *(const LAS bf16x8*)(lds + PG8_SA(b, h) + aoff + m * 2048 + k * 1024); } while (0)
; #define PG8_LDB(dst, b, h) do { _Pragma("unroll") for (int n = 0; n < 2; ++n) _Pragma("unroll") for (int k = 0; k < 2; ++k) dst[n][k] = *(const LAS bf16x8*)(lds + PG8_SB(b, h) + boff + n * 2048 + k * 1024); } while (0)
; #define PG8_MMA(ai, bj, At, Bt) do { __builtin_amdgcn_s_setprio(1); _Pragma("unroll") for (int m = 0; m < 4; ++m) _Pragma("unroll") for (int n = 0; n < 2; ++n) _Pragma("unroll") for (int k = 0; k < 2; ++k) \
;         acc[ai][bj][m][n] = __builtin_amdgcn_mfma_f32_16x16x32_bf16(Bt[n][k], At[m][k], acc[ai][bj][m][n], 0, 0, 0); __builtin_amdgcn_s_setprio(0); } while (0)
; #define PG8_WAIT_V(n) asm volatile("s_waitcnt vmcnt(" #n ")" ::: "memory")
; #define PG8_WAIT_L(n) asm volatile("s_waitcnt lgkmcnt(" #n ")" ::: "memory")
; #define PG8_BAR __builtin_amdgcn_s_barrier()
; #define PG8_SCHED __builtin_amdgcn_sched_barrier(0)
; template <class Epi>
; __device__ __forceinline__ void gemm_phase(LAS unsigned char* lds, const Gemm g, const StaticOrder S, const Epi E) {
;     ...
;             PG8_LDB(B0, 0, 0); PG8_LDB(B1, 0, 1); PG8_SCHED; PG8_LDA(At, 0, 0); PG8_STAGE(PG8_SA(1, 1), a1 + hstepA, voffA);
;             PG8_WAIT_V(8); PG8_WAIT_L(0); PG8_BAR; PG8_MMA(0, 0, At, B0); PG8_MMA(0, 1, At, B1); PG8_BAR; PG8_SCHED;
;             PG8_LDA(At, 0, 1); PG8_STAGE(PG8_SB(0, 0), b2, voffB); PG8_STAGE(PG8_SB(0, 1), b2 + hstepB, voffB); PG8_STAGE(PG8_SA(0, 0), a2, voffA);
;             PG8_WAIT_V(8); PG8_WAIT_L(0); PG8_BAR; PG8_MMA(1, 0, At, B0); PG8_MMA(1, 1, At, B1); PG8_BAR; PG8_SCHED;
.LBB0_938:
	v_add_u32_e32 v152, s59, v166
	v_add_u32_e32 v178, s60, v166
	ds_read_b128 v[128:131], v152
	ds_read_b128 v[132:135], v152 offset:1024
	ds_read_b128 v[136:139], v152 offset:2048
	ds_read_b128 v[152:155], v152 offset:3072
	ds_read_b128 v[156:159], v178
	ds_read_b128 v[170:173], v178 offset:1024
	ds_read_b128 v[174:177], v178 offset:2048
	ds_read_b128 v[178:181], v178 offset:3072
	s_or_b32 s48, s70, 1
	s_mul_i32 s49, s35, s48
	s_mul_hi_u32 s72, s34, s48
	s_add_i32 s72, s72, s49
	s_mul_i32 s48, s34, s48
	s_add_u32 s73, s30, s48
	s_addc_u32 s74, s31, s72
	s_add_u32 s48, s46, s44
	s_addc_u32 s49, s47, s45
	s_add_u32 s72, s73, 0x160000
	s_addc_u32 s73, s74, 0
	s_add_i32 m0, s50, 0xc000
	ds_read_b128 v[182:185], v168
	ds_read_b128 v[186:189], v168 offset:1024
	ds_read_b128 v[190:193], v168 offset:2048
	ds_read_b128 v[194:197], v168 offset:3072
	ds_read_b128 v[198:201], v168 offset:4096
	ds_read_b128 v[202:205], v168 offset:5120
	ds_read_b128 v[206:209], v168 offset:6144
	ds_read_b128 v[210:213], v168 offset:7168
	global_load_lds_dwordx4 v140, s[72:73]
	s_add_i32 m0, s50, 0xe000
	s_nop 0
	global_load_lds_dwordx4 v144, s[72:73]
	s_waitcnt vmcnt(8)
	s_waitcnt lgkmcnt(0)
	s_barrier
	s_waitcnt lgkmcnt(0)
	v_mfma_f32_16x16x32_bf16 v[124:127], v[128:131], v[182:185], v[124:127]
	v_mfma_f32_16x16x32_bf16 v[120:123], v[136:139], v[182:185], v[120:123]
	v_mfma_f32_16x16x32_bf16 v[108:111], v[128:131], v[190:193], v[108:111]
	v_mfma_f32_16x16x32_bf16 v[104:107], v[136:139], v[190:193], v[104:107]
	v_mfma_f32_16x16x32_bf16 v[92:95], v[128:131], v[198:201], v[92:95]
	v_mfma_f32_16x16x32_bf16 v[88:91], v[136:139], v[198:201], v[88:91]
	v_mfma_f32_16x16x32_bf16 v[76:79], v[128:131], v[206:209], v[76:79]
	v_mfma_f32_16x16x32_bf16 v[72:75], v[136:139], v[206:209], v[72:75]
	v_mfma_f32_16x16x32_bf16 v[124:127], v[132:135], v[186:189], v[124:127]
	v_mfma_f32_16x16x32_bf16 v[120:123], v[152:155], v[186:189], v[120:123]
	v_mfma_f32_16x16x32_bf16 v[108:111], v[132:135], v[194:197], v[108:111]
	v_mfma_f32_16x16x32_bf16 v[104:107], v[152:155], v[194:197], v[104:107]
	v_mfma_f32_16x16x32_bf16 v[92:95], v[132:135], v[202:205], v[92:95]
	v_mfma_f32_16x16x32_bf16 v[88:91], v[152:155], v[202:205], v[88:91]
	v_mfma_f32_16x16x32_bf16 v[76:79], v[132:135], v[210:213], v[76:79]
	v_mfma_f32_16x16x32_bf16 v[72:75], v[152:155], v[210:213], v[72:75]
	v_mfma_f32_16x16x32_bf16 v[116:119], v[156:159], v[182:185], v[116:119]
	v_mfma_f32_16x16x32_bf16 v[112:115], v[174:177], v[182:185], v[112:115]
	v_mfma_f32_16x16x32_bf16 v[100:103], v[156:159], v[190:193], v[100:103]
	v_mfma_f32_16x16x32_bf16 v[96:99], v[174:177], v[190:193], v[96:99]
	v_mfma_f32_16x16x32_bf16 v[84:87], v[156:159], v[198:201], v[84:87]
	v_mfma_f32_16x16x32_bf16 v[80:83], v[174:177], v[198:201], v[80:83]
	v_mfma_f32_16x16x32_bf16 v[68:71], v[156:159], v[206:209], v[68:71]
	v_mfma_f32_16x16x32_bf16 v[64:67], v[174:177], v[206:209], v[64:67]
	v_mfma_f32_16x16x32_bf16 v[116:119], v[170:173], v[186:189], v[116:119]
	v_mfma_f32_16x16x32_bf16 v[112:115], v[178:181], v[186:189], v[112:115]
	v_mfma_f32_16x16x32_bf16 v[100:103], v[170:173], v[194:197], v[100:103]
	v_mfma_f32_16x16x32_bf16 v[96:99], v[178:181], v[194:197], v[96:99]
	v_mfma_f32_16x16x32_bf16 v[84:87], v[170:173], v[202:205], v[84:87]
	v_mfma_f32_16x16x32_bf16 v[80:83], v[178:181], v[202:205], v[80:83]
	v_mfma_f32_16x16x32_bf16 v[68:71], v[170:173], v[210:213], v[68:71]
	v_mfma_f32_16x16x32_bf16 v[64:67], v[178:181], v[210:213], v[64:67]
	s_barrier
	s_add_i32 s72, s59, s33
	s_mov_b32 m0, s72
	ds_read_b128 v[182:185], v168 offset:16384
	ds_read_b128 v[186:189], v168 offset:17408
	ds_read_b128 v[190:193], v168 offset:18432
	ds_read_b128 v[194:197], v168 offset:19456
	ds_read_b128 v[198:201], v168 offset:20480
	ds_read_b128 v[202:205], v168 offset:21504
	ds_read_b128 v[206:209], v168 offset:22528
	ds_read_b128 v[210:213], v168 offset:23552
	global_load_lds_dwordx4 v142, s[42:43]
	s_add_i32 m0, s72, 0x2000
	s_add_u32 s72, s42, 0x160000
	s_addc_u32 s73, s43, 0
	s_add_i32 s74, s60, s33
	global_load_lds_dwordx4 v146, s[42:43]
	s_mov_b32 m0, s74
	s_nop 0
	global_load_lds_dwordx4 v142, s[72:73]
	s_add_i32 m0, s74, 0x2000
	s_nop 0
	global_load_lds_dwordx4 v146, s[72:73]
	s_mov_b32 m0, s50
	s_nop 0
	global_load_lds_dwordx4 v140, s[46:47]
	s_mov_b32 m0, s51
	s_nop 0
	global_load_lds_dwordx4 v144, s[46:47]
	s_waitcnt vmcnt(8)
	s_waitcnt lgkmcnt(0)
	s_barrier
	s_waitcnt lgkmcnt(0)
	v_mfma_f32_16x16x32_bf16 v[60:63], v[128:131], v[182:185], v[60:63]
	v_mfma_f32_16x16x32_bf16 v[56:59], v[136:139], v[182:185], v[56:59]
	v_mfma_f32_16x16x32_bf16 v[44:47], v[128:131], v[190:193], v[44:47]
	v_mfma_f32_16x16x32_bf16 v[40:43], v[136:139], v[190:193], v[40:43]
	v_mfma_f32_16x16x32_bf16 v[28:31], v[128:131], v[198:201], v[28:31]
	v_mfma_f32_16x16x32_bf16 v[24:27], v[136:139], v[198:201], v[24:27]
	v_mfma_f32_16x16x32_bf16 v[12:15], v[128:131], v[206:209], v[12:15]
	v_mfma_f32_16x16x32_bf16 v[8:11], v[136:139], v[206:209], v[8:11]
	v_mfma_f32_16x16x32_bf16 v[60:63], v[132:135], v[186:189], v[60:63]
	v_mfma_f32_16x16x32_bf16 v[56:59], v[152:155], v[186:189], v[56:59]
	v_mfma_f32_16x16x32_bf16 v[44:47], v[132:135], v[194:197], v[44:47]
	v_mfma_f32_16x16x32_bf16 v[40:43], v[152:155], v[194:197], v[40:43]
	v_mfma_f32_16x16x32_bf16 v[28:31], v[132:135], v[202:205], v[28:31]
	v_mfma_f32_16x16x32_bf16 v[24:27], v[152:155], v[202:205], v[24:27]
	v_mfma_f32_16x16x32_bf16 v[12:15], v[132:135], v[210:213], v[12:15]
	v_mfma_f32_16x16x32_bf16 v[8:11], v[152:155], v[210:213], v[8:11]
	v_mfma_f32_16x16x32_bf16 v[52:55], v[156:159], v[182:185], v[52:55]
	v_mfma_f32_16x16x32_bf16 v[48:51], v[174:177], v[182:185], v[48:51]
	v_mfma_f32_16x16x32_bf16 v[36:39], v[156:159], v[190:193], v[36:39]
	v_mfma_f32_16x16x32_bf16 v[32:35], v[174:177], v[190:193], v[32:35]
	v_mfma_f32_16x16x32_bf16 v[20:23], v[156:159], v[198:201], v[20:23]
	v_mfma_f32_16x16x32_bf16 v[16:19], v[174:177], v[198:201], v[16:19]
	v_mfma_f32_16x16x32_bf16 v[4:7], v[156:159], v[206:209], v[4:7]
	v_mfma_f32_16x16x32_bf16 v[0:3], v[174:177], v[206:209], v[0:3]
	v_mfma_f32_16x16x32_bf16 v[52:55], v[170:173], v[186:189], v[52:55]
	v_mfma_f32_16x16x32_bf16 v[48:51], v[178:181], v[186:189], v[48:51]
	v_mfma_f32_16x16x32_bf16 v[36:39], v[170:173], v[194:197], v[36:39]
	v_mfma_f32_16x16x32_bf16 v[32:35], v[178:181], v[194:197], v[32:35]
	v_mfma_f32_16x16x32_bf16 v[20:23], v[170:173], v[202:205], v[20:23]
	v_mfma_f32_16x16x32_bf16 v[16:19], v[178:181], v[202:205], v[16:19]
	v_mfma_f32_16x16x32_bf16 v[4:7], v[170:173], v[210:213], v[4:7]
	v_mfma_f32_16x16x32_bf16 v[0:3], v[178:181], v[210:213], v[0:3]
	s_barrier
; #define PG8_STAGE(bufoff, gbase, voff) do { _Pragma("unroll") for (int _i = 0; _i < 2; ++_i) \
;         __builtin_amdgcn_global_load_lds((const unsigned*)((const char*)(gbase) + (voff)[_i]), (LAS unsigned*)(lds + (bufoff) + ldsw + _i * 8192), 16, 0, 0); } while (0)
; #define PG8_LDA(dst, b, h) do { _Pragma("unroll") for (int m = 0; m < 4; ++m) _Pragma("unroll") for (int k = 0; k < 2; ++k) dst[m][k] = *(const LAS bf16x8*)(lds + PG8_SA(b, h) + aoff + m * 2048 + k * 1024); } while (0)
; #define PG8_LDB(dst, b, h) do { _Pragma("unroll") for (int n = 0; n < 2; ++n) _Pragma("unroll") for (int k = 0; k < 2; ++k) dst[n][k] = *(const LAS bf16x8*)(lds + PG8_SB(b, h) + boff + n * 2048 + k * 1024); } while (0)
; #define PG8_MMA(ai, bj, At, Bt) do { __builtin_amdgcn_s_setprio(1); _Pragma("unroll") for (int m = 0; m < 4; ++m) _Pragma("unroll") for (int n = 0; n < 2; ++n) _Pragma("unroll") for (int k = 0; k < 2; ++k) \
;         acc[ai][bj][m][n] = __builtin_amdgcn_mfma_f32_16x16x32_bf16(Bt[n][k], At[m][k], acc[ai][bj][m][n], 0, 0, 0); __builtin_amdgcn_s_setprio(0); } while (0)
; #define PG8_WAIT_V(n) asm volatile("s_waitcnt vmcnt(" #n ")" ::: "memory")
; #define PG8_WAIT_L(n) asm volatile("s_waitcnt lgkmcnt(" #n ")" ::: "memory")
; #define PG8_BAR __builtin_amdgcn_s_barrier()
; #define PG8_SCHED __builtin_amdgcn_sched_barrier(0)
; template <class Epi>
; __device__ __forceinline__ void gemm_phase(LAS unsigned char* lds, const Gemm g, const StaticOrder S, const Epi E) {
;     ...
;         for (int t = 0; t < nt; t += 2) {
;     ...
;             PG8_LDB(B0, 1, 0); PG8_LDB(B1, 1, 1); PG8_SCHED; PG8_LDA(At, 1, 0); PG8_STAGE(PG8_SA(0, 1), a2 + hstepA, voffA);
;             PG8_WAIT_V(8); PG8_WAIT_L(0); PG8_BAR; PG8_MMA(0, 0, At, B0); PG8_MMA(0, 1, At, B1); PG8_BAR; PG8_SCHED;
;             PG8_LDA(At, 1, 1); PG8_STAGE(PG8_SB(1, 0), b3, voffB); PG8_STAGE(PG8_SB(1, 1), b3 + hstepB, voffB); PG8_STAGE(PG8_SA(1, 0), a3, voffA);
;             PG8_WAIT_V(8); PG8_WAIT_L(0); PG8_BAR; PG8_MMA(1, 0, At, B0); PG8_MMA(1, 1, At, B1); PG8_BAR; PG8_SCHED;
	s_add_i32 s72, 0, 0x18000
	s_add_i32 s73, 0, 0x1c000
	v_add_u32_e32 v152, s72, v166
	v_add_u32_e32 v178, s73, v166
	ds_read_b128 v[128:131], v152
	ds_read_b128 v[132:135], v152 offset:1024
	ds_read_b128 v[136:139], v152 offset:2048
	ds_read_b128 v[152:155], v152 offset:3072
	ds_read_b128 v[156:159], v178
	ds_read_b128 v[170:173], v178 offset:1024
	ds_read_b128 v[174:177], v178 offset:2048
	ds_read_b128 v[178:181], v178 offset:3072
	s_add_u32 s46, s46, 0x160000
	s_addc_u32 s47, s47, 0
	s_mov_b32 m0, s52
	ds_read_b128 v[182:185], v168 offset:32768
	ds_read_b128 v[186:189], v168 offset:33792
	ds_read_b128 v[190:193], v168 offset:34816
	ds_read_b128 v[194:197], v168 offset:35840
	ds_read_b128 v[198:201], v168 offset:36864
	ds_read_b128 v[202:205], v168 offset:37888
	ds_read_b128 v[206:209], v168 offset:38912
	ds_read_b128 v[210:213], v168 offset:39936
	global_load_lds_dwordx4 v140, s[46:47]
	s_mov_b32 m0, s53
	s_nop 0
	global_load_lds_dwordx4 v144, s[46:47]
	s_waitcnt vmcnt(8)
	s_waitcnt lgkmcnt(0)
	s_barrier
	s_waitcnt lgkmcnt(0)
	v_mfma_f32_16x16x32_bf16 v[124:127], v[128:131], v[182:185], v[124:127]
	v_mfma_f32_16x16x32_bf16 v[120:123], v[136:139], v[182:185], v[120:123]
	v_mfma_f32_16x16x32_bf16 v[108:111], v[128:131], v[190:193], v[108:111]
	v_mfma_f32_16x16x32_bf16 v[104:107], v[136:139], v[190:193], v[104:107]
	v_mfma_f32_16x16x32_bf16 v[92:95], v[128:131], v[198:201], v[92:95]
	v_mfma_f32_16x16x32_bf16 v[88:91], v[136:139], v[198:201], v[88:91]
	v_mfma_f32_16x16x32_bf16 v[76:79], v[128:131], v[206:209], v[76:79]
	v_mfma_f32_16x16x32_bf16 v[72:75], v[136:139], v[206:209], v[72:75]
	v_mfma_f32_16x16x32_bf16 v[124:127], v[132:135], v[186:189], v[124:127]
	v_mfma_f32_16x16x32_bf16 v[120:123], v[152:155], v[186:189], v[120:123]
	v_mfma_f32_16x16x32_bf16 v[108:111], v[132:135], v[194:197], v[108:111]
	v_mfma_f32_16x16x32_bf16 v[104:107], v[152:155], v[194:197], v[104:107]
	v_mfma_f32_16x16x32_bf16 v[92:95], v[132:135], v[202:205], v[92:95]
	v_mfma_f32_16x16x32_bf16 v[88:91], v[152:155], v[202:205], v[88:91]
	v_mfma_f32_16x16x32_bf16 v[76:79], v[132:135], v[210:213], v[76:79]
	v_mfma_f32_16x16x32_bf16 v[72:75], v[152:155], v[210:213], v[72:75]
	v_mfma_f32_16x16x32_bf16 v[116:119], v[156:159], v[182:185], v[116:119]
	v_mfma_f32_16x16x32_bf16 v[112:115], v[174:177], v[182:185], v[112:115]
	v_mfma_f32_16x16x32_bf16 v[100:103], v[156:159], v[190:193], v[100:103]
	v_mfma_f32_16x16x32_bf16 v[96:99], v[174:177], v[190:193], v[96:99]
	v_mfma_f32_16x16x32_bf16 v[84:87], v[156:159], v[198:201], v[84:87]
	v_mfma_f32_16x16x32_bf16 v[80:83], v[174:177], v[198:201], v[80:83]
	v_mfma_f32_16x16x32_bf16 v[68:71], v[156:159], v[206:209], v[68:71]
	v_mfma_f32_16x16x32_bf16 v[64:67], v[174:177], v[206:209], v[64:67]
	v_mfma_f32_16x16x32_bf16 v[116:119], v[170:173], v[186:189], v[116:119]
	v_mfma_f32_16x16x32_bf16 v[112:115], v[178:181], v[186:189], v[112:115]
	v_mfma_f32_16x16x32_bf16 v[100:103], v[170:173], v[194:197], v[100:103]
	v_mfma_f32_16x16x32_bf16 v[96:99], v[178:181], v[194:197], v[96:99]
	v_mfma_f32_16x16x32_bf16 v[84:87], v[170:173], v[202:205], v[84:87]
	v_mfma_f32_16x16x32_bf16 v[80:83], v[178:181], v[202:205], v[80:83]
	v_mfma_f32_16x16x32_bf16 v[68:71], v[170:173], v[210:213], v[68:71]
	v_mfma_f32_16x16x32_bf16 v[64:67], v[178:181], v[210:213], v[64:67]
	s_barrier
	s_add_u32 s42, s42, s44
	s_addc_u32 s43, s43, s45
	s_add_i32 s44, s72, s33
	s_mov_b32 m0, s44
	ds_read_b128 v[182:185], v168 offset:49152
	ds_read_b128 v[186:189], v168 offset:50176
	ds_read_b128 v[190:193], v168 offset:51200
	ds_read_b128 v[194:197], v168 offset:52224
	ds_read_b128 v[198:201], v168 offset:53248
	ds_read_b128 v[202:205], v168 offset:54272
	ds_read_b128 v[206:209], v168 offset:55296
	ds_read_b128 v[210:213], v168 offset:56320
	global_load_lds_dwordx4 v142, s[42:43]
	s_add_i32 m0, s44, 0x2000
	s_nop 0
	global_load_lds_dwordx4 v146, s[42:43]
	s_add_u32 s42, s42, 0x160000
	s_addc_u32 s43, s43, 0
	s_add_i32 s44, s73, s33
	s_mov_b32 m0, s44
	s_nop 0
	global_load_lds_dwordx4 v142, s[42:43]
	s_add_i32 m0, s44, 0x2000
	s_nop 0
	global_load_lds_dwordx4 v146, s[42:43]
	s_mov_b32 m0, s55
	s_nop 0
	global_load_lds_dwordx4 v140, s[48:49]
	s_mov_b32 m0, s56
	s_nop 0
	global_load_lds_dwordx4 v144, s[48:49]
	s_waitcnt vmcnt(8)
	s_waitcnt lgkmcnt(0)
	s_barrier
	s_waitcnt lgkmcnt(0)
	v_mfma_f32_16x16x32_bf16 v[60:63], v[128:131], v[182:185], v[60:63]
	v_mfma_f32_16x16x32_bf16 v[56:59], v[136:139], v[182:185], v[56:59]
	v_mfma_f32_16x16x32_bf16 v[44:47], v[128:131], v[190:193], v[44:47]
	v_mfma_f32_16x16x32_bf16 v[40:43], v[136:139], v[190:193], v[40:43]
	v_mfma_f32_16x16x32_bf16 v[28:31], v[128:131], v[198:201], v[28:31]
	v_mfma_f32_16x16x32_bf16 v[24:27], v[136:139], v[198:201], v[24:27]
	v_mfma_f32_16x16x32_bf16 v[12:15], v[128:131], v[206:209], v[12:15]
	v_mfma_f32_16x16x32_bf16 v[8:11], v[136:139], v[206:209], v[8:11]
	v_mfma_f32_16x16x32_bf16 v[60:63], v[132:135], v[186:189], v[60:63]
	v_mfma_f32_16x16x32_bf16 v[56:59], v[152:155], v[186:189], v[56:59]
	v_mfma_f32_16x16x32_bf16 v[44:47], v[132:135], v[194:197], v[44:47]
	v_mfma_f32_16x16x32_bf16 v[40:43], v[152:155], v[194:197], v[40:43]
	v_mfma_f32_16x16x32_bf16 v[28:31], v[132:135], v[202:205], v[28:31]
	v_mfma_f32_16x16x32_bf16 v[24:27], v[152:155], v[202:205], v[24:27]
	v_mfma_f32_16x16x32_bf16 v[12:15], v[132:135], v[210:213], v[12:15]
	v_mfma_f32_16x16x32_bf16 v[8:11], v[152:155], v[210:213], v[8:11]
	v_mfma_f32_16x16x32_bf16 v[52:55], v[156:159], v[182:185], v[52:55]
	v_mfma_f32_16x16x32_bf16 v[48:51], v[174:177], v[182:185], v[48:51]
	v_mfma_f32_16x16x32_bf16 v[36:39], v[156:159], v[190:193], v[36:39]
	v_mfma_f32_16x16x32_bf16 v[32:35], v[174:177], v[190:193], v[32:35]
	v_mfma_f32_16x16x32_bf16 v[20:23], v[156:159], v[198:201], v[20:23]
	v_mfma_f32_16x16x32_bf16 v[16:19], v[174:177], v[198:201], v[16:19]
	v_mfma_f32_16x16x32_bf16 v[4:7], v[156:159], v[206:209], v[4:7]
	v_mfma_f32_16x16x32_bf16 v[0:3], v[174:177], v[206:209], v[0:3]
	v_mfma_f32_16x16x32_bf16 v[52:55], v[170:173], v[186:189], v[52:55]
	v_mfma_f32_16x16x32_bf16 v[48:51], v[178:181], v[186:189], v[48:51]
	v_mfma_f32_16x16x32_bf16 v[36:39], v[170:173], v[194:197], v[36:39]
	v_mfma_f32_16x16x32_bf16 v[32:35], v[178:181], v[194:197], v[32:35]
	v_mfma_f32_16x16x32_bf16 v[20:23], v[170:173], v[202:205], v[20:23]
	v_mfma_f32_16x16x32_bf16 v[16:19], v[178:181], v[202:205], v[16:19]
	v_mfma_f32_16x16x32_bf16 v[4:7], v[170:173], v[210:213], v[4:7]
	v_mfma_f32_16x16x32_bf16 v[0:3], v[178:181], v[210:213], v[0:3]
	s_barrier
	s_cmpk_gt_u32 s70, 0x55
	s_mov_b32 s70, s71
	s_cbranch_scc1 .LBB0_943

; #define PG8_STAGE(bufoff, gbase, voff) do { _Pragma("unroll") for (int _i = 0; _i < 2; ++_i) \
;         __builtin_amdgcn_global_load_lds((const unsigned*)((const char*)(gbase) + (voff)[_i]), (LAS unsigned*)(lds + (bufoff) + ldsw + _i * 8192), 16, 0, 0); } while (0)
; #define PG8_LDA(dst, b, h) do { _Pragma("unroll") for (int m = 0; m < 4; ++m) _Pragma("unroll") for (int k = 0; k < 2; ++k) dst[m][k] = *(const LAS bf16x8*)(lds + PG8_SA(b, h) + aoff + m * 2048 + k * 1024); } while (0)
; #define PG8_LDB(dst, b, h) do { _Pragma("unroll") for (int n = 0; n < 2; ++n) _Pragma("unroll") for (int k = 0; k < 2; ++k) dst[n][k] = *(const LAS bf16x8*)(lds + PG8_SB(b, h) + boff + n * 2048 + k * 1024); } while (0)
; #define PG8_MMA(ai, bj, At, Bt) do { __builtin_amdgcn_s_setprio(1); _Pragma("unroll") for (int m = 0; m < 4; ++m) _Pragma("unroll") for (int n = 0; n < 2; ++n) _Pragma("unroll") for (int k = 0; k < 2; ++k) \
;         acc[ai][bj][m][n] = __builtin_amdgcn_mfma_f32_16x16x32_bf16(Bt[n][k], At[m][k], acc[ai][bj][m][n], 0, 0, 0); __builtin_amdgcn_s_setprio(0); } while (0)
; #define PG8_WAIT_V(n) asm volatile("s_waitcnt vmcnt(" #n ")" ::: "memory")
; #define PG8_WAIT_L(n) asm volatile("s_waitcnt lgkmcnt(" #n ")" ::: "memory")
; #define PG8_BAR __builtin_amdgcn_s_barrier()
; #define PG8_SCHED __builtin_amdgcn_sched_barrier(0)
; template <class Epi>
; __device__ __forceinline__ void gemm_phase(LAS unsigned char* lds, const Gemm g, const StaticOrder S, const Epi E) {
;     ...
;             PG8_LDB(B0, 0, 0); PG8_LDB(B1, 0, 1); PG8_SCHED; PG8_LDA(At, 0, 0); PG8_STAGE(PG8_SA(1, 1), a1 + hstepA, voffA);
;             PG8_WAIT_V(8); PG8_WAIT_L(0); PG8_BAR; PG8_MMA(0, 0, At, B0); PG8_MMA(0, 1, At, B1); PG8_BAR; PG8_SCHED;
;             PG8_LDA(At, 0, 1); PG8_STAGE(PG8_SB(0, 0), b2, voffB); PG8_STAGE(PG8_SB(0, 1), b2 + hstepB, voffB); PG8_STAGE(PG8_SA(0, 0), a2, voffA);
;             PG8_WAIT_V(8); PG8_WAIT_L(0); PG8_BAR; PG8_MMA(1, 0, At, B0); PG8_MMA(1, 1, At, B1); PG8_BAR; PG8_SCHED;
.LBB0_1032:
	v_add_u32_e32 v140, s59, v227
	v_add_u32_e32 v156, s60, v227
	ds_read_b128 v[128:131], v140
	ds_read_b128 v[132:135], v140 offset:1024
	ds_read_b128 v[136:139], v140 offset:2048
	ds_read_b128 v[140:143], v140 offset:3072
	ds_read_b128 v[144:147], v156
	ds_read_b128 v[148:151], v156 offset:1024
	ds_read_b128 v[152:155], v156 offset:2048
	ds_read_b128 v[156:159], v156 offset:3072
	s_or_b32 s17, s3, 1
	s_mul_i32 s48, s31, s17
	s_mul_hi_u32 s49, s30, s17
	s_add_i32 s49, s49, s48
	s_mul_i32 s17, s30, s17
	s_add_u32 s17, s28, s17
	s_addc_u32 s63, s29, s49
	s_add_u32 s48, s46, s44
	s_addc_u32 s49, s47, s45
	s_add_u32 s64, s17, 0x80000
	s_addc_u32 s65, s63, 0
	s_add_i32 m0, s25, 0xc000
	ds_read_b128 v[160:163], v229
	ds_read_b128 v[164:167], v229 offset:1024
	ds_read_b128 v[168:171], v229 offset:2048
	ds_read_b128 v[172:175], v229 offset:3072
	ds_read_b128 v[176:179], v229 offset:4096
	ds_read_b128 v[180:183], v229 offset:5120
	ds_read_b128 v[184:187], v229 offset:6144
	ds_read_b128 v[188:191], v229 offset:7168
	global_load_lds_dwordx4 v192, s[64:65]
	s_add_i32 m0, s25, 0xe000
	s_nop 0
	global_load_lds_dwordx4 v196, s[64:65]
	s_waitcnt vmcnt(8)
	s_waitcnt lgkmcnt(0)
	s_barrier
	s_waitcnt lgkmcnt(0)
	v_mfma_f32_16x16x32_bf16 v[124:127], v[128:131], v[160:163], v[124:127]
	v_mfma_f32_16x16x32_bf16 v[120:123], v[136:139], v[160:163], v[120:123]
	v_mfma_f32_16x16x32_bf16 v[108:111], v[128:131], v[168:171], v[108:111]
	v_mfma_f32_16x16x32_bf16 v[104:107], v[136:139], v[168:171], v[104:107]
	v_mfma_f32_16x16x32_bf16 v[92:95], v[128:131], v[176:179], v[92:95]
	v_mfma_f32_16x16x32_bf16 v[88:91], v[136:139], v[176:179], v[88:91]
	v_mfma_f32_16x16x32_bf16 v[76:79], v[128:131], v[184:187], v[76:79]
	v_mfma_f32_16x16x32_bf16 v[72:75], v[136:139], v[184:187], v[72:75]
	v_mfma_f32_16x16x32_bf16 v[124:127], v[132:135], v[164:167], v[124:127]
	v_mfma_f32_16x16x32_bf16 v[120:123], v[140:143], v[164:167], v[120:123]
	v_mfma_f32_16x16x32_bf16 v[108:111], v[132:135], v[172:175], v[108:111]
	v_mfma_f32_16x16x32_bf16 v[104:107], v[140:143], v[172:175], v[104:107]
	v_mfma_f32_16x16x32_bf16 v[92:95], v[132:135], v[180:183], v[92:95]
	v_mfma_f32_16x16x32_bf16 v[88:91], v[140:143], v[180:183], v[88:91]
	v_mfma_f32_16x16x32_bf16 v[76:79], v[132:135], v[188:191], v[76:79]
	v_mfma_f32_16x16x32_bf16 v[72:75], v[140:143], v[188:191], v[72:75]
	v_mfma_f32_16x16x32_bf16 v[116:119], v[144:147], v[160:163], v[116:119]
	v_mfma_f32_16x16x32_bf16 v[112:115], v[152:155], v[160:163], v[112:115]
	v_mfma_f32_16x16x32_bf16 v[100:103], v[144:147], v[168:171], v[100:103]
	v_mfma_f32_16x16x32_bf16 v[96:99], v[152:155], v[168:171], v[96:99]
	v_mfma_f32_16x16x32_bf16 v[84:87], v[144:147], v[176:179], v[84:87]
	v_mfma_f32_16x16x32_bf16 v[80:83], v[152:155], v[176:179], v[80:83]
	v_mfma_f32_16x16x32_bf16 v[68:71], v[144:147], v[184:187], v[68:71]
	v_mfma_f32_16x16x32_bf16 v[64:67], v[152:155], v[184:187], v[64:67]
	v_mfma_f32_16x16x32_bf16 v[116:119], v[148:151], v[164:167], v[116:119]
	v_mfma_f32_16x16x32_bf16 v[112:115], v[156:159], v[164:167], v[112:115]
	v_mfma_f32_16x16x32_bf16 v[100:103], v[148:151], v[172:175], v[100:103]
	v_mfma_f32_16x16x32_bf16 v[96:99], v[156:159], v[172:175], v[96:99]
	v_mfma_f32_16x16x32_bf16 v[84:87], v[148:151], v[180:183], v[84:87]
	v_mfma_f32_16x16x32_bf16 v[80:83], v[156:159], v[180:183], v[80:83]
	v_mfma_f32_16x16x32_bf16 v[68:71], v[148:151], v[188:191], v[68:71]
	v_mfma_f32_16x16x32_bf16 v[64:67], v[156:159], v[188:191], v[64:67]
	s_barrier
	s_add_i32 s17, s59, s33
	s_mov_b32 m0, s17
	ds_read_b128 v[160:163], v229 offset:16384
	ds_read_b128 v[164:167], v229 offset:17408
	ds_read_b128 v[168:171], v229 offset:18432
	ds_read_b128 v[172:175], v229 offset:19456
	ds_read_b128 v[176:179], v229 offset:20480
	ds_read_b128 v[180:183], v229 offset:21504
	ds_read_b128 v[184:187], v229 offset:22528
	ds_read_b128 v[188:191], v229 offset:23552
	global_load_lds_dwordx4 v194, s[42:43]
	s_add_i32 m0, s17, 0x2000
	s_add_u32 s64, s42, 0x80000
	s_addc_u32 s65, s43, 0
	s_add_i32 s17, s60, s33
	global_load_lds_dwordx4 v198, s[42:43]
	s_mov_b32 m0, s17
	s_nop 0
	global_load_lds_dwordx4 v194, s[64:65]
	s_add_i32 m0, s17, 0x2000
	s_nop 0
	global_load_lds_dwordx4 v198, s[64:65]
	s_mov_b32 m0, s25
	s_nop 0
	global_load_lds_dwordx4 v192, s[46:47]
	s_mov_b32 m0, s50
	s_nop 0
	global_load_lds_dwordx4 v196, s[46:47]
	s_waitcnt vmcnt(8)
	s_waitcnt lgkmcnt(0)
	s_barrier
	s_waitcnt lgkmcnt(0)
	v_mfma_f32_16x16x32_bf16 v[60:63], v[128:131], v[160:163], v[60:63]
	v_mfma_f32_16x16x32_bf16 v[56:59], v[136:139], v[160:163], v[56:59]
	v_mfma_f32_16x16x32_bf16 v[44:47], v[128:131], v[168:171], v[44:47]
	v_mfma_f32_16x16x32_bf16 v[40:43], v[136:139], v[168:171], v[40:43]
	v_mfma_f32_16x16x32_bf16 v[28:31], v[128:131], v[176:179], v[28:31]
	v_mfma_f32_16x16x32_bf16 v[24:27], v[136:139], v[176:179], v[24:27]
	v_mfma_f32_16x16x32_bf16 v[12:15], v[128:131], v[184:187], v[12:15]
	v_mfma_f32_16x16x32_bf16 v[8:11], v[136:139], v[184:187], v[8:11]
	v_mfma_f32_16x16x32_bf16 v[60:63], v[132:135], v[164:167], v[60:63]
	v_mfma_f32_16x16x32_bf16 v[56:59], v[140:143], v[164:167], v[56:59]
	v_mfma_f32_16x16x32_bf16 v[44:47], v[132:135], v[172:175], v[44:47]
	v_mfma_f32_16x16x32_bf16 v[40:43], v[140:143], v[172:175], v[40:43]
	v_mfma_f32_16x16x32_bf16 v[28:31], v[132:135], v[180:183], v[28:31]
	v_mfma_f32_16x16x32_bf16 v[24:27], v[140:143], v[180:183], v[24:27]
	v_mfma_f32_16x16x32_bf16 v[12:15], v[132:135], v[188:191], v[12:15]
	v_mfma_f32_16x16x32_bf16 v[8:11], v[140:143], v[188:191], v[8:11]
	v_mfma_f32_16x16x32_bf16 v[52:55], v[144:147], v[160:163], v[52:55]
	v_mfma_f32_16x16x32_bf16 v[48:51], v[152:155], v[160:163], v[48:51]
	v_mfma_f32_16x16x32_bf16 v[36:39], v[144:147], v[168:171], v[36:39]
	v_mfma_f32_16x16x32_bf16 v[32:35], v[152:155], v[168:171], v[32:35]
	v_mfma_f32_16x16x32_bf16 v[20:23], v[144:147], v[176:179], v[20:23]
	v_mfma_f32_16x16x32_bf16 v[16:19], v[152:155], v[176:179], v[16:19]
	v_mfma_f32_16x16x32_bf16 v[4:7], v[144:147], v[184:187], v[4:7]
	v_mfma_f32_16x16x32_bf16 v[0:3], v[152:155], v[184:187], v[0:3]
	v_mfma_f32_16x16x32_bf16 v[52:55], v[148:151], v[164:167], v[52:55]
	v_mfma_f32_16x16x32_bf16 v[48:51], v[156:159], v[164:167], v[48:51]
	v_mfma_f32_16x16x32_bf16 v[36:39], v[148:151], v[172:175], v[36:39]
	v_mfma_f32_16x16x32_bf16 v[32:35], v[156:159], v[172:175], v[32:35]
	v_mfma_f32_16x16x32_bf16 v[20:23], v[148:151], v[180:183], v[20:23]
	v_mfma_f32_16x16x32_bf16 v[16:19], v[156:159], v[180:183], v[16:19]
	v_mfma_f32_16x16x32_bf16 v[4:7], v[148:151], v[188:191], v[4:7]
	v_mfma_f32_16x16x32_bf16 v[0:3], v[156:159], v[188:191], v[0:3]
	s_barrier
; #define PG8_STAGE(bufoff, gbase, voff) do { _Pragma("unroll") for (int _i = 0; _i < 2; ++_i) \
;         __builtin_amdgcn_global_load_lds((const unsigned*)((const char*)(gbase) + (voff)[_i]), (LAS unsigned*)(lds + (bufoff) + ldsw + _i * 8192), 16, 0, 0); } while (0)
; #define PG8_LDA(dst, b, h) do { _Pragma("unroll") for (int m = 0; m < 4; ++m) _Pragma("unroll") for (int k = 0; k < 2; ++k) dst[m][k] = *(const LAS bf16x8*)(lds + PG8_SA(b, h) + aoff + m * 2048 + k * 1024); } while (0)
; #define PG8_LDB(dst, b, h) do { _Pragma("unroll") for (int n = 0; n < 2; ++n) _Pragma("unroll") for (int k = 0; k < 2; ++k) dst[n][k] = *(const LAS bf16x8*)(lds + PG8_SB(b, h) + boff + n * 2048 + k * 1024); } while (0)
; #define PG8_MMA(ai, bj, At, Bt) do { __builtin_amdgcn_s_setprio(1); _Pragma("unroll") for (int m = 0; m < 4; ++m) _Pragma("unroll") for (int n = 0; n < 2; ++n) _Pragma("unroll") for (int k = 0; k < 2; ++k) \
;         acc[ai][bj][m][n] = __builtin_amdgcn_mfma_f32_16x16x32_bf16(Bt[n][k], At[m][k], acc[ai][bj][m][n], 0, 0, 0); __builtin_amdgcn_s_setprio(0); } while (0)
; #define PG8_WAIT_V(n) asm volatile("s_waitcnt vmcnt(" #n ")" ::: "memory")
; #define PG8_WAIT_L(n) asm volatile("s_waitcnt lgkmcnt(" #n ")" ::: "memory")
; #define PG8_BAR __builtin_amdgcn_s_barrier()
; #define PG8_SCHED __builtin_amdgcn_sched_barrier(0)
; template <class Epi>
; __device__ __forceinline__ void gemm_phase(LAS unsigned char* lds, const Gemm g, const StaticOrder S, const Epi E) {
;     ...
;         for (int t = 0; t < nt; t += 2) {
;     ...
;             PG8_LDB(B0, 1, 0); PG8_LDB(B1, 1, 1); PG8_SCHED; PG8_LDA(At, 1, 0); PG8_STAGE(PG8_SA(0, 1), a2 + hstepA, voffA);
;             PG8_WAIT_V(8); PG8_WAIT_L(0); PG8_BAR; PG8_MMA(0, 0, At, B0); PG8_MMA(0, 1, At, B1); PG8_BAR; PG8_SCHED;
;             PG8_LDA(At, 1, 1); PG8_STAGE(PG8_SB(1, 0), b3, voffB); PG8_STAGE(PG8_SB(1, 1), b3 + hstepB, voffB); PG8_STAGE(PG8_SA(1, 0), a3, voffA);
;             PG8_WAIT_V(8); PG8_WAIT_L(0); PG8_BAR; PG8_MMA(1, 0, At, B0); PG8_MMA(1, 1, At, B1); PG8_BAR; PG8_SCHED;
	s_add_i32 s17, 0, 0x18000
	s_add_i32 s63, 0, 0x1c000
	v_add_u32_e32 v140, s17, v227
	v_add_u32_e32 v156, s63, v227
	ds_read_b128 v[128:131], v140
	ds_read_b128 v[132:135], v140 offset:1024
	ds_read_b128 v[136:139], v140 offset:2048
	ds_read_b128 v[140:143], v140 offset:3072
	ds_read_b128 v[144:147], v156
	ds_read_b128 v[148:151], v156 offset:1024
	ds_read_b128 v[152:155], v156 offset:2048
	ds_read_b128 v[156:159], v156 offset:3072
	s_add_u32 s46, s46, 0x80000
	s_addc_u32 s47, s47, 0
	s_mov_b32 m0, s51
	ds_read_b128 v[160:163], v229 offset:32768
	ds_read_b128 v[164:167], v229 offset:33792
	ds_read_b128 v[168:171], v229 offset:34816
	ds_read_b128 v[172:175], v229 offset:35840
	ds_read_b128 v[176:179], v229 offset:36864
	ds_read_b128 v[180:183], v229 offset:37888
	ds_read_b128 v[184:187], v229 offset:38912
	ds_read_b128 v[188:191], v229 offset:39936
	global_load_lds_dwordx4 v192, s[46:47]
	s_mov_b32 m0, s52
	s_nop 0
	global_load_lds_dwordx4 v196, s[46:47]
	s_waitcnt vmcnt(8)
	s_waitcnt lgkmcnt(0)
	s_barrier
	s_waitcnt lgkmcnt(0)
	v_mfma_f32_16x16x32_bf16 v[124:127], v[128:131], v[160:163], v[124:127]
	v_mfma_f32_16x16x32_bf16 v[120:123], v[136:139], v[160:163], v[120:123]
	v_mfma_f32_16x16x32_bf16 v[108:111], v[128:131], v[168:171], v[108:111]
	v_mfma_f32_16x16x32_bf16 v[104:107], v[136:139], v[168:171], v[104:107]
	v_mfma_f32_16x16x32_bf16 v[92:95], v[128:131], v[176:179], v[92:95]
	v_mfma_f32_16x16x32_bf16 v[88:91], v[136:139], v[176:179], v[88:91]
	v_mfma_f32_16x16x32_bf16 v[76:79], v[128:131], v[184:187], v[76:79]
	v_mfma_f32_16x16x32_bf16 v[72:75], v[136:139], v[184:187], v[72:75]
	v_mfma_f32_16x16x32_bf16 v[124:127], v[132:135], v[164:167], v[124:127]
	v_mfma_f32_16x16x32_bf16 v[120:123], v[140:143], v[164:167], v[120:123]
	v_mfma_f32_16x16x32_bf16 v[108:111], v[132:135], v[172:175], v[108:111]
	v_mfma_f32_16x16x32_bf16 v[104:107], v[140:143], v[172:175], v[104:107]
	v_mfma_f32_16x16x32_bf16 v[92:95], v[132:135], v[180:183], v[92:95]
	v_mfma_f32_16x16x32_bf16 v[88:91], v[140:143], v[180:183], v[88:91]
	v_mfma_f32_16x16x32_bf16 v[76:79], v[132:135], v[188:191], v[76:79]
	v_mfma_f32_16x16x32_bf16 v[72:75], v[140:143], v[188:191], v[72:75]
	v_mfma_f32_16x16x32_bf16 v[116:119], v[144:147], v[160:163], v[116:119]
	v_mfma_f32_16x16x32_bf16 v[112:115], v[152:155], v[160:163], v[112:115]
	v_mfma_f32_16x16x32_bf16 v[100:103], v[144:147], v[168:171], v[100:103]
	v_mfma_f32_16x16x32_bf16 v[96:99], v[152:155], v[168:171], v[96:99]
	v_mfma_f32_16x16x32_bf16 v[84:87], v[144:147], v[176:179], v[84:87]
	v_mfma_f32_16x16x32_bf16 v[80:83], v[152:155], v[176:179], v[80:83]
	v_mfma_f32_16x16x32_bf16 v[68:71], v[144:147], v[184:187], v[68:71]
	v_mfma_f32_16x16x32_bf16 v[64:67], v[152:155], v[184:187], v[64:67]
	v_mfma_f32_16x16x32_bf16 v[116:119], v[148:151], v[164:167], v[116:119]
	v_mfma_f32_16x16x32_bf16 v[112:115], v[156:159], v[164:167], v[112:115]
	v_mfma_f32_16x16x32_bf16 v[100:103], v[148:151], v[172:175], v[100:103]
	v_mfma_f32_16x16x32_bf16 v[96:99], v[156:159], v[172:175], v[96:99]
	v_mfma_f32_16x16x32_bf16 v[84:87], v[148:151], v[180:183], v[84:87]
	v_mfma_f32_16x16x32_bf16 v[80:83], v[156:159], v[180:183], v[80:83]
	v_mfma_f32_16x16x32_bf16 v[68:71], v[148:151], v[188:191], v[68:71]
	v_mfma_f32_16x16x32_bf16 v[64:67], v[156:159], v[188:191], v[64:67]
	s_barrier
	s_add_u32 s42, s42, s44
	s_addc_u32 s43, s43, s45
	s_add_i32 s17, s17, s33
	s_mov_b32 m0, s17
	ds_read_b128 v[160:163], v229 offset:49152
	ds_read_b128 v[164:167], v229 offset:50176
	ds_read_b128 v[168:171], v229 offset:51200
	ds_read_b128 v[172:175], v229 offset:52224
	ds_read_b128 v[176:179], v229 offset:53248
	ds_read_b128 v[180:183], v229 offset:54272
	ds_read_b128 v[184:187], v229 offset:55296
	ds_read_b128 v[188:191], v229 offset:56320
	global_load_lds_dwordx4 v194, s[42:43]
	s_add_i32 m0, s17, 0x2000
	s_nop 0
	global_load_lds_dwordx4 v198, s[42:43]
	s_add_u32 s42, s42, 0x80000
	s_addc_u32 s43, s43, 0
	s_add_i32 s17, s63, s33
	s_mov_b32 m0, s17
	s_nop 0
	global_load_lds_dwordx4 v194, s[42:43]
	s_add_i32 m0, s17, 0x2000
	s_nop 0
	global_load_lds_dwordx4 v198, s[42:43]
	s_mov_b32 m0, s54
	s_nop 0
	global_load_lds_dwordx4 v192, s[48:49]
	s_mov_b32 m0, s55
	s_nop 0
	global_load_lds_dwordx4 v196, s[48:49]
	s_waitcnt vmcnt(8)
	s_waitcnt lgkmcnt(0)
	s_barrier
	s_waitcnt lgkmcnt(0)
	v_mfma_f32_16x16x32_bf16 v[60:63], v[128:131], v[160:163], v[60:63]
	v_mfma_f32_16x16x32_bf16 v[56:59], v[136:139], v[160:163], v[56:59]
	v_mfma_f32_16x16x32_bf16 v[44:47], v[128:131], v[168:171], v[44:47]
	v_mfma_f32_16x16x32_bf16 v[40:43], v[136:139], v[168:171], v[40:43]
	v_mfma_f32_16x16x32_bf16 v[28:31], v[128:131], v[176:179], v[28:31]
	v_mfma_f32_16x16x32_bf16 v[24:27], v[136:139], v[176:179], v[24:27]
	v_mfma_f32_16x16x32_bf16 v[12:15], v[128:131], v[184:187], v[12:15]
	v_mfma_f32_16x16x32_bf16 v[8:11], v[136:139], v[184:187], v[8:11]
	v_mfma_f32_16x16x32_bf16 v[60:63], v[132:135], v[164:167], v[60:63]
	v_mfma_f32_16x16x32_bf16 v[56:59], v[140:143], v[164:167], v[56:59]
	v_mfma_f32_16x16x32_bf16 v[44:47], v[132:135], v[172:175], v[44:47]
	v_mfma_f32_16x16x32_bf16 v[40:43], v[140:143], v[172:175], v[40:43]
	v_mfma_f32_16x16x32_bf16 v[28:31], v[132:135], v[180:183], v[28:31]
	v_mfma_f32_16x16x32_bf16 v[24:27], v[140:143], v[180:183], v[24:27]
	v_mfma_f32_16x16x32_bf16 v[12:15], v[132:135], v[188:191], v[12:15]
	v_mfma_f32_16x16x32_bf16 v[8:11], v[140:143], v[188:191], v[8:11]
	v_mfma_f32_16x16x32_bf16 v[52:55], v[144:147], v[160:163], v[52:55]
	v_mfma_f32_16x16x32_bf16 v[48:51], v[152:155], v[160:163], v[48:51]
	v_mfma_f32_16x16x32_bf16 v[36:39], v[144:147], v[168:171], v[36:39]
	v_mfma_f32_16x16x32_bf16 v[32:35], v[152:155], v[168:171], v[32:35]
	v_mfma_f32_16x16x32_bf16 v[20:23], v[144:147], v[176:179], v[20:23]
	v_mfma_f32_16x16x32_bf16 v[16:19], v[152:155], v[176:179], v[16:19]
	v_mfma_f32_16x16x32_bf16 v[4:7], v[144:147], v[184:187], v[4:7]
	v_mfma_f32_16x16x32_bf16 v[0:3], v[152:155], v[184:187], v[0:3]
	v_mfma_f32_16x16x32_bf16 v[52:55], v[148:151], v[164:167], v[52:55]
	v_mfma_f32_16x16x32_bf16 v[48:51], v[156:159], v[164:167], v[48:51]
	v_mfma_f32_16x16x32_bf16 v[36:39], v[148:151], v[172:175], v[36:39]
	v_mfma_f32_16x16x32_bf16 v[32:35], v[156:159], v[172:175], v[32:35]
	v_mfma_f32_16x16x32_bf16 v[20:23], v[148:151], v[180:183], v[20:23]
	v_mfma_f32_16x16x32_bf16 v[16:19], v[156:159], v[180:183], v[16:19]
	v_mfma_f32_16x16x32_bf16 v[4:7], v[148:151], v[188:191], v[4:7]
	v_mfma_f32_16x16x32_bf16 v[0:3], v[156:159], v[188:191], v[0:3]
	s_barrier
	s_cmp_gt_u32 s3, 29
	s_mov_b32 s3, s15
	s_cbranch_scc1 .LBB0_1037

; #define PG8_STAGE(bufoff, gbase, voff) do { _Pragma("unroll") for (int _i = 0; _i < 2; ++_i) \
;         __builtin_amdgcn_global_load_lds((const unsigned*)((const char*)(gbase) + (voff)[_i]), (LAS unsigned*)(lds + (bufoff) + ldsw + _i * 8192), 16, 0, 0); } while (0)
; #define PG8_LDA(dst, b, h) do { _Pragma("unroll") for (int m = 0; m < 4; ++m) _Pragma("unroll") for (int k = 0; k < 2; ++k) dst[m][k] = *(const LAS bf16x8*)(lds + PG8_SA(b, h) + aoff + m * 2048 + k * 1024); } while (0)
; #define PG8_LDB(dst, b, h) do { _Pragma("unroll") for (int n = 0; n < 2; ++n) _Pragma("unroll") for (int k = 0; k < 2; ++k) dst[n][k] = *(const LAS bf16x8*)(lds + PG8_SB(b, h) + boff + n * 2048 + k * 1024); } while (0)
; #define PG8_MMA(ai, bj, At, Bt) do { __builtin_amdgcn_s_setprio(1); _Pragma("unroll") for (int m = 0; m < 4; ++m) _Pragma("unroll") for (int n = 0; n < 2; ++n) _Pragma("unroll") for (int k = 0; k < 2; ++k) \
;         acc[ai][bj][m][n] = __builtin_amdgcn_mfma_f32_16x16x32_bf16(Bt[n][k], At[m][k], acc[ai][bj][m][n], 0, 0, 0); __builtin_amdgcn_s_setprio(0); } while (0)
; #define PG8_WAIT_V(n) asm volatile("s_waitcnt vmcnt(" #n ")" ::: "memory")
; #define PG8_WAIT_L(n) asm volatile("s_waitcnt lgkmcnt(" #n ")" ::: "memory")
; #define PG8_BAR __builtin_amdgcn_s_barrier()
; #define PG8_SCHED __builtin_amdgcn_sched_barrier(0)
; template <class Epi>
; __device__ __forceinline__ void gemm_phase(LAS unsigned char* lds, const Gemm g, const StaticOrder S, const Epi E) {
;     ...
;             PG8_LDB(B0, 0, 0); PG8_LDB(B1, 0, 1); PG8_SCHED; PG8_LDA(At, 0, 0); PG8_STAGE(PG8_SA(1, 1), a1 + hstepA, voffA);
;             PG8_WAIT_V(8); PG8_WAIT_L(0); PG8_BAR; PG8_MMA(0, 0, At, B0); PG8_MMA(0, 1, At, B1); PG8_BAR; PG8_SCHED;
;             PG8_LDA(At, 0, 1); PG8_STAGE(PG8_SB(0, 0), b2, voffB); PG8_STAGE(PG8_SB(0, 1), b2 + hstepB, voffB); PG8_STAGE(PG8_SA(0, 0), a2, voffA);
;             PG8_WAIT_V(8); PG8_WAIT_L(0); PG8_BAR; PG8_MMA(1, 0, At, B0); PG8_MMA(1, 1, At, B1); PG8_BAR; PG8_SCHED;
.LBB0_1373:
	v_add_u32_e32 v152, s64, v164
	v_add_u32_e32 v176, s65, v164
	ds_read_b128 v[128:131], v152
	ds_read_b128 v[132:135], v152 offset:1024
	ds_read_b128 v[136:139], v152 offset:2048
	ds_read_b128 v[152:155], v152 offset:3072
	ds_read_b128 v[156:159], v176
	ds_read_b128 v[168:171], v176 offset:1024
	ds_read_b128 v[172:175], v176 offset:2048
	ds_read_b128 v[176:179], v176 offset:3072
	s_or_b32 s23, s31, 1
	s_mul_i32 s54, s41, s23
	s_mul_hi_u32 s55, s40, s23
	s_add_i32 s55, s55, s54
	s_mul_i32 s23, s40, s23
	s_add_u32 s23, s38, s23
	s_addc_u32 s71, s39, s55
	s_add_u32 s54, s52, s50
	s_addc_u32 s55, s53, s51
	s_add_u32 s72, s23, 0x80000
	s_addc_u32 s73, s71, 0
	s_add_i32 m0, s35, 0xc000
	ds_read_b128 v[180:183], v166
	ds_read_b128 v[184:187], v166 offset:1024
	ds_read_b128 v[188:191], v166 offset:2048
	ds_read_b128 v[192:195], v166 offset:3072
	ds_read_b128 v[196:199], v166 offset:4096
	ds_read_b128 v[200:203], v166 offset:5120
	ds_read_b128 v[204:207], v166 offset:6144
	ds_read_b128 v[208:211], v166 offset:7168
	global_load_lds_dwordx4 v140, s[72:73]
	s_add_i32 m0, s35, 0xe000
	s_nop 0
	global_load_lds_dwordx4 v144, s[72:73]
	s_waitcnt vmcnt(8)
	s_waitcnt lgkmcnt(0)
	s_barrier
	s_waitcnt lgkmcnt(0)
	v_mfma_f32_16x16x32_bf16 v[124:127], v[128:131], v[180:183], v[124:127]
	v_mfma_f32_16x16x32_bf16 v[120:123], v[136:139], v[180:183], v[120:123]
	v_mfma_f32_16x16x32_bf16 v[108:111], v[128:131], v[188:191], v[108:111]
	v_mfma_f32_16x16x32_bf16 v[104:107], v[136:139], v[188:191], v[104:107]
	v_mfma_f32_16x16x32_bf16 v[92:95], v[128:131], v[196:199], v[92:95]
	v_mfma_f32_16x16x32_bf16 v[88:91], v[136:139], v[196:199], v[88:91]
	v_mfma_f32_16x16x32_bf16 v[76:79], v[128:131], v[204:207], v[76:79]
	v_mfma_f32_16x16x32_bf16 v[72:75], v[136:139], v[204:207], v[72:75]
	v_mfma_f32_16x16x32_bf16 v[124:127], v[132:135], v[184:187], v[124:127]
	v_mfma_f32_16x16x32_bf16 v[120:123], v[152:155], v[184:187], v[120:123]
	v_mfma_f32_16x16x32_bf16 v[108:111], v[132:135], v[192:195], v[108:111]
	v_mfma_f32_16x16x32_bf16 v[104:107], v[152:155], v[192:195], v[104:107]
	v_mfma_f32_16x16x32_bf16 v[92:95], v[132:135], v[200:203], v[92:95]
	v_mfma_f32_16x16x32_bf16 v[88:91], v[152:155], v[200:203], v[88:91]
	v_mfma_f32_16x16x32_bf16 v[76:79], v[132:135], v[208:211], v[76:79]
	v_mfma_f32_16x16x32_bf16 v[72:75], v[152:155], v[208:211], v[72:75]
	v_mfma_f32_16x16x32_bf16 v[116:119], v[156:159], v[180:183], v[116:119]
	v_mfma_f32_16x16x32_bf16 v[112:115], v[172:175], v[180:183], v[112:115]
	v_mfma_f32_16x16x32_bf16 v[100:103], v[156:159], v[188:191], v[100:103]
	v_mfma_f32_16x16x32_bf16 v[96:99], v[172:175], v[188:191], v[96:99]
	v_mfma_f32_16x16x32_bf16 v[84:87], v[156:159], v[196:199], v[84:87]
	v_mfma_f32_16x16x32_bf16 v[80:83], v[172:175], v[196:199], v[80:83]
	v_mfma_f32_16x16x32_bf16 v[68:71], v[156:159], v[204:207], v[68:71]
	v_mfma_f32_16x16x32_bf16 v[64:67], v[172:175], v[204:207], v[64:67]
	v_mfma_f32_16x16x32_bf16 v[116:119], v[168:171], v[184:187], v[116:119]
	v_mfma_f32_16x16x32_bf16 v[112:115], v[176:179], v[184:187], v[112:115]
	v_mfma_f32_16x16x32_bf16 v[100:103], v[168:171], v[192:195], v[100:103]
	v_mfma_f32_16x16x32_bf16 v[96:99], v[176:179], v[192:195], v[96:99]
	v_mfma_f32_16x16x32_bf16 v[84:87], v[168:171], v[200:203], v[84:87]
	v_mfma_f32_16x16x32_bf16 v[80:83], v[176:179], v[200:203], v[80:83]
	v_mfma_f32_16x16x32_bf16 v[68:71], v[168:171], v[208:211], v[68:71]
	v_mfma_f32_16x16x32_bf16 v[64:67], v[176:179], v[208:211], v[64:67]
	s_barrier
	s_add_i32 s23, s64, s33
	s_mov_b32 m0, s23
	ds_read_b128 v[180:183], v166 offset:16384
	ds_read_b128 v[184:187], v166 offset:17408
	ds_read_b128 v[188:191], v166 offset:18432
	ds_read_b128 v[192:195], v166 offset:19456
	ds_read_b128 v[196:199], v166 offset:20480
	ds_read_b128 v[200:203], v166 offset:21504
	ds_read_b128 v[204:207], v166 offset:22528
	ds_read_b128 v[208:211], v166 offset:23552
	global_load_lds_dwordx4 v142, s[48:49]
	s_add_i32 m0, s23, 0x2000
	s_add_u32 s72, s48, 0x80000
	s_addc_u32 s73, s49, 0
	s_add_i32 s23, s65, s33
	global_load_lds_dwordx4 v146, s[48:49]
	s_mov_b32 m0, s23
	s_nop 0
	global_load_lds_dwordx4 v142, s[72:73]
	s_add_i32 m0, s23, 0x2000
	s_nop 0
	global_load_lds_dwordx4 v146, s[72:73]
	s_mov_b32 m0, s35
	s_nop 0
	global_load_lds_dwordx4 v140, s[52:53]
	s_mov_b32 m0, s56
	s_nop 0
	global_load_lds_dwordx4 v144, s[52:53]
	s_waitcnt vmcnt(8)
	s_waitcnt lgkmcnt(0)
	s_barrier
	s_waitcnt lgkmcnt(0)
	v_mfma_f32_16x16x32_bf16 v[60:63], v[128:131], v[180:183], v[60:63]
	v_mfma_f32_16x16x32_bf16 v[56:59], v[136:139], v[180:183], v[56:59]
	v_mfma_f32_16x16x32_bf16 v[44:47], v[128:131], v[188:191], v[44:47]
	v_mfma_f32_16x16x32_bf16 v[40:43], v[136:139], v[188:191], v[40:43]
	v_mfma_f32_16x16x32_bf16 v[28:31], v[128:131], v[196:199], v[28:31]
	v_mfma_f32_16x16x32_bf16 v[24:27], v[136:139], v[196:199], v[24:27]
	v_mfma_f32_16x16x32_bf16 v[12:15], v[128:131], v[204:207], v[12:15]
	v_mfma_f32_16x16x32_bf16 v[8:11], v[136:139], v[204:207], v[8:11]
	v_mfma_f32_16x16x32_bf16 v[60:63], v[132:135], v[184:187], v[60:63]
	v_mfma_f32_16x16x32_bf16 v[56:59], v[152:155], v[184:187], v[56:59]
	v_mfma_f32_16x16x32_bf16 v[44:47], v[132:135], v[192:195], v[44:47]
	v_mfma_f32_16x16x32_bf16 v[40:43], v[152:155], v[192:195], v[40:43]
	v_mfma_f32_16x16x32_bf16 v[28:31], v[132:135], v[200:203], v[28:31]
	v_mfma_f32_16x16x32_bf16 v[24:27], v[152:155], v[200:203], v[24:27]
	v_mfma_f32_16x16x32_bf16 v[12:15], v[132:135], v[208:211], v[12:15]
	v_mfma_f32_16x16x32_bf16 v[8:11], v[152:155], v[208:211], v[8:11]
	v_mfma_f32_16x16x32_bf16 v[52:55], v[156:159], v[180:183], v[52:55]
	v_mfma_f32_16x16x32_bf16 v[48:51], v[172:175], v[180:183], v[48:51]
	v_mfma_f32_16x16x32_bf16 v[36:39], v[156:159], v[188:191], v[36:39]
	v_mfma_f32_16x16x32_bf16 v[32:35], v[172:175], v[188:191], v[32:35]
	v_mfma_f32_16x16x32_bf16 v[20:23], v[156:159], v[196:199], v[20:23]
	v_mfma_f32_16x16x32_bf16 v[16:19], v[172:175], v[196:199], v[16:19]
	v_mfma_f32_16x16x32_bf16 v[4:7], v[156:159], v[204:207], v[4:7]
	v_mfma_f32_16x16x32_bf16 v[0:3], v[172:175], v[204:207], v[0:3]
	v_mfma_f32_16x16x32_bf16 v[52:55], v[168:171], v[184:187], v[52:55]
	v_mfma_f32_16x16x32_bf16 v[48:51], v[176:179], v[184:187], v[48:51]
	v_mfma_f32_16x16x32_bf16 v[36:39], v[168:171], v[192:195], v[36:39]
	v_mfma_f32_16x16x32_bf16 v[32:35], v[176:179], v[192:195], v[32:35]
	v_mfma_f32_16x16x32_bf16 v[20:23], v[168:171], v[200:203], v[20:23]
	v_mfma_f32_16x16x32_bf16 v[16:19], v[176:179], v[200:203], v[16:19]
	v_mfma_f32_16x16x32_bf16 v[4:7], v[168:171], v[208:211], v[4:7]
	v_mfma_f32_16x16x32_bf16 v[0:3], v[176:179], v[208:211], v[0:3]
	s_barrier
; #define PG8_STAGE(bufoff, gbase, voff) do { _Pragma("unroll") for (int _i = 0; _i < 2; ++_i) \
;         __builtin_amdgcn_global_load_lds((const unsigned*)((const char*)(gbase) + (voff)[_i]), (LAS unsigned*)(lds + (bufoff) + ldsw + _i * 8192), 16, 0, 0); } while (0)
; #define PG8_LDA(dst, b, h) do { _Pragma("unroll") for (int m = 0; m < 4; ++m) _Pragma("unroll") for (int k = 0; k < 2; ++k) dst[m][k] = *(const LAS bf16x8*)(lds + PG8_SA(b, h) + aoff + m * 2048 + k * 1024); } while (0)
; #define PG8_LDB(dst, b, h) do { _Pragma("unroll") for (int n = 0; n < 2; ++n) _Pragma("unroll") for (int k = 0; k < 2; ++k) dst[n][k] = *(const LAS bf16x8*)(lds + PG8_SB(b, h) + boff + n * 2048 + k * 1024); } while (0)
; #define PG8_MMA(ai, bj, At, Bt) do { __builtin_amdgcn_s_setprio(1); _Pragma("unroll") for (int m = 0; m < 4; ++m) _Pragma("unroll") for (int n = 0; n < 2; ++n) _Pragma("unroll") for (int k = 0; k < 2; ++k) \
;         acc[ai][bj][m][n] = __builtin_amdgcn_mfma_f32_16x16x32_bf16(Bt[n][k], At[m][k], acc[ai][bj][m][n], 0, 0, 0); __builtin_amdgcn_s_setprio(0); } while (0)
; #define PG8_WAIT_V(n) asm volatile("s_waitcnt vmcnt(" #n ")" ::: "memory")
; #define PG8_WAIT_L(n) asm volatile("s_waitcnt lgkmcnt(" #n ")" ::: "memory")
; #define PG8_BAR __builtin_amdgcn_s_barrier()
; #define PG8_SCHED __builtin_amdgcn_sched_barrier(0)
; template <class Epi>
; __device__ __forceinline__ void gemm_phase(LAS unsigned char* lds, const Gemm g, const StaticOrder S, const Epi E) {
;     ...
;         for (int t = 0; t < nt; t += 2) {
;     ...
;             PG8_LDB(B0, 1, 0); PG8_LDB(B1, 1, 1); PG8_SCHED; PG8_LDA(At, 1, 0); PG8_STAGE(PG8_SA(0, 1), a2 + hstepA, voffA);
;             PG8_WAIT_V(8); PG8_WAIT_L(0); PG8_BAR; PG8_MMA(0, 0, At, B0); PG8_MMA(0, 1, At, B1); PG8_BAR; PG8_SCHED;
;             PG8_LDA(At, 1, 1); PG8_STAGE(PG8_SB(1, 0), b3, voffB); PG8_STAGE(PG8_SB(1, 1), b3 + hstepB, voffB); PG8_STAGE(PG8_SA(1, 0), a3, voffA);
;             PG8_WAIT_V(8); PG8_WAIT_L(0); PG8_BAR; PG8_MMA(1, 0, At, B0); PG8_MMA(1, 1, At, B1); PG8_BAR; PG8_SCHED;
	s_add_i32 s23, 0, 0x18000
	s_add_i32 s71, 0, 0x1c000
	v_add_u32_e32 v152, s23, v164
	v_add_u32_e32 v176, s71, v164
	ds_read_b128 v[128:131], v152
	ds_read_b128 v[132:135], v152 offset:1024
	ds_read_b128 v[136:139], v152 offset:2048
	ds_read_b128 v[152:155], v152 offset:3072
	ds_read_b128 v[156:159], v176
	ds_read_b128 v[168:171], v176 offset:1024
	ds_read_b128 v[172:175], v176 offset:2048
	ds_read_b128 v[176:179], v176 offset:3072
	s_add_u32 s52, s52, 0x80000
	s_addc_u32 s53, s53, 0
	s_mov_b32 m0, s57
	ds_read_b128 v[180:183], v166 offset:32768
	ds_read_b128 v[184:187], v166 offset:33792
	ds_read_b128 v[188:191], v166 offset:34816
	ds_read_b128 v[192:195], v166 offset:35840
	ds_read_b128 v[196:199], v166 offset:36864
	ds_read_b128 v[200:203], v166 offset:37888
	ds_read_b128 v[204:207], v166 offset:38912
	ds_read_b128 v[208:211], v166 offset:39936
	global_load_lds_dwordx4 v140, s[52:53]
	s_mov_b32 m0, s58
	s_nop 0
	global_load_lds_dwordx4 v144, s[52:53]
	s_waitcnt vmcnt(8)
	s_waitcnt lgkmcnt(0)
	s_barrier
	s_waitcnt lgkmcnt(0)
	v_mfma_f32_16x16x32_bf16 v[124:127], v[128:131], v[180:183], v[124:127]
	v_mfma_f32_16x16x32_bf16 v[120:123], v[136:139], v[180:183], v[120:123]
	v_mfma_f32_16x16x32_bf16 v[108:111], v[128:131], v[188:191], v[108:111]
	v_mfma_f32_16x16x32_bf16 v[104:107], v[136:139], v[188:191], v[104:107]
	v_mfma_f32_16x16x32_bf16 v[92:95], v[128:131], v[196:199], v[92:95]
	v_mfma_f32_16x16x32_bf16 v[88:91], v[136:139], v[196:199], v[88:91]
	v_mfma_f32_16x16x32_bf16 v[76:79], v[128:131], v[204:207], v[76:79]
	v_mfma_f32_16x16x32_bf16 v[72:75], v[136:139], v[204:207], v[72:75]
	v_mfma_f32_16x16x32_bf16 v[124:127], v[132:135], v[184:187], v[124:127]
	v_mfma_f32_16x16x32_bf16 v[120:123], v[152:155], v[184:187], v[120:123]
	v_mfma_f32_16x16x32_bf16 v[108:111], v[132:135], v[192:195], v[108:111]
	v_mfma_f32_16x16x32_bf16 v[104:107], v[152:155], v[192:195], v[104:107]
	v_mfma_f32_16x16x32_bf16 v[92:95], v[132:135], v[200:203], v[92:95]
	v_mfma_f32_16x16x32_bf16 v[88:91], v[152:155], v[200:203], v[88:91]
	v_mfma_f32_16x16x32_bf16 v[76:79], v[132:135], v[208:211], v[76:79]
	v_mfma_f32_16x16x32_bf16 v[72:75], v[152:155], v[208:211], v[72:75]
	v_mfma_f32_16x16x32_bf16 v[116:119], v[156:159], v[180:183], v[116:119]
	v_mfma_f32_16x16x32_bf16 v[112:115], v[172:175], v[180:183], v[112:115]
	v_mfma_f32_16x16x32_bf16 v[100:103], v[156:159], v[188:191], v[100:103]
	v_mfma_f32_16x16x32_bf16 v[96:99], v[172:175], v[188:191], v[96:99]
	v_mfma_f32_16x16x32_bf16 v[84:87], v[156:159], v[196:199], v[84:87]
	v_mfma_f32_16x16x32_bf16 v[80:83], v[172:175], v[196:199], v[80:83]
	v_mfma_f32_16x16x32_bf16 v[68:71], v[156:159], v[204:207], v[68:71]
	v_mfma_f32_16x16x32_bf16 v[64:67], v[172:175], v[204:207], v[64:67]
	v_mfma_f32_16x16x32_bf16 v[116:119], v[168:171], v[184:187], v[116:119]
	v_mfma_f32_16x16x32_bf16 v[112:115], v[176:179], v[184:187], v[112:115]
	v_mfma_f32_16x16x32_bf16 v[100:103], v[168:171], v[192:195], v[100:103]
	v_mfma_f32_16x16x32_bf16 v[96:99], v[176:179], v[192:195], v[96:99]
	v_mfma_f32_16x16x32_bf16 v[84:87], v[168:171], v[200:203], v[84:87]
	v_mfma_f32_16x16x32_bf16 v[80:83], v[176:179], v[200:203], v[80:83]
	v_mfma_f32_16x16x32_bf16 v[68:71], v[168:171], v[208:211], v[68:71]
	v_mfma_f32_16x16x32_bf16 v[64:67], v[176:179], v[208:211], v[64:67]
	s_barrier
	s_add_u32 s48, s48, s50
	s_addc_u32 s49, s49, s51
	s_add_i32 s23, s23, s33
	s_mov_b32 m0, s23
	ds_read_b128 v[180:183], v166 offset:49152
	ds_read_b128 v[184:187], v166 offset:50176
	ds_read_b128 v[188:191], v166 offset:51200
	ds_read_b128 v[192:195], v166 offset:52224
	ds_read_b128 v[196:199], v166 offset:53248
	ds_read_b128 v[200:203], v166 offset:54272
	ds_read_b128 v[204:207], v166 offset:55296
	ds_read_b128 v[208:211], v166 offset:56320
	global_load_lds_dwordx4 v142, s[48:49]
	s_add_i32 m0, s23, 0x2000
	s_nop 0
	global_load_lds_dwordx4 v146, s[48:49]
	s_add_u32 s48, s48, 0x80000
	s_addc_u32 s49, s49, 0
	s_add_i32 s23, s71, s33
	s_mov_b32 m0, s23
	s_nop 0
	global_load_lds_dwordx4 v142, s[48:49]
	s_add_i32 m0, s23, 0x2000
	s_nop 0
	global_load_lds_dwordx4 v146, s[48:49]
	s_mov_b32 m0, s60
	s_nop 0
	global_load_lds_dwordx4 v140, s[54:55]
	s_mov_b32 m0, s61
	s_nop 0
	global_load_lds_dwordx4 v144, s[54:55]
	s_waitcnt vmcnt(8)
	s_waitcnt lgkmcnt(0)
	s_barrier
	s_waitcnt lgkmcnt(0)
	v_mfma_f32_16x16x32_bf16 v[60:63], v[128:131], v[180:183], v[60:63]
	v_mfma_f32_16x16x32_bf16 v[56:59], v[136:139], v[180:183], v[56:59]
	v_mfma_f32_16x16x32_bf16 v[44:47], v[128:131], v[188:191], v[44:47]
	v_mfma_f32_16x16x32_bf16 v[40:43], v[136:139], v[188:191], v[40:43]
	v_mfma_f32_16x16x32_bf16 v[28:31], v[128:131], v[196:199], v[28:31]
	v_mfma_f32_16x16x32_bf16 v[24:27], v[136:139], v[196:199], v[24:27]
	v_mfma_f32_16x16x32_bf16 v[12:15], v[128:131], v[204:207], v[12:15]
	v_mfma_f32_16x16x32_bf16 v[8:11], v[136:139], v[204:207], v[8:11]
	v_mfma_f32_16x16x32_bf16 v[60:63], v[132:135], v[184:187], v[60:63]
	v_mfma_f32_16x16x32_bf16 v[56:59], v[152:155], v[184:187], v[56:59]
	v_mfma_f32_16x16x32_bf16 v[44:47], v[132:135], v[192:195], v[44:47]
	v_mfma_f32_16x16x32_bf16 v[40:43], v[152:155], v[192:195], v[40:43]
	v_mfma_f32_16x16x32_bf16 v[28:31], v[132:135], v[200:203], v[28:31]
	v_mfma_f32_16x16x32_bf16 v[24:27], v[152:155], v[200:203], v[24:27]
	v_mfma_f32_16x16x32_bf16 v[12:15], v[132:135], v[208:211], v[12:15]
	v_mfma_f32_16x16x32_bf16 v[8:11], v[152:155], v[208:211], v[8:11]
	v_mfma_f32_16x16x32_bf16 v[52:55], v[156:159], v[180:183], v[52:55]
	v_mfma_f32_16x16x32_bf16 v[48:51], v[172:175], v[180:183], v[48:51]
	v_mfma_f32_16x16x32_bf16 v[36:39], v[156:159], v[188:191], v[36:39]
	v_mfma_f32_16x16x32_bf16 v[32:35], v[172:175], v[188:191], v[32:35]
	v_mfma_f32_16x16x32_bf16 v[20:23], v[156:159], v[196:199], v[20:23]
	v_mfma_f32_16x16x32_bf16 v[16:19], v[172:175], v[196:199], v[16:19]
	v_mfma_f32_16x16x32_bf16 v[4:7], v[156:159], v[204:207], v[4:7]
	v_mfma_f32_16x16x32_bf16 v[0:3], v[172:175], v[204:207], v[0:3]
	v_mfma_f32_16x16x32_bf16 v[52:55], v[168:171], v[184:187], v[52:55]
	v_mfma_f32_16x16x32_bf16 v[48:51], v[176:179], v[184:187], v[48:51]
	v_mfma_f32_16x16x32_bf16 v[36:39], v[168:171], v[192:195], v[36:39]
	v_mfma_f32_16x16x32_bf16 v[32:35], v[176:179], v[192:195], v[32:35]
	v_mfma_f32_16x16x32_bf16 v[20:23], v[168:171], v[200:203], v[20:23]
	v_mfma_f32_16x16x32_bf16 v[16:19], v[176:179], v[200:203], v[16:19]
	v_mfma_f32_16x16x32_bf16 v[4:7], v[168:171], v[208:211], v[4:7]
	v_mfma_f32_16x16x32_bf16 v[0:3], v[176:179], v[208:211], v[0:3]
	s_barrier
	s_cmp_gt_u32 s31, 29
	s_mov_b32 s31, s21
	s_cbranch_scc1 .LBB0_1378

; #define PG8_STAGE(bufoff, gbase, voff) do { _Pragma("unroll") for (int _i = 0; _i < 2; ++_i) \
;         __builtin_amdgcn_global_load_lds((const unsigned*)((const char*)(gbase) + (voff)[_i]), (LAS unsigned*)(lds + (bufoff) + ldsw + _i * 8192), 16, 0, 0); } while (0)
; #define PG8_LDA(dst, b, h) do { _Pragma("unroll") for (int m = 0; m < 4; ++m) _Pragma("unroll") for (int k = 0; k < 2; ++k) dst[m][k] = *(const LAS bf16x8*)(lds + PG8_SA(b, h) + aoff + m * 2048 + k * 1024); } while (0)
; #define PG8_LDB(dst, b, h) do { _Pragma("unroll") for (int n = 0; n < 2; ++n) _Pragma("unroll") for (int k = 0; k < 2; ++k) dst[n][k] = *(const LAS bf16x8*)(lds + PG8_SB(b, h) + boff + n * 2048 + k * 1024); } while (0)
; #define PG8_MMA(ai, bj, At, Bt) do { __builtin_amdgcn_s_setprio(1); _Pragma("unroll") for (int m = 0; m < 4; ++m) _Pragma("unroll") for (int n = 0; n < 2; ++n) _Pragma("unroll") for (int k = 0; k < 2; ++k) \
;         acc[ai][bj][m][n] = __builtin_amdgcn_mfma_f32_16x16x32_bf16(Bt[n][k], At[m][k], acc[ai][bj][m][n], 0, 0, 0); __builtin_amdgcn_s_setprio(0); } while (0)
; #define PG8_WAIT_V(n) asm volatile("s_waitcnt vmcnt(" #n ")" ::: "memory")
; #define PG8_WAIT_L(n) asm volatile("s_waitcnt lgkmcnt(" #n ")" ::: "memory")
; #define PG8_BAR __builtin_amdgcn_s_barrier()
; #define PG8_SCHED __builtin_amdgcn_sched_barrier(0)
; template <class Epi>
; __device__ __forceinline__ void gemm_phase(LAS unsigned char* lds, const Gemm g, const StaticOrder S, const Epi E) {
;     ...
;             PG8_LDB(B0, 0, 0); PG8_LDB(B1, 0, 1); PG8_SCHED; PG8_LDA(At, 0, 0); PG8_STAGE(PG8_SA(1, 1), a1 + hstepA, voffA);
;             PG8_WAIT_V(8); PG8_WAIT_L(0); PG8_BAR; PG8_MMA(0, 0, At, B0); PG8_MMA(0, 1, At, B1); PG8_BAR; PG8_SCHED;
;             PG8_LDA(At, 0, 1); PG8_STAGE(PG8_SB(0, 0), b2, voffB); PG8_STAGE(PG8_SB(0, 1), b2 + hstepB, voffB); PG8_STAGE(PG8_SA(0, 0), a2, voffA);
;             PG8_WAIT_V(8); PG8_WAIT_L(0); PG8_BAR; PG8_MMA(1, 0, At, B0); PG8_MMA(1, 1, At, B1); PG8_BAR; PG8_SCHED;
.LBB0_1473:
	ds_read_b128 v[148:151], v254
	ds_read_b128 v[152:155], v254 offset:1024
	ds_read_b128 v[156:159], v254 offset:2048
	ds_read_b128 v[160:163], v254 offset:3072
	ds_read_b128 v[164:167], v254 offset:16384
	ds_read_b128 v[168:171], v254 offset:17408
	ds_read_b128 v[172:175], v254 offset:18432
	ds_read_b128 v[176:179], v254 offset:19456
	s_or_b32 s13, s60, 1
	s_mul_i32 s42, s27, s13
	s_mul_hi_u32 s43, s26, s13
	s_add_i32 s43, s43, s42
	s_mul_i32 s13, s26, s13
	s_add_u32 s13, s24, s13
	s_addc_u32 s61, s25, s43
	s_add_u32 s42, s40, s38
	s_addc_u32 s43, s41, s39
	s_add_u32 s62, s13, 0x80000
	s_addc_u32 s63, s61, 0
	s_add_i32 m0, s21, 0xc000
	ds_read_b128 v[180:183], v145
	ds_read_b128 v[184:187], v145 offset:1024
	ds_read_b128 v[188:191], v145 offset:2048
	ds_read_b128 v[192:195], v145 offset:3072
	ds_read_b128 v[196:199], v145 offset:4096
	ds_read_b128 v[200:203], v145 offset:5120
	ds_read_b128 v[204:207], v145 offset:6144
	ds_read_b128 v[208:211], v145 offset:7168
	global_load_lds_dwordx4 v134, s[62:63]
	s_add_i32 m0, s21, 0xe000
	s_nop 0
	global_load_lds_dwordx4 v130, s[62:63]
	s_waitcnt vmcnt(8)
	s_waitcnt lgkmcnt(0)
	s_barrier
	s_waitcnt lgkmcnt(0)
	v_mfma_f32_16x16x32_bf16 v[116:119], v[148:151], v[180:183], v[116:119]
	v_mfma_f32_16x16x32_bf16 v[112:115], v[156:159], v[180:183], v[112:115]
	v_mfma_f32_16x16x32_bf16 v[108:111], v[148:151], v[188:191], v[108:111]
	v_mfma_f32_16x16x32_bf16 v[104:107], v[156:159], v[188:191], v[104:107]
	v_mfma_f32_16x16x32_bf16 v[92:95], v[148:151], v[196:199], v[92:95]
	v_mfma_f32_16x16x32_bf16 v[88:91], v[156:159], v[196:199], v[88:91]
	v_mfma_f32_16x16x32_bf16 v[76:79], v[148:151], v[204:207], v[76:79]
	v_mfma_f32_16x16x32_bf16 v[72:75], v[156:159], v[204:207], v[72:75]
	v_mfma_f32_16x16x32_bf16 v[116:119], v[152:155], v[184:187], v[116:119]
	v_mfma_f32_16x16x32_bf16 v[112:115], v[160:163], v[184:187], v[112:115]
	v_mfma_f32_16x16x32_bf16 v[108:111], v[152:155], v[192:195], v[108:111]
	v_mfma_f32_16x16x32_bf16 v[104:107], v[160:163], v[192:195], v[104:107]
	v_mfma_f32_16x16x32_bf16 v[92:95], v[152:155], v[200:203], v[92:95]
	v_mfma_f32_16x16x32_bf16 v[88:91], v[160:163], v[200:203], v[88:91]
	v_mfma_f32_16x16x32_bf16 v[76:79], v[152:155], v[208:211], v[76:79]
	v_mfma_f32_16x16x32_bf16 v[72:75], v[160:163], v[208:211], v[72:75]
	v_mfma_f32_16x16x32_bf16 v[124:127], v[164:167], v[180:183], v[124:127]
	v_mfma_f32_16x16x32_bf16 v[120:123], v[172:175], v[180:183], v[120:123]
	v_mfma_f32_16x16x32_bf16 v[100:103], v[164:167], v[188:191], v[100:103]
	v_mfma_f32_16x16x32_bf16 v[96:99], v[172:175], v[188:191], v[96:99]
	v_mfma_f32_16x16x32_bf16 v[84:87], v[164:167], v[196:199], v[84:87]
	v_mfma_f32_16x16x32_bf16 v[80:83], v[172:175], v[196:199], v[80:83]
	v_mfma_f32_16x16x32_bf16 v[68:71], v[164:167], v[204:207], v[68:71]
	v_mfma_f32_16x16x32_bf16 v[64:67], v[172:175], v[204:207], v[64:67]
	v_mfma_f32_16x16x32_bf16 v[124:127], v[168:171], v[184:187], v[124:127]
	v_mfma_f32_16x16x32_bf16 v[120:123], v[176:179], v[184:187], v[120:123]
	v_mfma_f32_16x16x32_bf16 v[100:103], v[168:171], v[192:195], v[100:103]
	v_mfma_f32_16x16x32_bf16 v[96:99], v[176:179], v[192:195], v[96:99]
	v_mfma_f32_16x16x32_bf16 v[84:87], v[168:171], v[200:203], v[84:87]
	v_mfma_f32_16x16x32_bf16 v[80:83], v[176:179], v[200:203], v[80:83]
	v_mfma_f32_16x16x32_bf16 v[68:71], v[168:171], v[208:211], v[68:71]
	v_mfma_f32_16x16x32_bf16 v[64:67], v[176:179], v[208:211], v[64:67]
	s_barrier
	s_add_i32 s13, s55, s45
	s_mov_b32 m0, s13
	ds_read_b128 v[180:183], v145 offset:16384
	ds_read_b128 v[184:187], v145 offset:17408
	ds_read_b128 v[188:191], v145 offset:18432
	ds_read_b128 v[192:195], v145 offset:19456
	ds_read_b128 v[196:199], v145 offset:20480
	ds_read_b128 v[200:203], v145 offset:21504
	ds_read_b128 v[204:207], v145 offset:22528
	ds_read_b128 v[208:211], v145 offset:23552
	global_load_lds_dwordx4 v132, s[36:37]
	s_add_i32 m0, s13, 0x2000
	s_add_u32 s62, s36, 0x80000
	s_addc_u32 s63, s37, 0
	s_add_i32 s13, s56, s45
	global_load_lds_dwordx4 v128, s[36:37]
	s_mov_b32 m0, s13
	s_nop 0
	global_load_lds_dwordx4 v132, s[62:63]
	s_add_i32 m0, s13, 0x2000
	s_nop 0
	global_load_lds_dwordx4 v128, s[62:63]
	s_mov_b32 m0, s21
	s_nop 0
	global_load_lds_dwordx4 v134, s[40:41]
	s_mov_b32 m0, s48
	s_nop 0
	global_load_lds_dwordx4 v130, s[40:41]
	s_waitcnt vmcnt(8)
	s_waitcnt lgkmcnt(0)
	s_barrier
	s_waitcnt lgkmcnt(0)
	v_mfma_f32_16x16x32_bf16 v[60:63], v[148:151], v[180:183], v[60:63]
	v_mfma_f32_16x16x32_bf16 v[56:59], v[156:159], v[180:183], v[56:59]
	v_mfma_f32_16x16x32_bf16 v[44:47], v[148:151], v[188:191], v[44:47]
	v_mfma_f32_16x16x32_bf16 v[40:43], v[156:159], v[188:191], v[40:43]
	v_mfma_f32_16x16x32_bf16 v[28:31], v[148:151], v[196:199], v[28:31]
	v_mfma_f32_16x16x32_bf16 v[24:27], v[156:159], v[196:199], v[24:27]
	v_mfma_f32_16x16x32_bf16 v[12:15], v[148:151], v[204:207], v[12:15]
	v_mfma_f32_16x16x32_bf16 v[8:11], v[156:159], v[204:207], v[8:11]
	v_mfma_f32_16x16x32_bf16 v[60:63], v[152:155], v[184:187], v[60:63]
	v_mfma_f32_16x16x32_bf16 v[56:59], v[160:163], v[184:187], v[56:59]
	v_mfma_f32_16x16x32_bf16 v[44:47], v[152:155], v[192:195], v[44:47]
	v_mfma_f32_16x16x32_bf16 v[40:43], v[160:163], v[192:195], v[40:43]
	v_mfma_f32_16x16x32_bf16 v[28:31], v[152:155], v[200:203], v[28:31]
	v_mfma_f32_16x16x32_bf16 v[24:27], v[160:163], v[200:203], v[24:27]
	v_mfma_f32_16x16x32_bf16 v[12:15], v[152:155], v[208:211], v[12:15]
	v_mfma_f32_16x16x32_bf16 v[8:11], v[160:163], v[208:211], v[8:11]
	v_mfma_f32_16x16x32_bf16 v[52:55], v[164:167], v[180:183], v[52:55]
	v_mfma_f32_16x16x32_bf16 v[48:51], v[172:175], v[180:183], v[48:51]
	v_mfma_f32_16x16x32_bf16 v[36:39], v[164:167], v[188:191], v[36:39]
	v_mfma_f32_16x16x32_bf16 v[32:35], v[172:175], v[188:191], v[32:35]
	v_mfma_f32_16x16x32_bf16 v[20:23], v[164:167], v[196:199], v[20:23]
	v_mfma_f32_16x16x32_bf16 v[16:19], v[172:175], v[196:199], v[16:19]
	v_mfma_f32_16x16x32_bf16 v[4:7], v[164:167], v[204:207], v[4:7]
	v_mfma_f32_16x16x32_bf16 v[0:3], v[172:175], v[204:207], v[0:3]
	v_mfma_f32_16x16x32_bf16 v[52:55], v[168:171], v[184:187], v[52:55]
	v_mfma_f32_16x16x32_bf16 v[48:51], v[176:179], v[184:187], v[48:51]
	v_mfma_f32_16x16x32_bf16 v[36:39], v[168:171], v[192:195], v[36:39]
	v_mfma_f32_16x16x32_bf16 v[32:35], v[176:179], v[192:195], v[32:35]
	v_mfma_f32_16x16x32_bf16 v[20:23], v[168:171], v[200:203], v[20:23]
	v_mfma_f32_16x16x32_bf16 v[16:19], v[176:179], v[200:203], v[16:19]
	v_mfma_f32_16x16x32_bf16 v[4:7], v[168:171], v[208:211], v[4:7]
	v_mfma_f32_16x16x32_bf16 v[0:3], v[176:179], v[208:211], v[0:3]
	s_barrier
; #define PG8_STAGE(bufoff, gbase, voff) do { _Pragma("unroll") for (int _i = 0; _i < 2; ++_i) \
;         __builtin_amdgcn_global_load_lds((const unsigned*)((const char*)(gbase) + (voff)[_i]), (LAS unsigned*)(lds + (bufoff) + ldsw + _i * 8192), 16, 0, 0); } while (0)
; #define PG8_LDA(dst, b, h) do { _Pragma("unroll") for (int m = 0; m < 4; ++m) _Pragma("unroll") for (int k = 0; k < 2; ++k) dst[m][k] = *(const LAS bf16x8*)(lds + PG8_SA(b, h) + aoff + m * 2048 + k * 1024); } while (0)
; #define PG8_LDB(dst, b, h) do { _Pragma("unroll") for (int n = 0; n < 2; ++n) _Pragma("unroll") for (int k = 0; k < 2; ++k) dst[n][k] = *(const LAS bf16x8*)(lds + PG8_SB(b, h) + boff + n * 2048 + k * 1024); } while (0)
; #define PG8_MMA(ai, bj, At, Bt) do { __builtin_amdgcn_s_setprio(1); _Pragma("unroll") for (int m = 0; m < 4; ++m) _Pragma("unroll") for (int n = 0; n < 2; ++n) _Pragma("unroll") for (int k = 0; k < 2; ++k) \
;         acc[ai][bj][m][n] = __builtin_amdgcn_mfma_f32_16x16x32_bf16(Bt[n][k], At[m][k], acc[ai][bj][m][n], 0, 0, 0); __builtin_amdgcn_s_setprio(0); } while (0)
; #define PG8_WAIT_V(n) asm volatile("s_waitcnt vmcnt(" #n ")" ::: "memory")
; #define PG8_WAIT_L(n) asm volatile("s_waitcnt lgkmcnt(" #n ")" ::: "memory")
; #define PG8_BAR __builtin_amdgcn_s_barrier()
; #define PG8_SCHED __builtin_amdgcn_sched_barrier(0)
; template <class Epi>
; __device__ __forceinline__ void gemm_phase(LAS unsigned char* lds, const Gemm g, const StaticOrder S, const Epi E) {
;     ...
;         for (int t = 0; t < nt; t += 2) {
;     ...
;             PG8_LDB(B0, 1, 0); PG8_LDB(B1, 1, 1); PG8_SCHED; PG8_LDA(At, 1, 0); PG8_STAGE(PG8_SA(0, 1), a2 + hstepA, voffA);
;             PG8_WAIT_V(8); PG8_WAIT_L(0); PG8_BAR; PG8_MMA(0, 0, At, B0); PG8_MMA(0, 1, At, B1); PG8_BAR; PG8_SCHED;
;             PG8_LDA(At, 1, 1); PG8_STAGE(PG8_SB(1, 0), b3, voffB); PG8_STAGE(PG8_SB(1, 1), b3 + hstepB, voffB); PG8_STAGE(PG8_SA(1, 0), a3, voffA);
;             PG8_WAIT_V(8); PG8_WAIT_L(0); PG8_BAR; PG8_MMA(1, 0, At, B0); PG8_MMA(1, 1, At, B1); PG8_BAR; PG8_SCHED;
	s_add_i32 s13, 0, 0x18000
	s_add_i32 s61, 0, 0x1c000
	ds_read_b128 v[148:151], v254 offset:32768
	ds_read_b128 v[152:155], v254 offset:33792
	ds_read_b128 v[156:159], v254 offset:34816
	ds_read_b128 v[160:163], v254 offset:35840
	ds_read_b128 v[164:167], v254 offset:49152
	ds_read_b128 v[168:171], v254 offset:50176
	ds_read_b128 v[172:175], v254 offset:51200
	ds_read_b128 v[176:179], v254 offset:52224
	s_add_u32 s40, s40, 0x80000
	s_addc_u32 s41, s41, 0
	s_mov_b32 m0, s49
	ds_read_b128 v[180:183], v145 offset:32768
	ds_read_b128 v[184:187], v145 offset:33792
	ds_read_b128 v[188:191], v145 offset:34816
	ds_read_b128 v[192:195], v145 offset:35840
	ds_read_b128 v[196:199], v145 offset:36864
	ds_read_b128 v[200:203], v145 offset:37888
	ds_read_b128 v[204:207], v145 offset:38912
	ds_read_b128 v[208:211], v145 offset:39936
	global_load_lds_dwordx4 v134, s[40:41]
	s_mov_b32 m0, s50
	s_nop 0
	global_load_lds_dwordx4 v130, s[40:41]
	s_waitcnt vmcnt(8)
	s_waitcnt lgkmcnt(0)
	s_barrier
	s_waitcnt lgkmcnt(0)
	v_mfma_f32_16x16x32_bf16 v[116:119], v[148:151], v[180:183], v[116:119]
	v_mfma_f32_16x16x32_bf16 v[112:115], v[156:159], v[180:183], v[112:115]
	v_mfma_f32_16x16x32_bf16 v[108:111], v[148:151], v[188:191], v[108:111]
	v_mfma_f32_16x16x32_bf16 v[104:107], v[156:159], v[188:191], v[104:107]
	v_mfma_f32_16x16x32_bf16 v[92:95], v[148:151], v[196:199], v[92:95]
	v_mfma_f32_16x16x32_bf16 v[88:91], v[156:159], v[196:199], v[88:91]
	v_mfma_f32_16x16x32_bf16 v[76:79], v[148:151], v[204:207], v[76:79]
	v_mfma_f32_16x16x32_bf16 v[72:75], v[156:159], v[204:207], v[72:75]
	v_mfma_f32_16x16x32_bf16 v[116:119], v[152:155], v[184:187], v[116:119]
	v_mfma_f32_16x16x32_bf16 v[112:115], v[160:163], v[184:187], v[112:115]
	v_mfma_f32_16x16x32_bf16 v[108:111], v[152:155], v[192:195], v[108:111]
	v_mfma_f32_16x16x32_bf16 v[104:107], v[160:163], v[192:195], v[104:107]
	v_mfma_f32_16x16x32_bf16 v[92:95], v[152:155], v[200:203], v[92:95]
	v_mfma_f32_16x16x32_bf16 v[88:91], v[160:163], v[200:203], v[88:91]
	v_mfma_f32_16x16x32_bf16 v[76:79], v[152:155], v[208:211], v[76:79]
	v_mfma_f32_16x16x32_bf16 v[72:75], v[160:163], v[208:211], v[72:75]
	v_mfma_f32_16x16x32_bf16 v[124:127], v[164:167], v[180:183], v[124:127]
	v_mfma_f32_16x16x32_bf16 v[120:123], v[172:175], v[180:183], v[120:123]
	v_mfma_f32_16x16x32_bf16 v[100:103], v[164:167], v[188:191], v[100:103]
	v_mfma_f32_16x16x32_bf16 v[96:99], v[172:175], v[188:191], v[96:99]
	v_mfma_f32_16x16x32_bf16 v[84:87], v[164:167], v[196:199], v[84:87]
	v_mfma_f32_16x16x32_bf16 v[80:83], v[172:175], v[196:199], v[80:83]
	v_mfma_f32_16x16x32_bf16 v[68:71], v[164:167], v[204:207], v[68:71]
	v_mfma_f32_16x16x32_bf16 v[64:67], v[172:175], v[204:207], v[64:67]
	v_mfma_f32_16x16x32_bf16 v[124:127], v[168:171], v[184:187], v[124:127]
	v_mfma_f32_16x16x32_bf16 v[120:123], v[176:179], v[184:187], v[120:123]
	v_mfma_f32_16x16x32_bf16 v[100:103], v[168:171], v[192:195], v[100:103]
	v_mfma_f32_16x16x32_bf16 v[96:99], v[176:179], v[192:195], v[96:99]
	v_mfma_f32_16x16x32_bf16 v[84:87], v[168:171], v[200:203], v[84:87]
	v_mfma_f32_16x16x32_bf16 v[80:83], v[176:179], v[200:203], v[80:83]
	v_mfma_f32_16x16x32_bf16 v[68:71], v[168:171], v[208:211], v[68:71]
	v_mfma_f32_16x16x32_bf16 v[64:67], v[176:179], v[208:211], v[64:67]
	s_barrier
	s_add_u32 s36, s36, s38
	s_addc_u32 s37, s37, s39
	s_add_i32 s13, s13, s45
	s_mov_b32 m0, s13
	ds_read_b128 v[180:183], v145 offset:49152
	ds_read_b128 v[184:187], v145 offset:50176
	ds_read_b128 v[188:191], v145 offset:51200
	ds_read_b128 v[192:195], v145 offset:52224
	ds_read_b128 v[196:199], v145 offset:53248
	ds_read_b128 v[200:203], v145 offset:54272
	ds_read_b128 v[204:207], v145 offset:55296
	ds_read_b128 v[208:211], v145 offset:56320
	global_load_lds_dwordx4 v132, s[36:37]
	s_add_i32 m0, s13, 0x2000
	s_nop 0
	global_load_lds_dwordx4 v128, s[36:37]
	s_add_u32 s36, s36, 0x80000
	s_addc_u32 s37, s37, 0
	s_add_i32 s13, s61, s45
	s_mov_b32 m0, s13
	s_nop 0
	global_load_lds_dwordx4 v132, s[36:37]
	s_add_i32 m0, s13, 0x2000
	s_nop 0
	global_load_lds_dwordx4 v128, s[36:37]
	s_mov_b32 m0, s51
	s_nop 0
	global_load_lds_dwordx4 v134, s[42:43]
	s_mov_b32 m0, s52
	s_nop 0
	global_load_lds_dwordx4 v130, s[42:43]
	s_waitcnt vmcnt(8)
	s_waitcnt lgkmcnt(0)
	s_barrier
	s_waitcnt lgkmcnt(0)
	v_mfma_f32_16x16x32_bf16 v[60:63], v[148:151], v[180:183], v[60:63]
	v_mfma_f32_16x16x32_bf16 v[56:59], v[156:159], v[180:183], v[56:59]
	v_mfma_f32_16x16x32_bf16 v[44:47], v[148:151], v[188:191], v[44:47]
	v_mfma_f32_16x16x32_bf16 v[40:43], v[156:159], v[188:191], v[40:43]
	v_mfma_f32_16x16x32_bf16 v[28:31], v[148:151], v[196:199], v[28:31]
	v_mfma_f32_16x16x32_bf16 v[24:27], v[156:159], v[196:199], v[24:27]
	v_mfma_f32_16x16x32_bf16 v[12:15], v[148:151], v[204:207], v[12:15]
	v_mfma_f32_16x16x32_bf16 v[8:11], v[156:159], v[204:207], v[8:11]
	v_mfma_f32_16x16x32_bf16 v[60:63], v[152:155], v[184:187], v[60:63]
	v_mfma_f32_16x16x32_bf16 v[56:59], v[160:163], v[184:187], v[56:59]
	v_mfma_f32_16x16x32_bf16 v[44:47], v[152:155], v[192:195], v[44:47]
	v_mfma_f32_16x16x32_bf16 v[40:43], v[160:163], v[192:195], v[40:43]
	v_mfma_f32_16x16x32_bf16 v[28:31], v[152:155], v[200:203], v[28:31]
	v_mfma_f32_16x16x32_bf16 v[24:27], v[160:163], v[200:203], v[24:27]
	v_mfma_f32_16x16x32_bf16 v[12:15], v[152:155], v[208:211], v[12:15]
	v_mfma_f32_16x16x32_bf16 v[8:11], v[160:163], v[208:211], v[8:11]
	v_mfma_f32_16x16x32_bf16 v[52:55], v[164:167], v[180:183], v[52:55]
	v_mfma_f32_16x16x32_bf16 v[48:51], v[172:175], v[180:183], v[48:51]
	v_mfma_f32_16x16x32_bf16 v[36:39], v[164:167], v[188:191], v[36:39]
	v_mfma_f32_16x16x32_bf16 v[32:35], v[172:175], v[188:191], v[32:35]
	v_mfma_f32_16x16x32_bf16 v[20:23], v[164:167], v[196:199], v[20:23]
	v_mfma_f32_16x16x32_bf16 v[16:19], v[172:175], v[196:199], v[16:19]
	v_mfma_f32_16x16x32_bf16 v[4:7], v[164:167], v[204:207], v[4:7]
	v_mfma_f32_16x16x32_bf16 v[0:3], v[172:175], v[204:207], v[0:3]
	v_mfma_f32_16x16x32_bf16 v[52:55], v[168:171], v[184:187], v[52:55]
	v_mfma_f32_16x16x32_bf16 v[48:51], v[176:179], v[184:187], v[48:51]
	v_mfma_f32_16x16x32_bf16 v[36:39], v[168:171], v[192:195], v[36:39]
	v_mfma_f32_16x16x32_bf16 v[32:35], v[176:179], v[192:195], v[32:35]
	v_mfma_f32_16x16x32_bf16 v[20:23], v[168:171], v[200:203], v[20:23]
	v_mfma_f32_16x16x32_bf16 v[16:19], v[176:179], v[200:203], v[16:19]
	v_mfma_f32_16x16x32_bf16 v[4:7], v[168:171], v[208:211], v[4:7]
	v_mfma_f32_16x16x32_bf16 v[0:3], v[176:179], v[208:211], v[0:3]
	s_barrier
	s_cmp_gt_u32 s60, 29
	s_mov_b32 s60, s11
	s_cbranch_scc1 .LBB0_1478

; #define PG8_STAGE(bufoff, gbase, voff) do { _Pragma("unroll") for (int _i = 0; _i < 2; ++_i) \
;         __builtin_amdgcn_global_load_lds((const unsigned*)((const char*)(gbase) + (voff)[_i]), (LAS unsigned*)(lds + (bufoff) + ldsw + _i * 8192), 16, 0, 0); } while (0)
; #define PG8_LDA(dst, b, h) do { _Pragma("unroll") for (int m = 0; m < 4; ++m) _Pragma("unroll") for (int k = 0; k < 2; ++k) dst[m][k] = *(const LAS bf16x8*)(lds + PG8_SA(b, h) + aoff + m * 2048 + k * 1024); } while (0)
; #define PG8_LDB(dst, b, h) do { _Pragma("unroll") for (int n = 0; n < 2; ++n) _Pragma("unroll") for (int k = 0; k < 2; ++k) dst[n][k] = *(const LAS bf16x8*)(lds + PG8_SB(b, h) + boff + n * 2048 + k * 1024); } while (0)
; #define PG8_MMA(ai, bj, At, Bt) do { __builtin_amdgcn_s_setprio(1); _Pragma("unroll") for (int m = 0; m < 4; ++m) _Pragma("unroll") for (int n = 0; n < 2; ++n) _Pragma("unroll") for (int k = 0; k < 2; ++k) \
;         acc[ai][bj][m][n] = __builtin_amdgcn_mfma_f32_16x16x32_bf16(Bt[n][k], At[m][k], acc[ai][bj][m][n], 0, 0, 0); __builtin_amdgcn_s_setprio(0); } while (0)
; #define PG8_WAIT_V(n) asm volatile("s_waitcnt vmcnt(" #n ")" ::: "memory")
; #define PG8_WAIT_L(n) asm volatile("s_waitcnt lgkmcnt(" #n ")" ::: "memory")
; #define PG8_BAR __builtin_amdgcn_s_barrier()
; #define PG8_SCHED __builtin_amdgcn_sched_barrier(0)
; template <class Epi>
; __device__ __forceinline__ void gemm_phase(LAS unsigned char* lds, const Gemm g, const StaticOrder S, const Epi E) {
;     ...
;             PG8_LDB(B0, 0, 0); PG8_LDB(B1, 0, 1); PG8_SCHED; PG8_LDA(At, 0, 0); PG8_STAGE(PG8_SA(1, 1), a1 + hstepA, voffA);
;             PG8_WAIT_V(8); PG8_WAIT_L(0); PG8_BAR; PG8_MMA(0, 0, At, B0); PG8_MMA(0, 1, At, B1); PG8_BAR; PG8_SCHED;
;             PG8_LDA(At, 0, 1); PG8_STAGE(PG8_SB(0, 0), b2, voffB); PG8_STAGE(PG8_SB(0, 1), b2 + hstepB, voffB); PG8_STAGE(PG8_SA(0, 0), a2, voffA);
;             PG8_WAIT_V(8); PG8_WAIT_L(0); PG8_BAR; PG8_MMA(1, 0, At, B0); PG8_MMA(1, 1, At, B1); PG8_BAR; PG8_SCHED;
.LBB0_1558:
	v_add_u32_e32 v152, s55, v161
	ds_read_b128 v[128:131], v152
	ds_read_b128 v[132:135], v152 offset:1024
	ds_read_b128 v[136:139], v152 offset:2048
	ds_read_b128 v[152:155], v152 offset:3072
	ds_read_b128 v[156:159], v254 offset:16384
	ds_read_b128 v[166:169], v254 offset:17408
	ds_read_b128 v[170:173], v254 offset:18432
	ds_read_b128 v[174:177], v254 offset:19456
	s_or_b32 s42, s66, 1
	s_mul_i32 s43, s35, s42
	s_mul_hi_u32 s68, s34, s42
	s_add_i32 s68, s68, s43
	s_mul_i32 s42, s34, s42
	s_add_u32 s69, s30, s42
	s_addc_u32 s70, s31, s68
	s_add_u32 s42, s40, s38
	s_addc_u32 s43, s41, s39
	s_add_u32 s68, s69, 0x160000
	s_addc_u32 s69, s70, 0
	s_add_i32 m0, s46, 0xc000
	ds_read_b128 v[178:181], v163
	ds_read_b128 v[182:185], v163 offset:1024
	ds_read_b128 v[186:189], v163 offset:2048
	ds_read_b128 v[190:193], v163 offset:3072
	ds_read_b128 v[194:197], v163 offset:4096
	ds_read_b128 v[198:201], v163 offset:5120
	ds_read_b128 v[202:205], v163 offset:6144
	ds_read_b128 v[206:209], v163 offset:7168
	global_load_lds_dwordx4 v140, s[68:69]
	s_add_i32 m0, s46, 0xe000
	s_nop 0
	global_load_lds_dwordx4 v144, s[68:69]
	s_waitcnt vmcnt(8)
	s_waitcnt lgkmcnt(0)
	s_barrier
	s_waitcnt lgkmcnt(0)
	v_mfma_f32_16x16x32_bf16 v[124:127], v[128:131], v[178:181], v[124:127]
	v_mfma_f32_16x16x32_bf16 v[120:123], v[136:139], v[178:181], v[120:123]
	v_mfma_f32_16x16x32_bf16 v[108:111], v[128:131], v[186:189], v[108:111]
	v_mfma_f32_16x16x32_bf16 v[104:107], v[136:139], v[186:189], v[104:107]
	v_mfma_f32_16x16x32_bf16 v[92:95], v[128:131], v[194:197], v[92:95]
	v_mfma_f32_16x16x32_bf16 v[88:91], v[136:139], v[194:197], v[88:91]
	v_mfma_f32_16x16x32_bf16 v[76:79], v[128:131], v[202:205], v[76:79]
	v_mfma_f32_16x16x32_bf16 v[72:75], v[136:139], v[202:205], v[72:75]
	v_mfma_f32_16x16x32_bf16 v[124:127], v[132:135], v[182:185], v[124:127]
	v_mfma_f32_16x16x32_bf16 v[120:123], v[152:155], v[182:185], v[120:123]
	v_mfma_f32_16x16x32_bf16 v[108:111], v[132:135], v[190:193], v[108:111]
	v_mfma_f32_16x16x32_bf16 v[104:107], v[152:155], v[190:193], v[104:107]
	v_mfma_f32_16x16x32_bf16 v[92:95], v[132:135], v[198:201], v[92:95]
	v_mfma_f32_16x16x32_bf16 v[88:91], v[152:155], v[198:201], v[88:91]
	v_mfma_f32_16x16x32_bf16 v[76:79], v[132:135], v[206:209], v[76:79]
	v_mfma_f32_16x16x32_bf16 v[72:75], v[152:155], v[206:209], v[72:75]
	v_mfma_f32_16x16x32_bf16 v[116:119], v[156:159], v[178:181], v[116:119]
	v_mfma_f32_16x16x32_bf16 v[112:115], v[170:173], v[178:181], v[112:115]
	v_mfma_f32_16x16x32_bf16 v[100:103], v[156:159], v[186:189], v[100:103]
	v_mfma_f32_16x16x32_bf16 v[96:99], v[170:173], v[186:189], v[96:99]
	v_mfma_f32_16x16x32_bf16 v[84:87], v[156:159], v[194:197], v[84:87]
	v_mfma_f32_16x16x32_bf16 v[80:83], v[170:173], v[194:197], v[80:83]
	v_mfma_f32_16x16x32_bf16 v[68:71], v[156:159], v[202:205], v[68:71]
	v_mfma_f32_16x16x32_bf16 v[64:67], v[170:173], v[202:205], v[64:67]
	v_mfma_f32_16x16x32_bf16 v[116:119], v[166:169], v[182:185], v[116:119]
	v_mfma_f32_16x16x32_bf16 v[112:115], v[174:177], v[182:185], v[112:115]
	v_mfma_f32_16x16x32_bf16 v[100:103], v[166:169], v[190:193], v[100:103]
	v_mfma_f32_16x16x32_bf16 v[96:99], v[174:177], v[190:193], v[96:99]
	v_mfma_f32_16x16x32_bf16 v[84:87], v[166:169], v[198:201], v[84:87]
	v_mfma_f32_16x16x32_bf16 v[80:83], v[174:177], v[198:201], v[80:83]
	v_mfma_f32_16x16x32_bf16 v[68:71], v[166:169], v[206:209], v[68:71]
	v_mfma_f32_16x16x32_bf16 v[64:67], v[174:177], v[206:209], v[64:67]
	s_barrier
	s_add_i32 s68, s55, s45
	s_mov_b32 m0, s68
	ds_read_b128 v[178:181], v163 offset:16384
	ds_read_b128 v[182:185], v163 offset:17408
	ds_read_b128 v[186:189], v163 offset:18432
	ds_read_b128 v[190:193], v163 offset:19456
	ds_read_b128 v[194:197], v163 offset:20480
	ds_read_b128 v[198:201], v163 offset:21504
	ds_read_b128 v[202:205], v163 offset:22528
	ds_read_b128 v[206:209], v163 offset:23552
	global_load_lds_dwordx4 v142, s[36:37]
	s_add_i32 m0, s68, 0x2000
	s_add_u32 s68, s36, 0x160000
	s_addc_u32 s69, s37, 0
	s_add_i32 s70, s56, s45
	global_load_lds_dwordx4 v146, s[36:37]
	s_mov_b32 m0, s70
	s_nop 0
	global_load_lds_dwordx4 v142, s[68:69]
	s_add_i32 m0, s70, 0x2000
	s_nop 0
	global_load_lds_dwordx4 v146, s[68:69]
	s_mov_b32 m0, s46
	s_nop 0
	global_load_lds_dwordx4 v140, s[40:41]
	s_mov_b32 m0, s47
	s_nop 0
	global_load_lds_dwordx4 v144, s[40:41]
	s_waitcnt vmcnt(8)
	s_waitcnt lgkmcnt(0)
	s_barrier
	s_waitcnt lgkmcnt(0)
	v_mfma_f32_16x16x32_bf16 v[60:63], v[128:131], v[178:181], v[60:63]
	v_mfma_f32_16x16x32_bf16 v[56:59], v[136:139], v[178:181], v[56:59]
	v_mfma_f32_16x16x32_bf16 v[44:47], v[128:131], v[186:189], v[44:47]
	v_mfma_f32_16x16x32_bf16 v[40:43], v[136:139], v[186:189], v[40:43]
	v_mfma_f32_16x16x32_bf16 v[28:31], v[128:131], v[194:197], v[28:31]
	v_mfma_f32_16x16x32_bf16 v[24:27], v[136:139], v[194:197], v[24:27]
	v_mfma_f32_16x16x32_bf16 v[12:15], v[128:131], v[202:205], v[12:15]
	v_mfma_f32_16x16x32_bf16 v[8:11], v[136:139], v[202:205], v[8:11]
	v_mfma_f32_16x16x32_bf16 v[60:63], v[132:135], v[182:185], v[60:63]
	v_mfma_f32_16x16x32_bf16 v[56:59], v[152:155], v[182:185], v[56:59]
	v_mfma_f32_16x16x32_bf16 v[44:47], v[132:135], v[190:193], v[44:47]
	v_mfma_f32_16x16x32_bf16 v[40:43], v[152:155], v[190:193], v[40:43]
	v_mfma_f32_16x16x32_bf16 v[28:31], v[132:135], v[198:201], v[28:31]
	v_mfma_f32_16x16x32_bf16 v[24:27], v[152:155], v[198:201], v[24:27]
	v_mfma_f32_16x16x32_bf16 v[12:15], v[132:135], v[206:209], v[12:15]
	v_mfma_f32_16x16x32_bf16 v[8:11], v[152:155], v[206:209], v[8:11]
	v_mfma_f32_16x16x32_bf16 v[52:55], v[156:159], v[178:181], v[52:55]
	v_mfma_f32_16x16x32_bf16 v[48:51], v[170:173], v[178:181], v[48:51]
	v_mfma_f32_16x16x32_bf16 v[36:39], v[156:159], v[186:189], v[36:39]
	v_mfma_f32_16x16x32_bf16 v[32:35], v[170:173], v[186:189], v[32:35]
	v_mfma_f32_16x16x32_bf16 v[20:23], v[156:159], v[194:197], v[20:23]
	v_mfma_f32_16x16x32_bf16 v[16:19], v[170:173], v[194:197], v[16:19]
	v_mfma_f32_16x16x32_bf16 v[4:7], v[156:159], v[202:205], v[4:7]
	v_mfma_f32_16x16x32_bf16 v[0:3], v[170:173], v[202:205], v[0:3]
	v_mfma_f32_16x16x32_bf16 v[52:55], v[166:169], v[182:185], v[52:55]
	v_mfma_f32_16x16x32_bf16 v[48:51], v[174:177], v[182:185], v[48:51]
	v_mfma_f32_16x16x32_bf16 v[36:39], v[166:169], v[190:193], v[36:39]
	v_mfma_f32_16x16x32_bf16 v[32:35], v[174:177], v[190:193], v[32:35]
	v_mfma_f32_16x16x32_bf16 v[20:23], v[166:169], v[198:201], v[20:23]
	v_mfma_f32_16x16x32_bf16 v[16:19], v[174:177], v[198:201], v[16:19]
	v_mfma_f32_16x16x32_bf16 v[4:7], v[166:169], v[206:209], v[4:7]
	v_mfma_f32_16x16x32_bf16 v[0:3], v[174:177], v[206:209], v[0:3]
	s_barrier
; #define PG8_STAGE(bufoff, gbase, voff) do { _Pragma("unroll") for (int _i = 0; _i < 2; ++_i) \
;         __builtin_amdgcn_global_load_lds((const unsigned*)((const char*)(gbase) + (voff)[_i]), (LAS unsigned*)(lds + (bufoff) + ldsw + _i * 8192), 16, 0, 0); } while (0)
; #define PG8_LDA(dst, b, h) do { _Pragma("unroll") for (int m = 0; m < 4; ++m) _Pragma("unroll") for (int k = 0; k < 2; ++k) dst[m][k] = *(const LAS bf16x8*)(lds + PG8_SA(b, h) + aoff + m * 2048 + k * 1024); } while (0)
; #define PG8_LDB(dst, b, h) do { _Pragma("unroll") for (int n = 0; n < 2; ++n) _Pragma("unroll") for (int k = 0; k < 2; ++k) dst[n][k] = *(const LAS bf16x8*)(lds + PG8_SB(b, h) + boff + n * 2048 + k * 1024); } while (0)
; #define PG8_MMA(ai, bj, At, Bt) do { __builtin_amdgcn_s_setprio(1); _Pragma("unroll") for (int m = 0; m < 4; ++m) _Pragma("unroll") for (int n = 0; n < 2; ++n) _Pragma("unroll") for (int k = 0; k < 2; ++k) \
;         acc[ai][bj][m][n] = __builtin_amdgcn_mfma_f32_16x16x32_bf16(Bt[n][k], At[m][k], acc[ai][bj][m][n], 0, 0, 0); __builtin_amdgcn_s_setprio(0); } while (0)
; #define PG8_WAIT_V(n) asm volatile("s_waitcnt vmcnt(" #n ")" ::: "memory")
; #define PG8_WAIT_L(n) asm volatile("s_waitcnt lgkmcnt(" #n ")" ::: "memory")
; #define PG8_BAR __builtin_amdgcn_s_barrier()
; #define PG8_SCHED __builtin_amdgcn_sched_barrier(0)
; template <class Epi>
; __device__ __forceinline__ void gemm_phase(LAS unsigned char* lds, const Gemm g, const StaticOrder S, const Epi E) {
;     ...
;         for (int t = 0; t < nt; t += 2) {
;     ...
;             PG8_LDB(B0, 1, 0); PG8_LDB(B1, 1, 1); PG8_SCHED; PG8_LDA(At, 1, 0); PG8_STAGE(PG8_SA(0, 1), a2 + hstepA, voffA);
;             PG8_WAIT_V(8); PG8_WAIT_L(0); PG8_BAR; PG8_MMA(0, 0, At, B0); PG8_MMA(0, 1, At, B1); PG8_BAR; PG8_SCHED;
;             PG8_LDA(At, 1, 1); PG8_STAGE(PG8_SB(1, 0), b3, voffB); PG8_STAGE(PG8_SB(1, 1), b3 + hstepB, voffB); PG8_STAGE(PG8_SA(1, 0), a3, voffA);
;             PG8_WAIT_V(8); PG8_WAIT_L(0); PG8_BAR; PG8_MMA(1, 0, At, B0); PG8_MMA(1, 1, At, B1); PG8_BAR; PG8_SCHED;
	s_add_i32 s68, 0, 0x18000
	s_add_i32 s69, 0, 0x1c000
	v_add_u32_e32 v152, s68, v161
	ds_read_b128 v[128:131], v152
	ds_read_b128 v[132:135], v152 offset:1024
	ds_read_b128 v[136:139], v152 offset:2048
	ds_read_b128 v[152:155], v152 offset:3072
	ds_read_b128 v[156:159], v254 offset:49152
	ds_read_b128 v[166:169], v254 offset:50176
	ds_read_b128 v[170:173], v254 offset:51200
	ds_read_b128 v[174:177], v254 offset:52224
	s_add_u32 s40, s40, 0x160000
	s_addc_u32 s41, s41, 0
	s_mov_b32 m0, s48
	ds_read_b128 v[178:181], v163 offset:32768
	ds_read_b128 v[182:185], v163 offset:33792
	ds_read_b128 v[186:189], v163 offset:34816
	ds_read_b128 v[190:193], v163 offset:35840
	ds_read_b128 v[194:197], v163 offset:36864
	ds_read_b128 v[198:201], v163 offset:37888
	ds_read_b128 v[202:205], v163 offset:38912
	ds_read_b128 v[206:209], v163 offset:39936
	global_load_lds_dwordx4 v140, s[40:41]
	s_mov_b32 m0, s49
	s_nop 0
	global_load_lds_dwordx4 v144, s[40:41]
	s_waitcnt vmcnt(8)
	s_waitcnt lgkmcnt(0)
	s_barrier
	s_waitcnt lgkmcnt(0)
	v_mfma_f32_16x16x32_bf16 v[124:127], v[128:131], v[178:181], v[124:127]
	v_mfma_f32_16x16x32_bf16 v[120:123], v[136:139], v[178:181], v[120:123]
	v_mfma_f32_16x16x32_bf16 v[108:111], v[128:131], v[186:189], v[108:111]
	v_mfma_f32_16x16x32_bf16 v[104:107], v[136:139], v[186:189], v[104:107]
	v_mfma_f32_16x16x32_bf16 v[92:95], v[128:131], v[194:197], v[92:95]
	v_mfma_f32_16x16x32_bf16 v[88:91], v[136:139], v[194:197], v[88:91]
	v_mfma_f32_16x16x32_bf16 v[76:79], v[128:131], v[202:205], v[76:79]
	v_mfma_f32_16x16x32_bf16 v[72:75], v[136:139], v[202:205], v[72:75]
	v_mfma_f32_16x16x32_bf16 v[124:127], v[132:135], v[182:185], v[124:127]
	v_mfma_f32_16x16x32_bf16 v[120:123], v[152:155], v[182:185], v[120:123]
	v_mfma_f32_16x16x32_bf16 v[108:111], v[132:135], v[190:193], v[108:111]
	v_mfma_f32_16x16x32_bf16 v[104:107], v[152:155], v[190:193], v[104:107]
	v_mfma_f32_16x16x32_bf16 v[92:95], v[132:135], v[198:201], v[92:95]
	v_mfma_f32_16x16x32_bf16 v[88:91], v[152:155], v[198:201], v[88:91]
	v_mfma_f32_16x16x32_bf16 v[76:79], v[132:135], v[206:209], v[76:79]
	v_mfma_f32_16x16x32_bf16 v[72:75], v[152:155], v[206:209], v[72:75]
	v_mfma_f32_16x16x32_bf16 v[116:119], v[156:159], v[178:181], v[116:119]
	v_mfma_f32_16x16x32_bf16 v[112:115], v[170:173], v[178:181], v[112:115]
	v_mfma_f32_16x16x32_bf16 v[100:103], v[156:159], v[186:189], v[100:103]
	v_mfma_f32_16x16x32_bf16 v[96:99], v[170:173], v[186:189], v[96:99]
	v_mfma_f32_16x16x32_bf16 v[84:87], v[156:159], v[194:197], v[84:87]
	v_mfma_f32_16x16x32_bf16 v[80:83], v[170:173], v[194:197], v[80:83]
	v_mfma_f32_16x16x32_bf16 v[68:71], v[156:159], v[202:205], v[68:71]
	v_mfma_f32_16x16x32_bf16 v[64:67], v[170:173], v[202:205], v[64:67]
	v_mfma_f32_16x16x32_bf16 v[116:119], v[166:169], v[182:185], v[116:119]
	v_mfma_f32_16x16x32_bf16 v[112:115], v[174:177], v[182:185], v[112:115]
	v_mfma_f32_16x16x32_bf16 v[100:103], v[166:169], v[190:193], v[100:103]
	v_mfma_f32_16x16x32_bf16 v[96:99], v[174:177], v[190:193], v[96:99]
	v_mfma_f32_16x16x32_bf16 v[84:87], v[166:169], v[198:201], v[84:87]
	v_mfma_f32_16x16x32_bf16 v[80:83], v[174:177], v[198:201], v[80:83]
	v_mfma_f32_16x16x32_bf16 v[68:71], v[166:169], v[206:209], v[68:71]
	v_mfma_f32_16x16x32_bf16 v[64:67], v[174:177], v[206:209], v[64:67]
	s_barrier
	s_add_u32 s36, s36, s38
	s_addc_u32 s37, s37, s39
	s_add_i32 s38, s68, s45
	s_mov_b32 m0, s38
	ds_read_b128 v[178:181], v163 offset:49152
	ds_read_b128 v[182:185], v163 offset:50176
	ds_read_b128 v[186:189], v163 offset:51200
	ds_read_b128 v[190:193], v163 offset:52224
	ds_read_b128 v[194:197], v163 offset:53248
	ds_read_b128 v[198:201], v163 offset:54272
	ds_read_b128 v[202:205], v163 offset:55296
	ds_read_b128 v[206:209], v163 offset:56320
	global_load_lds_dwordx4 v142, s[36:37]
	s_add_i32 m0, s38, 0x2000
	s_nop 0
	global_load_lds_dwordx4 v146, s[36:37]
	s_add_u32 s36, s36, 0x160000
	s_addc_u32 s37, s37, 0
	s_add_i32 s38, s69, s45
	s_mov_b32 m0, s38
	s_nop 0
	global_load_lds_dwordx4 v142, s[36:37]
	s_add_i32 m0, s38, 0x2000
	s_nop 0
	global_load_lds_dwordx4 v146, s[36:37]
	s_mov_b32 m0, s51
	s_nop 0
	global_load_lds_dwordx4 v140, s[42:43]
	s_mov_b32 m0, s52
	s_nop 0
	global_load_lds_dwordx4 v144, s[42:43]
	s_waitcnt vmcnt(8)
	s_waitcnt lgkmcnt(0)
	s_barrier
	s_waitcnt lgkmcnt(0)
	v_mfma_f32_16x16x32_bf16 v[60:63], v[128:131], v[178:181], v[60:63]
	v_mfma_f32_16x16x32_bf16 v[56:59], v[136:139], v[178:181], v[56:59]
	v_mfma_f32_16x16x32_bf16 v[44:47], v[128:131], v[186:189], v[44:47]
	v_mfma_f32_16x16x32_bf16 v[40:43], v[136:139], v[186:189], v[40:43]
	v_mfma_f32_16x16x32_bf16 v[28:31], v[128:131], v[194:197], v[28:31]
	v_mfma_f32_16x16x32_bf16 v[24:27], v[136:139], v[194:197], v[24:27]
	v_mfma_f32_16x16x32_bf16 v[12:15], v[128:131], v[202:205], v[12:15]
	v_mfma_f32_16x16x32_bf16 v[8:11], v[136:139], v[202:205], v[8:11]
	v_mfma_f32_16x16x32_bf16 v[60:63], v[132:135], v[182:185], v[60:63]
	v_mfma_f32_16x16x32_bf16 v[56:59], v[152:155], v[182:185], v[56:59]
	v_mfma_f32_16x16x32_bf16 v[44:47], v[132:135], v[190:193], v[44:47]
	v_mfma_f32_16x16x32_bf16 v[40:43], v[152:155], v[190:193], v[40:43]
	v_mfma_f32_16x16x32_bf16 v[28:31], v[132:135], v[198:201], v[28:31]
	v_mfma_f32_16x16x32_bf16 v[24:27], v[152:155], v[198:201], v[24:27]
	v_mfma_f32_16x16x32_bf16 v[12:15], v[132:135], v[206:209], v[12:15]
	v_mfma_f32_16x16x32_bf16 v[8:11], v[152:155], v[206:209], v[8:11]
	v_mfma_f32_16x16x32_bf16 v[52:55], v[156:159], v[178:181], v[52:55]
	v_mfma_f32_16x16x32_bf16 v[48:51], v[170:173], v[178:181], v[48:51]
	v_mfma_f32_16x16x32_bf16 v[36:39], v[156:159], v[186:189], v[36:39]
	v_mfma_f32_16x16x32_bf16 v[32:35], v[170:173], v[186:189], v[32:35]
	v_mfma_f32_16x16x32_bf16 v[20:23], v[156:159], v[194:197], v[20:23]
	v_mfma_f32_16x16x32_bf16 v[16:19], v[170:173], v[194:197], v[16:19]
	v_mfma_f32_16x16x32_bf16 v[4:7], v[156:159], v[202:205], v[4:7]
	v_mfma_f32_16x16x32_bf16 v[0:3], v[170:173], v[202:205], v[0:3]
	v_mfma_f32_16x16x32_bf16 v[52:55], v[166:169], v[182:185], v[52:55]
	v_mfma_f32_16x16x32_bf16 v[48:51], v[174:177], v[182:185], v[48:51]
	v_mfma_f32_16x16x32_bf16 v[36:39], v[166:169], v[190:193], v[36:39]
	v_mfma_f32_16x16x32_bf16 v[32:35], v[174:177], v[190:193], v[32:35]
	v_mfma_f32_16x16x32_bf16 v[20:23], v[166:169], v[198:201], v[20:23]
	v_mfma_f32_16x16x32_bf16 v[16:19], v[174:177], v[198:201], v[16:19]
	v_mfma_f32_16x16x32_bf16 v[4:7], v[166:169], v[206:209], v[4:7]
	v_mfma_f32_16x16x32_bf16 v[0:3], v[174:177], v[206:209], v[0:3]
	s_barrier
	s_cmpk_gt_u32 s66, 0x55
	s_mov_b32 s66, s67
	s_cbranch_scc1 .LBB0_1563
